# W_uv fragments requested up front as 16-byte pieces with lane-half exchange; xattn output stores widened to 16 bytes; row-stat lane sums by row swaps
# speedup vs baseline: 1.0308x; 1.0308x over previous
; #define PG8_GAS __attribute__((address_space(1)))
; __device__ __forceinline__ float row_rstd(const float* parts, int r, int fq) {
;     const f32x4 p = *(const PG8_GAS f32x4*)(parts + (size_t)r * 16 + 4 * fq);
;     float s = (p[0] + p[1]) + (p[2] + p[3]);
;     s += __shfl_xor(s, 16); s += __shfl_xor(s, 32);
;     return rsqrtf(s * (1.0f / 1024.0f) + RMS_EPS);
;     __device__ __forceinline__ void operator()(const f32x4 (&acc)[2][2][4][2], const Unit& u, int wr, int wc, int fr, int fq) const {
;         const int row0 = u.pm * BM + wr * 64 + fr, col0 = u.pn * 128 + wc * 32 + 8 * fq;
;         float rs8[2][4];
; #pragma unroll
;         for (int ai = 0; ai < 2; ++ai)
; #pragma unroll
;             for (int m = 0; m < 4; ++m) rs8[ai][m] = row_rstd(parts, row0 + ai * HALF + m * 16, fq);
.LBB0_697:
	s_lshl_b32 s6, s6, 8
	v_mov_b32_e32 v132, v252
	s_add_i32 s6, s6, s53
	s_nop 0
	v_bfe_u32 v200, v132, 4, 2
	v_and_or_b32 v160, v132, 15, s6
	v_lshlrev_b32_e32 v132, 4, v200
	v_ashrrev_i32_e32 v161, 31, v160
	v_or_b32_e32 v156, 16, v160
	v_lshl_add_u64 v[190:191], s[80:81], 0, v[132:133]
	v_lshlrev_b64 v[140:141], 6, v[160:161]
	v_ashrrev_i32_e32 v157, 31, v156
	v_or_b32_e32 v152, 32, v160
	v_lshl_add_u64 v[140:141], v[190:191], 0, v[140:141]
	v_lshlrev_b64 v[142:143], 6, v[156:157]
	v_ashrrev_i32_e32 v153, 31, v152
	v_lshl_add_u64 v[142:143], v[190:191], 0, v[142:143]
	global_load_dwordx4 v[166:169], v[140:141], off
	global_load_dwordx4 v[170:173], v[142:143], off
	v_lshlrev_b64 v[140:141], 6, v[152:153]
	v_or_b32_e32 v148, 48, v160
	v_lshl_add_u64 v[140:141], v[190:191], 0, v[140:141]
	v_ashrrev_i32_e32 v149, 31, v148
	global_load_dwordx4 v[174:177], v[140:141], off
	v_lshlrev_b64 v[140:141], 6, v[148:149]
	v_lshl_add_u64 v[140:141], v[190:191], 0, v[140:141]
	global_load_dwordx4 v[178:181], v[140:141], off
	v_add_u32_e32 v146, 0x80, v160
	v_ashrrev_i32_e32 v147, 31, v146
	v_lshlrev_b64 v[140:141], 6, v[146:147]
	v_add_u32_e32 v144, 0x90, v160
	v_lshl_add_u64 v[140:141], v[190:191], 0, v[140:141]
	v_ashrrev_i32_e32 v145, 31, v144
	global_load_dwordx4 v[182:185], v[140:141], off
	v_lshlrev_b64 v[140:141], 6, v[144:145]
	v_lshl_add_u64 v[140:141], v[190:191], 0, v[140:141]
	global_load_dwordx4 v[186:189], v[140:141], off
	v_and_b32_e32 v140, 64, v165
	v_add_u32_e32 v147, 64, v140
	v_add_u32_e32 v142, 0xa0, v160
	v_add_u32_e32 v140, 0xb0, v160
	v_ashrrev_i32_e32 v143, 31, v142
	v_ashrrev_i32_e32 v141, 31, v140
	v_lshlrev_b64 v[192:193], 6, v[142:143]
	v_lshlrev_b64 v[194:195], 6, v[140:141]
	v_lshl_add_u64 v[192:193], v[190:191], 0, v[192:193]
	v_lshl_add_u64 v[194:195], v[190:191], 0, v[194:195]
	global_load_dwordx4 v[190:193], v[192:193], off
	s_nop 0
	global_load_dwordx4 v[194:197], v[194:195], off
	v_xor_b32_e32 v132, 16, v165
	v_cmp_lt_i32_e32 vcc, v132, v147
	v_xor_b32_e32 v145, 32, v165
	s_waitcnt vmcnt(0)
	v_mov_b32_e32 v198, v167
	v_mov_b32_e32 v199, v168
	v_mov_b32_e32 v167, v169
	v_mov_b32_e32 v168, v171
	v_mov_b32_e32 v169, v172
	v_mov_b32_e32 v171, v173
	v_pk_add_f32 v[166:167], v[198:199], v[166:167]
	v_mov_b32_e32 v172, v175
	v_mov_b32_e32 v173, v176
	v_mov_b32_e32 v175, v177
	v_mov_b32_e32 v176, v179
	v_mov_b32_e32 v177, v180
	v_mov_b32_e32 v179, v181
	v_pk_add_f32 v[168:169], v[168:169], v[170:171]
	v_cndmask_b32_e32 v132, v165, v132, vcc
	v_mov_b32_e32 v171, v166
	v_pk_add_f32 v[172:173], v[172:173], v[174:175]
	v_pk_add_f32 v[174:175], v[176:177], v[178:179]
	v_mov_b32_e32 v170, v168
	v_mov_b32_e32 v166, v169
	v_lshlrev_b32_e32 v132, 2, v132
	v_mov_b32_e32 v168, v174
	v_mov_b32_e32 v169, v172
	v_mov_b32_e32 v172, v175
	v_pk_add_f32 v[166:167], v[170:171], v[166:167]
	v_pk_add_f32 v[168:169], v[168:169], v[172:173]
	v_mov_b32_e32 v171, v167
	s_nop 1
	v_permlane16_swap_b32_e32 v167, v171
	v_mov_b32_e32 v170, v166
	s_nop 1
	v_permlane16_swap_b32_e32 v166, v170
	v_mov_b32_e32 v173, v169
	s_nop 1
	v_permlane16_swap_b32_e32 v169, v173
	v_mov_b32_e32 v172, v168
	s_nop 1
	v_permlane16_swap_b32_e32 v168, v172
	v_cmp_lt_i32_e32 vcc, v145, v147
	v_mov_b64_e32 v[174:175], s[28:29]
	s_waitcnt lgkmcnt(2)
	v_pk_add_f32 v[166:167], v[166:167], v[170:171]
	v_cndmask_b32_e32 v141, v165, v145, vcc
	v_lshlrev_b32_e32 v141, 2, v141
	s_waitcnt lgkmcnt(0)
	v_pk_add_f32 v[168:169], v[168:169], v[172:173]
	v_mov_b32_e32 v171, v167
	s_nop 1
	v_permlane32_swap_b32_e32 v167, v171
	v_mov_b32_e32 v170, v166
	s_nop 1
	v_permlane32_swap_b32_e32 v166, v170
	v_mov_b32_e32 v173, v169
	s_nop 1
	v_permlane32_swap_b32_e32 v169, v173
	v_mov_b32_e32 v172, v168
	s_nop 1
	v_permlane32_swap_b32_e32 v168, v172
	v_mov_b32_e32 v176, v183
	v_mov_b32_e32 v177, v184
	s_waitcnt lgkmcnt(2)
	v_pk_add_f32 v[166:167], v[166:167], v[170:171]
	v_mov_b32_e32 v183, v185
	s_waitcnt lgkmcnt(0)
	v_pk_add_f32 v[168:169], v[168:169], v[172:173]
	v_pk_fma_f32 v[166:167], v[166:167], s[26:27], v[174:175] op_sel_hi:[1,0,0]
	v_mov_b32_e32 v172, v187
	v_mov_b32_e32 v173, v188
	v_mov_b32_e32 v187, v189
	v_mul_f32_e32 v143, 0x4b800000, v167
	v_cmp_gt_f32_e32 vcc, s58, v167
	v_pk_add_f32 v[170:171], v[176:177], v[182:183]
	v_pk_add_f32 v[172:173], v[172:173], v[186:187]
	v_cndmask_b32_e32 v143, v167, v143, vcc
	v_mov_b32_e32 v176, v172
	v_mov_b32_e32 v177, v170
	v_mov_b32_e32 v170, v173
	v_rsq_f32_e32 v143, v143
	v_pk_add_f32 v[170:171], v[176:177], v[170:171]
	v_mov_b32_e32 v173, v171
	s_nop 1
	v_permlane16_swap_b32_e32 v171, v173
	v_mov_b32_e32 v172, v170
	s_nop 1
	v_permlane16_swap_b32_e32 v170, v172
	v_pk_fma_f32 v[168:169], v[168:169], s[26:27], v[174:175] op_sel_hi:[1,0,0]
	v_mul_f32_e32 v145, 0x4b800000, v166
	v_cmp_gt_f32_e64 s[6:7], s58, v166
	v_mul_f32_e32 v149, 0x45800000, v143
	v_mul_f32_e32 v147, 0x4b800000, v169
	v_cndmask_b32_e64 v145, v166, v145, s[6:7]
	v_cmp_gt_f32_e64 s[8:9], s58, v169
	v_cndmask_b32_e32 v166, v143, v149, vcc
	v_mul_f32_e32 v143, 0x4b800000, v168
	v_cmp_gt_f32_e32 vcc, s58, v168
	v_cndmask_b32_e64 v147, v169, v147, s[8:9]
	v_mov_b32_e32 v176, v195
	v_cndmask_b32_e32 v143, v168, v143, vcc
	s_waitcnt lgkmcnt(0)
	v_pk_add_f32 v[168:169], v[170:171], v[172:173]
	v_mov_b32_e32 v171, v169
	s_nop 1
	v_permlane32_swap_b32_e32 v169, v171
	v_mov_b32_e32 v170, v168
	s_nop 1
	v_permlane32_swap_b32_e32 v168, v170
	v_mov_b32_e32 v177, v196
	v_mov_b32_e32 v195, v197
	v_pk_add_f32 v[176:177], v[176:177], v[194:195]
	v_rsq_f32_e32 v145, v145
	s_waitcnt lgkmcnt(0)
; #define PG8_GAS __attribute__((address_space(1)))
; __device__ __forceinline__ unsigned pk2_(float lo, float hi) { f32x2c_t v = {lo, hi}; bf16x2c_t b = __builtin_convertvector(v, bf16x2c_t); return __builtin_bit_cast(unsigned, b); }
; __device__ __forceinline__ float silu_f(float x) { return x * __builtin_amdgcn_rcpf(1.0f + __builtin_amdgcn_exp2f(-1.4426950408889634f * x)); }
; __device__ __forceinline__ float row_rstd(const float* parts, int r, int fq) {
;     const f32x4 p = *(const PG8_GAS f32x4*)(parts + (size_t)r * 16 + 4 * fq);
;     float s = (p[0] + p[1]) + (p[2] + p[3]);
;     s += __shfl_xor(s, 16); s += __shfl_xor(s, 32);
;     return rsqrtf(s * (1.0f / 1024.0f) + RMS_EPS);
;     __device__ __forceinline__ void operator()(const f32x4 (&acc)[2][2][4][2], const Unit& u, int wr, int wc, int fr, int fq) const {
;     ...
;             for (int m = 0; m < 4; ++m) {
;                 const int r = row0 + ai * HALF + m * 16; const float s = rs8[ai][m];
;                 float o[8];
; #pragma unroll
;                 for (int n = 0; n < 2; ++n)
; #pragma unroll
;                     for (int i = 0; i < 4; ++i) o[4 * n + i] = silu_f(acc[ai][0][m][n][i] * s) * (acc[ai][1][m][n][i] * s);
;                 u32x4 w; w.x = pk2_(o[0], o[1]); w.y = pk2_(o[2], o[3]); w.z = pk2_(o[4], o[5]); w.w = pk2_(o[6], o[7]);
;                 *(PG8_GAS u32x4*)(O + (size_t)r * 2816 + col0) = w;
	v_pk_add_f32 v[168:169], v[168:169], v[170:171]
	v_mov_b32_e32 v170, v191
	v_mov_b32_e32 v171, v192
	v_mov_b32_e32 v191, v193
	v_pk_add_f32 v[170:171], v[170:171], v[190:191]
	v_mov_b32_e32 v178, v176
	v_mov_b32_e32 v179, v170
	v_mov_b32_e32 v170, v177
	v_rsq_f32_e32 v147, v147
	v_pk_add_f32 v[170:171], v[178:179], v[170:171]
	v_mov_b32_e32 v177, v171
	s_nop 1
	v_permlane16_swap_b32_e32 v171, v177
	v_mov_b32_e32 v176, v170
	s_nop 1
	v_permlane16_swap_b32_e32 v170, v176
	v_mul_f32_e32 v150, 0x45800000, v145
	v_cndmask_b32_e64 v172, v145, v150, s[6:7]
	v_mul_f32_e32 v145, 0x45800000, v147
	v_pk_fma_f32 v[168:169], v[168:169], s[26:27], v[174:175] op_sel_hi:[1,0,0]
	v_cndmask_b32_e64 v164, v147, v145, s[8:9]
	v_mul_f32_e32 v147, 0x4b800000, v169
	v_cmp_gt_f32_e64 s[6:7], s58, v169
	v_mul_f32_e32 v132, 0x4b800000, v168
	v_cmp_gt_f32_e64 s[8:9], s58, v168
	v_cndmask_b32_e64 v147, v169, v147, s[6:7]
	v_rsq_f32_e32 v143, v143
	v_cndmask_b32_e64 v132, v168, v132, s[8:9]
	s_waitcnt lgkmcnt(0)
	v_pk_add_f32 v[168:169], v[170:171], v[176:177]
	v_mov_b32_e32 v171, v169
	s_nop 1
	v_permlane32_swap_b32_e32 v169, v171
	v_mov_b32_e32 v170, v168
	s_nop 1
	v_permlane32_swap_b32_e32 v168, v170
	v_rsq_f32_e32 v147, v147
	v_mul_f32_e32 v145, 0x45800000, v143
	v_cndmask_b32_e32 v162, v143, v145, vcc
	v_rsq_f32_e32 v132, v132
	s_waitcnt lgkmcnt(0)
	v_pk_add_f32 v[168:169], v[168:169], v[170:171]
	v_mul_f32_e32 v141, 0x45800000, v147
	v_pk_fma_f32 v[168:169], v[168:169], s[26:27], v[174:175] op_sel_hi:[1,0,0]
	v_cndmask_b32_e64 v158, v147, v141, s[6:7]
	v_mul_f32_e32 v143, 0x4b800000, v169
	v_cmp_gt_f32_e32 vcc, s58, v169
	v_mul_f32_e32 v145, 0x4b800000, v168
	v_cmp_gt_f32_e64 s[6:7], s58, v168
	v_cndmask_b32_e32 v143, v169, v143, vcc
	v_rsq_f32_e32 v143, v143
	v_cndmask_b32_e64 v145, v168, v145, s[6:7]
	v_rsq_f32_e32 v145, v145
	v_mul_f32_e32 v141, 0x45800000, v132
	v_cndmask_b32_e64 v154, v132, v141, s[8:9]
	v_mul_f32_e32 v132, 0x45800000, v143
	v_cndmask_b32_e32 v150, v143, v132, vcc
	v_mul_f32_e32 v132, 0x45800000, v145
	v_cndmask_b32_e64 v132, v145, v132, s[6:7]
	s_lshl_b32 s6, s60, 7
	v_lshl_or_b32 v141, v200, 3, s6
	v_pk_mul_f32 v[124:125], v[124:125], v[166:167] op_sel_hi:[1,0]
	v_or_b32_e32 v168, s54, v141
	v_mul_f32_e32 v141, 0xbfb8aa3b, v124
	v_exp_f32_e32 v141, v141
	v_mul_f32_e32 v143, 0xbfb8aa3b, v125
	v_exp_f32_e32 v143, v143
	v_pk_mul_f32 v[126:127], v[126:127], v[166:167] op_sel_hi:[1,0]
	v_add_f32_e32 v141, 1.0, v141
	v_rcp_f32_e32 v170, v141
	v_add_f32_e32 v141, 1.0, v143
	v_mul_f32_e32 v143, 0xbfb8aa3b, v126
	v_exp_f32_e32 v143, v143
	v_mul_f32_e32 v145, 0xbfb8aa3b, v127
	v_exp_f32_e32 v145, v145
	v_rcp_f32_e32 v171, v141
	v_add_f32_e32 v141, 1.0, v143
	v_rcp_f32_e32 v174, v141
	v_add_f32_e32 v141, 1.0, v145
	v_rcp_f32_e32 v175, v141
	v_pk_mul_f32 v[124:125], v[124:125], v[170:171]
	v_pk_mul_f32 v[116:117], v[116:117], v[166:167] op_sel_hi:[1,0]
	v_pk_mul_f32 v[120:121], v[120:121], v[166:167] op_sel_hi:[1,0]
	v_pk_mul_f32 v[116:117], v[116:117], v[124:125]
	v_pk_mul_f32 v[124:125], v[126:127], v[174:175]
	v_mul_f32_e32 v126, 0xbfb8aa3b, v120
	v_mul_f32_e32 v127, 0xbfb8aa3b, v121
	v_exp_f32_e32 v126, v126
	v_exp_f32_e32 v127, v127
	v_pk_mul_f32 v[118:119], v[118:119], v[166:167] op_sel_hi:[1,0]
	v_pk_mul_f32 v[122:123], v[122:123], v[166:167] op_sel_hi:[1,0]
	v_pk_mul_f32 v[118:119], v[118:119], v[124:125]
	v_add_f32_e32 v124, 1.0, v126
	v_add_f32_e32 v125, 1.0, v127
	v_mul_f32_e32 v126, 0xbfb8aa3b, v122
	v_mul_f32_e32 v127, 0xbfb8aa3b, v123
	v_exp_f32_e32 v126, v126
	v_exp_f32_e32 v127, v127
	v_rcp_f32_e32 v124, v124
	v_rcp_f32_e32 v125, v125
	v_add_f32_e32 v126, 1.0, v126
	v_add_f32_e32 v127, 1.0, v127
	v_rcp_f32_e32 v126, v126
	v_rcp_f32_e32 v127, v127
	v_pk_mul_f32 v[120:121], v[120:121], v[124:125]
	v_pk_mul_f32 v[112:113], v[112:113], v[166:167] op_sel_hi:[1,0]
	v_pk_mul_f32 v[114:115], v[114:115], v[166:167] op_sel_hi:[1,0]
	v_pk_mul_f32 v[112:113], v[112:113], v[120:121]
	v_pk_mul_f32 v[120:121], v[122:123], v[126:127]
	v_ashrrev_i32_e32 v169, 31, v168
	v_pk_mul_f32 v[114:115], v[114:115], v[120:121]
	v_cvt_pk_bf16_f32 v116, v116, v117
	v_cvt_pk_bf16_f32 v117, v118, v119
	v_cvt_pk_bf16_f32 v118, v112, v113
	v_mov_b64_e32 v[112:113], s[14:15]
	v_cvt_pk_bf16_f32 v119, v114, v115
	v_mad_i64_i32 v[120:121], s[6:7], v160, s59, v[112:113]
	v_lshlrev_b64 v[114:115], 1, v[168:169]
	v_pk_mul_f32 v[108:109], v[108:109], v[172:173] op_sel_hi:[1,0]
	v_lshl_add_u64 v[120:121], v[120:121], 0, v[114:115]
	v_mul_f32_e32 v122, 0xbfb8aa3b, v108
	v_mul_f32_e32 v123, 0xbfb8aa3b, v109
	v_pk_mul_f32 v[110:111], v[110:111], v[172:173] op_sel_hi:[1,0]
	v_exp_f32_e32 v122, v122
	v_exp_f32_e32 v123, v123
	global_store_dwordx4 v[120:121], v[116:119], off
	v_pk_mul_f32 v[100:101], v[100:101], v[172:173] op_sel_hi:[1,0]
	v_pk_mul_f32 v[104:105], v[104:105], v[172:173] op_sel_hi:[1,0]
	v_mul_f32_e32 v118, 0xbfb8aa3b, v110
	v_mul_f32_e32 v119, 0xbfb8aa3b, v111
	v_exp_f32_e32 v118, v118
	v_exp_f32_e32 v119, v119
	v_add_f32_e32 v116, 1.0, v122
	v_add_f32_e32 v117, 1.0, v123
	v_rcp_f32_e32 v116, v116
	v_rcp_f32_e32 v117, v117
	v_add_f32_e32 v118, 1.0, v118
	v_add_f32_e32 v119, 1.0, v119
	v_rcp_f32_e32 v118, v118
	v_rcp_f32_e32 v119, v119
	v_pk_mul_f32 v[108:109], v[108:109], v[116:117]
	v_pk_mul_f32 v[102:103], v[102:103], v[172:173] op_sel_hi:[1,0]
	v_pk_mul_f32 v[100:101], v[100:101], v[108:109]
	v_pk_mul_f32 v[108:109], v[110:111], v[118:119]
	v_mul_f32_e32 v110, 0xbfb8aa3b, v104
	v_mul_f32_e32 v111, 0xbfb8aa3b, v105
	v_exp_f32_e32 v110, v110
	v_exp_f32_e32 v111, v111
	v_pk_mul_f32 v[106:107], v[106:107], v[172:173] op_sel_hi:[1,0]
	v_pk_mul_f32 v[102:103], v[102:103], v[108:109]
; #define PG8_GAS __attribute__((address_space(1)))
; __device__ __forceinline__ unsigned pk2_(float lo, float hi) { f32x2c_t v = {lo, hi}; bf16x2c_t b = __builtin_convertvector(v, bf16x2c_t); return __builtin_bit_cast(unsigned, b); }
; __device__ __forceinline__ float silu_f(float x) { return x * __builtin_amdgcn_rcpf(1.0f + __builtin_amdgcn_exp2f(-1.4426950408889634f * x)); }
;     __device__ __forceinline__ void operator()(const f32x4 (&acc)[2][2][4][2], const Unit& u, int wr, int wc, int fr, int fq) const {
;     ...
;             for (int m = 0; m < 4; ++m) {
;                 const int r = row0 + ai * HALF + m * 16; const float s = rs8[ai][m];
;                 float o[8];
; #pragma unroll
;                 for (int n = 0; n < 2; ++n)
; #pragma unroll
;                     for (int i = 0; i < 4; ++i) o[4 * n + i] = silu_f(acc[ai][0][m][n][i] * s) * (acc[ai][1][m][n][i] * s);
;                 u32x4 w; w.x = pk2_(o[0], o[1]); w.y = pk2_(o[2], o[3]); w.z = pk2_(o[4], o[5]); w.w = pk2_(o[6], o[7]);
;                 *(PG8_GAS u32x4*)(O + (size_t)r * 2816 + col0) = w;
	v_add_f32_e32 v108, 1.0, v110
	v_add_f32_e32 v109, 1.0, v111
	v_mul_f32_e32 v110, 0xbfb8aa3b, v106
	v_mul_f32_e32 v111, 0xbfb8aa3b, v107
	v_exp_f32_e32 v110, v110
	v_exp_f32_e32 v111, v111
	v_rcp_f32_e32 v108, v108
	v_rcp_f32_e32 v109, v109
	v_add_f32_e32 v110, 1.0, v110
	v_add_f32_e32 v111, 1.0, v111
	v_rcp_f32_e32 v110, v110
	v_rcp_f32_e32 v111, v111
	v_pk_mul_f32 v[104:105], v[104:105], v[108:109]
	v_pk_mul_f32 v[96:97], v[96:97], v[172:173] op_sel_hi:[1,0]
	v_pk_mul_f32 v[98:99], v[98:99], v[172:173] op_sel_hi:[1,0]
	v_pk_mul_f32 v[104:105], v[96:97], v[104:105]
	v_pk_mul_f32 v[96:97], v[106:107], v[110:111]
	v_pk_mul_f32 v[92:93], v[92:93], v[164:165] op_sel_hi:[1,0]
	v_pk_mul_f32 v[106:107], v[98:99], v[96:97]
	v_cvt_pk_bf16_f32 v96, v100, v101
	v_mad_i64_i32 v[100:101], s[6:7], v156, s59, v[112:113]
	v_cvt_pk_bf16_f32 v97, v102, v103
	v_cvt_pk_bf16_f32 v98, v104, v105
	v_cvt_pk_bf16_f32 v99, v106, v107
	v_lshl_add_u64 v[100:101], v[100:101], 0, v[114:115]
	v_mul_f32_e32 v102, 0xbfb8aa3b, v92
	v_mul_f32_e32 v103, 0xbfb8aa3b, v93
	v_pk_mul_f32 v[94:95], v[94:95], v[164:165] op_sel_hi:[1,0]
	v_exp_f32_e32 v102, v102
	v_exp_f32_e32 v103, v103
	global_store_dwordx4 v[100:101], v[96:99], off
	v_pk_mul_f32 v[84:85], v[84:85], v[164:165] op_sel_hi:[1,0]
	v_pk_mul_f32 v[88:89], v[88:89], v[164:165] op_sel_hi:[1,0]
	v_mul_f32_e32 v98, 0xbfb8aa3b, v94
	v_mul_f32_e32 v99, 0xbfb8aa3b, v95
	v_exp_f32_e32 v98, v98
	v_exp_f32_e32 v99, v99
	v_add_f32_e32 v96, 1.0, v102
	v_add_f32_e32 v97, 1.0, v103
	v_rcp_f32_e32 v96, v96
	v_rcp_f32_e32 v97, v97
	v_add_f32_e32 v98, 1.0, v98
	v_add_f32_e32 v99, 1.0, v99
	v_rcp_f32_e32 v98, v98
	v_rcp_f32_e32 v99, v99
	v_pk_mul_f32 v[92:93], v[92:93], v[96:97]
	v_pk_mul_f32 v[86:87], v[86:87], v[164:165] op_sel_hi:[1,0]
	v_pk_mul_f32 v[84:85], v[84:85], v[92:93]
	v_pk_mul_f32 v[92:93], v[94:95], v[98:99]
	v_mul_f32_e32 v94, 0xbfb8aa3b, v88
	v_mul_f32_e32 v95, 0xbfb8aa3b, v89
	v_exp_f32_e32 v94, v94
	v_exp_f32_e32 v95, v95
	v_pk_mul_f32 v[90:91], v[90:91], v[164:165] op_sel_hi:[1,0]
	v_pk_mul_f32 v[86:87], v[86:87], v[92:93]
	v_add_f32_e32 v92, 1.0, v94
	v_add_f32_e32 v93, 1.0, v95
	v_mul_f32_e32 v94, 0xbfb8aa3b, v90
	v_mul_f32_e32 v95, 0xbfb8aa3b, v91
	v_exp_f32_e32 v94, v94
	v_exp_f32_e32 v95, v95
	v_rcp_f32_e32 v92, v92
	v_rcp_f32_e32 v93, v93
	v_add_f32_e32 v94, 1.0, v94
	v_add_f32_e32 v95, 1.0, v95
	v_rcp_f32_e32 v94, v94
	v_rcp_f32_e32 v95, v95
	v_pk_mul_f32 v[88:89], v[88:89], v[92:93]
	v_pk_mul_f32 v[80:81], v[80:81], v[164:165] op_sel_hi:[1,0]
	v_pk_mul_f32 v[82:83], v[82:83], v[164:165] op_sel_hi:[1,0]
	v_pk_mul_f32 v[88:89], v[80:81], v[88:89]
	v_pk_mul_f32 v[80:81], v[90:91], v[94:95]
	v_pk_mul_f32 v[76:77], v[76:77], v[162:163] op_sel_hi:[1,0]
	v_pk_mul_f32 v[90:91], v[82:83], v[80:81]
	v_cvt_pk_bf16_f32 v80, v84, v85
	v_mad_i64_i32 v[84:85], s[6:7], v152, s59, v[112:113]
	v_cvt_pk_bf16_f32 v81, v86, v87
	v_cvt_pk_bf16_f32 v82, v88, v89
	v_cvt_pk_bf16_f32 v83, v90, v91
	v_lshl_add_u64 v[84:85], v[84:85], 0, v[114:115]
	v_mul_f32_e32 v86, 0xbfb8aa3b, v76
	v_mul_f32_e32 v87, 0xbfb8aa3b, v77
	v_pk_mul_f32 v[78:79], v[78:79], v[162:163] op_sel_hi:[1,0]
	v_exp_f32_e32 v86, v86
	v_exp_f32_e32 v87, v87
	global_store_dwordx4 v[84:85], v[80:83], off
	v_pk_mul_f32 v[68:69], v[68:69], v[162:163] op_sel_hi:[1,0]
	v_pk_mul_f32 v[72:73], v[72:73], v[162:163] op_sel_hi:[1,0]
	v_mul_f32_e32 v82, 0xbfb8aa3b, v78
	v_mul_f32_e32 v83, 0xbfb8aa3b, v79
	v_exp_f32_e32 v82, v82
	v_exp_f32_e32 v83, v83
	v_add_f32_e32 v80, 1.0, v86
	v_add_f32_e32 v81, 1.0, v87
	v_rcp_f32_e32 v80, v80
	v_rcp_f32_e32 v81, v81
	v_add_f32_e32 v82, 1.0, v82
	v_add_f32_e32 v83, 1.0, v83
	v_rcp_f32_e32 v82, v82
	v_rcp_f32_e32 v83, v83
	v_pk_mul_f32 v[76:77], v[76:77], v[80:81]
	v_pk_mul_f32 v[70:71], v[70:71], v[162:163] op_sel_hi:[1,0]
	v_pk_mul_f32 v[68:69], v[68:69], v[76:77]
	v_pk_mul_f32 v[76:77], v[78:79], v[82:83]
	v_mul_f32_e32 v78, 0xbfb8aa3b, v72
	v_mul_f32_e32 v79, 0xbfb8aa3b, v73
	v_exp_f32_e32 v78, v78
	v_exp_f32_e32 v79, v79
	v_pk_mul_f32 v[74:75], v[74:75], v[162:163] op_sel_hi:[1,0]
	v_pk_mul_f32 v[70:71], v[70:71], v[76:77]
	v_add_f32_e32 v76, 1.0, v78
	v_add_f32_e32 v77, 1.0, v79
	v_mul_f32_e32 v78, 0xbfb8aa3b, v74
	v_mul_f32_e32 v79, 0xbfb8aa3b, v75
	v_exp_f32_e32 v78, v78
	v_exp_f32_e32 v79, v79
	v_rcp_f32_e32 v76, v76
	v_rcp_f32_e32 v77, v77
	v_add_f32_e32 v78, 1.0, v78
	v_add_f32_e32 v79, 1.0, v79
	v_rcp_f32_e32 v78, v78
	v_rcp_f32_e32 v79, v79
	v_pk_mul_f32 v[72:73], v[72:73], v[76:77]
	v_pk_mul_f32 v[64:65], v[64:65], v[162:163] op_sel_hi:[1,0]
	v_pk_mul_f32 v[66:67], v[66:67], v[162:163] op_sel_hi:[1,0]
	v_pk_mul_f32 v[72:73], v[64:65], v[72:73]
	v_pk_mul_f32 v[64:65], v[74:75], v[78:79]
	v_pk_mul_f32 v[60:61], v[60:61], v[158:159] op_sel_hi:[1,0]
	v_pk_mul_f32 v[74:75], v[66:67], v[64:65]
	v_cvt_pk_bf16_f32 v64, v68, v69
	v_mad_i64_i32 v[68:69], s[6:7], v148, s59, v[112:113]
	v_cvt_pk_bf16_f32 v65, v70, v71
	v_cvt_pk_bf16_f32 v66, v72, v73
	v_cvt_pk_bf16_f32 v67, v74, v75
	v_lshl_add_u64 v[68:69], v[68:69], 0, v[114:115]
	v_mul_f32_e32 v70, 0xbfb8aa3b, v60
	v_mul_f32_e32 v71, 0xbfb8aa3b, v61
	v_pk_mul_f32 v[62:63], v[62:63], v[158:159] op_sel_hi:[1,0]
	v_exp_f32_e32 v70, v70
	v_exp_f32_e32 v71, v71
	global_store_dwordx4 v[68:69], v[64:67], off
	v_pk_mul_f32 v[52:53], v[52:53], v[158:159] op_sel_hi:[1,0]
	v_pk_mul_f32 v[56:57], v[56:57], v[158:159] op_sel_hi:[1,0]
	v_mul_f32_e32 v66, 0xbfb8aa3b, v62
	v_mul_f32_e32 v67, 0xbfb8aa3b, v63
	v_exp_f32_e32 v66, v66
	v_exp_f32_e32 v67, v67
	v_add_f32_e32 v64, 1.0, v70
	v_add_f32_e32 v65, 1.0, v71
	v_rcp_f32_e32 v64, v64
	v_rcp_f32_e32 v65, v65
	v_add_f32_e32 v66, 1.0, v66
; #define PG8_GAS __attribute__((address_space(1)))
; __device__ __forceinline__ unsigned pk2_(float lo, float hi) { f32x2c_t v = {lo, hi}; bf16x2c_t b = __builtin_convertvector(v, bf16x2c_t); return __builtin_bit_cast(unsigned, b); }
; __device__ __forceinline__ float silu_f(float x) { return x * __builtin_amdgcn_rcpf(1.0f + __builtin_amdgcn_exp2f(-1.4426950408889634f * x)); }
;     __device__ __forceinline__ void operator()(const f32x4 (&acc)[2][2][4][2], const Unit& u, int wr, int wc, int fr, int fq) const {
;     ...
;             for (int m = 0; m < 4; ++m) {
;                 const int r = row0 + ai * HALF + m * 16; const float s = rs8[ai][m];
;                 float o[8];
; #pragma unroll
;                 for (int n = 0; n < 2; ++n)
; #pragma unroll
;                     for (int i = 0; i < 4; ++i) o[4 * n + i] = silu_f(acc[ai][0][m][n][i] * s) * (acc[ai][1][m][n][i] * s);
;                 u32x4 w; w.x = pk2_(o[0], o[1]); w.y = pk2_(o[2], o[3]); w.z = pk2_(o[4], o[5]); w.w = pk2_(o[6], o[7]);
;                 *(PG8_GAS u32x4*)(O + (size_t)r * 2816 + col0) = w;
	v_add_f32_e32 v67, 1.0, v67
	v_rcp_f32_e32 v66, v66
	v_rcp_f32_e32 v67, v67
	v_pk_mul_f32 v[60:61], v[60:61], v[64:65]
	v_pk_mul_f32 v[54:55], v[54:55], v[158:159] op_sel_hi:[1,0]
	v_pk_mul_f32 v[52:53], v[52:53], v[60:61]
	v_pk_mul_f32 v[60:61], v[62:63], v[66:67]
	v_mul_f32_e32 v62, 0xbfb8aa3b, v56
	v_mul_f32_e32 v63, 0xbfb8aa3b, v57
	v_exp_f32_e32 v62, v62
	v_exp_f32_e32 v63, v63
	v_pk_mul_f32 v[58:59], v[58:59], v[158:159] op_sel_hi:[1,0]
	v_pk_mul_f32 v[54:55], v[54:55], v[60:61]
	v_add_f32_e32 v60, 1.0, v62
	v_add_f32_e32 v61, 1.0, v63
	v_mul_f32_e32 v62, 0xbfb8aa3b, v58
	v_mul_f32_e32 v63, 0xbfb8aa3b, v59
	v_exp_f32_e32 v62, v62
	v_exp_f32_e32 v63, v63
	v_rcp_f32_e32 v60, v60
	v_rcp_f32_e32 v61, v61
	v_add_f32_e32 v62, 1.0, v62
	v_add_f32_e32 v63, 1.0, v63
	v_rcp_f32_e32 v62, v62
	v_rcp_f32_e32 v63, v63
	v_pk_mul_f32 v[56:57], v[56:57], v[60:61]
	v_pk_mul_f32 v[48:49], v[48:49], v[158:159] op_sel_hi:[1,0]
	v_pk_mul_f32 v[50:51], v[50:51], v[158:159] op_sel_hi:[1,0]
	v_pk_mul_f32 v[56:57], v[48:49], v[56:57]
	v_pk_mul_f32 v[48:49], v[58:59], v[62:63]
	v_pk_mul_f32 v[44:45], v[44:45], v[154:155] op_sel_hi:[1,0]
	v_pk_mul_f32 v[58:59], v[50:51], v[48:49]
	v_cvt_pk_bf16_f32 v48, v52, v53
	v_mad_i64_i32 v[52:53], s[6:7], v146, s59, v[112:113]
	v_cvt_pk_bf16_f32 v49, v54, v55
	v_cvt_pk_bf16_f32 v50, v56, v57
	v_cvt_pk_bf16_f32 v51, v58, v59
	v_lshl_add_u64 v[52:53], v[52:53], 0, v[114:115]
	v_mul_f32_e32 v54, 0xbfb8aa3b, v44
	v_mul_f32_e32 v55, 0xbfb8aa3b, v45
	v_pk_mul_f32 v[46:47], v[46:47], v[154:155] op_sel_hi:[1,0]
	v_exp_f32_e32 v54, v54
	v_exp_f32_e32 v55, v55
	global_store_dwordx4 v[52:53], v[48:51], off
	v_pk_mul_f32 v[36:37], v[36:37], v[154:155] op_sel_hi:[1,0]
	v_pk_mul_f32 v[40:41], v[40:41], v[154:155] op_sel_hi:[1,0]
	v_mul_f32_e32 v50, 0xbfb8aa3b, v46
	v_mul_f32_e32 v51, 0xbfb8aa3b, v47
	v_exp_f32_e32 v50, v50
	v_exp_f32_e32 v51, v51
	v_add_f32_e32 v48, 1.0, v54
	v_add_f32_e32 v49, 1.0, v55
	v_rcp_f32_e32 v48, v48
	v_rcp_f32_e32 v49, v49
	v_add_f32_e32 v50, 1.0, v50
	v_add_f32_e32 v51, 1.0, v51
	v_rcp_f32_e32 v50, v50
	v_rcp_f32_e32 v51, v51
	v_pk_mul_f32 v[44:45], v[44:45], v[48:49]
	v_pk_mul_f32 v[38:39], v[38:39], v[154:155] op_sel_hi:[1,0]
	v_pk_mul_f32 v[36:37], v[36:37], v[44:45]
	v_pk_mul_f32 v[44:45], v[46:47], v[50:51]
	v_mul_f32_e32 v46, 0xbfb8aa3b, v40
	v_mul_f32_e32 v47, 0xbfb8aa3b, v41
	v_exp_f32_e32 v46, v46
	v_exp_f32_e32 v47, v47
	v_pk_mul_f32 v[42:43], v[42:43], v[154:155] op_sel_hi:[1,0]
	v_pk_mul_f32 v[38:39], v[38:39], v[44:45]
	v_add_f32_e32 v44, 1.0, v46
	v_add_f32_e32 v45, 1.0, v47
	v_mul_f32_e32 v46, 0xbfb8aa3b, v42
	v_mul_f32_e32 v47, 0xbfb8aa3b, v43
	v_exp_f32_e32 v46, v46
	v_exp_f32_e32 v47, v47
	v_rcp_f32_e32 v44, v44
	v_rcp_f32_e32 v45, v45
	v_add_f32_e32 v46, 1.0, v46
	v_add_f32_e32 v47, 1.0, v47
	v_rcp_f32_e32 v46, v46
	v_rcp_f32_e32 v47, v47
	v_pk_mul_f32 v[40:41], v[40:41], v[44:45]
	v_pk_mul_f32 v[32:33], v[32:33], v[154:155] op_sel_hi:[1,0]
	v_pk_mul_f32 v[34:35], v[34:35], v[154:155] op_sel_hi:[1,0]
	v_pk_mul_f32 v[40:41], v[32:33], v[40:41]
	v_pk_mul_f32 v[32:33], v[42:43], v[46:47]
	v_pk_mul_f32 v[28:29], v[28:29], v[150:151] op_sel_hi:[1,0]
	v_pk_mul_f32 v[42:43], v[34:35], v[32:33]
	v_cvt_pk_bf16_f32 v32, v36, v37
	v_mad_i64_i32 v[36:37], s[6:7], v144, s59, v[112:113]
	v_cvt_pk_bf16_f32 v33, v38, v39
	v_cvt_pk_bf16_f32 v34, v40, v41
	v_cvt_pk_bf16_f32 v35, v42, v43
	v_lshl_add_u64 v[36:37], v[36:37], 0, v[114:115]
	v_mul_f32_e32 v38, 0xbfb8aa3b, v28
	v_mul_f32_e32 v39, 0xbfb8aa3b, v29
	v_pk_mul_f32 v[30:31], v[30:31], v[150:151] op_sel_hi:[1,0]
	v_exp_f32_e32 v38, v38
	v_exp_f32_e32 v39, v39
	global_store_dwordx4 v[36:37], v[32:35], off
	v_pk_mul_f32 v[20:21], v[20:21], v[150:151] op_sel_hi:[1,0]
	v_pk_mul_f32 v[24:25], v[24:25], v[150:151] op_sel_hi:[1,0]
; #define PG8_GAS __attribute__((address_space(1)))
; __device__ __forceinline__ unsigned pk2_(float lo, float hi) { f32x2c_t v = {lo, hi}; bf16x2c_t b = __builtin_convertvector(v, bf16x2c_t); return __builtin_bit_cast(unsigned, b); }
; __device__ __forceinline__ float silu_f(float x) { return x * __builtin_amdgcn_rcpf(1.0f + __builtin_amdgcn_exp2f(-1.4426950408889634f * x)); }
; #define PG8_BAR __builtin_amdgcn_s_barrier()
;     __device__ __forceinline__ void operator()(const f32x4 (&acc)[2][2][4][2], const Unit& u, int wr, int wc, int fr, int fq) const {
;     ...
;             for (int m = 0; m < 4; ++m) {
;                 const int r = row0 + ai * HALF + m * 16; const float s = rs8[ai][m];
;                 float o[8];
; #pragma unroll
;                 for (int n = 0; n < 2; ++n)
; #pragma unroll
;                     for (int i = 0; i < 4; ++i) o[4 * n + i] = silu_f(acc[ai][0][m][n][i] * s) * (acc[ai][1][m][n][i] * s);
;                 u32x4 w; w.x = pk2_(o[0], o[1]); w.y = pk2_(o[2], o[3]); w.z = pk2_(o[4], o[5]); w.w = pk2_(o[6], o[7]);
;                 *(PG8_GAS u32x4*)(O + (size_t)r * 2816 + col0) = w;
; template <class Epi, class Sched, bool ALIGN_EPI = false, bool SP2 = false>
; __device__ __forceinline__ void gemm_phase(PG8_LAS unsigned char* lds, const Gemm g, const Sched& S, const Epi& E) {
;     ...
;         if (!has_next) break;
; #pragma unroll
;         for (int a = 0; a < 2; ++a)
; #pragma unroll
;             for (int b = 0; b < 2; ++b)
; #pragma unroll
;                 for (int m = 0; m < 4; ++m)
; #pragma unroll
;                     for (int n = 0; n < 2; ++n) acc[a][b][m][n] = (f32x4){0.f, 0.f, 0.f, 0.f};
;         cur = nxt; cA = nA; cB = nB; ++ui;
;         if constexpr (ALIGN_EPI) { if (wr == 1) PG8_BAR; }
	v_mul_f32_e32 v34, 0xbfb8aa3b, v30
	v_mul_f32_e32 v35, 0xbfb8aa3b, v31
	v_exp_f32_e32 v34, v34
	v_exp_f32_e32 v35, v35
	v_add_f32_e32 v32, 1.0, v38
	v_add_f32_e32 v33, 1.0, v39
	v_rcp_f32_e32 v32, v32
	v_rcp_f32_e32 v33, v33
	v_add_f32_e32 v34, 1.0, v34
	v_add_f32_e32 v35, 1.0, v35
	v_rcp_f32_e32 v34, v34
	v_rcp_f32_e32 v35, v35
	v_pk_mul_f32 v[28:29], v[28:29], v[32:33]
	v_pk_mul_f32 v[22:23], v[22:23], v[150:151] op_sel_hi:[1,0]
	v_pk_mul_f32 v[20:21], v[20:21], v[28:29]
	v_pk_mul_f32 v[28:29], v[30:31], v[34:35]
	v_mul_f32_e32 v30, 0xbfb8aa3b, v24
	v_mul_f32_e32 v31, 0xbfb8aa3b, v25
	v_exp_f32_e32 v30, v30
	v_exp_f32_e32 v31, v31
	v_pk_mul_f32 v[26:27], v[26:27], v[150:151] op_sel_hi:[1,0]
	v_pk_mul_f32 v[22:23], v[22:23], v[28:29]
	v_add_f32_e32 v28, 1.0, v30
	v_add_f32_e32 v29, 1.0, v31
	v_mul_f32_e32 v30, 0xbfb8aa3b, v26
	v_mul_f32_e32 v31, 0xbfb8aa3b, v27
	v_exp_f32_e32 v30, v30
	v_exp_f32_e32 v31, v31
	v_rcp_f32_e32 v28, v28
	v_rcp_f32_e32 v29, v29
	v_add_f32_e32 v30, 1.0, v30
	v_add_f32_e32 v31, 1.0, v31
	v_rcp_f32_e32 v30, v30
	v_rcp_f32_e32 v31, v31
	v_pk_mul_f32 v[24:25], v[24:25], v[28:29]
	v_pk_mul_f32 v[16:17], v[16:17], v[150:151] op_sel_hi:[1,0]
	v_pk_mul_f32 v[18:19], v[18:19], v[150:151] op_sel_hi:[1,0]
	v_pk_mul_f32 v[24:25], v[16:17], v[24:25]
	v_pk_mul_f32 v[16:17], v[26:27], v[30:31]
	v_pk_mul_f32 v[12:13], v[12:13], v[132:133] op_sel_hi:[1,0]
	v_pk_mul_f32 v[26:27], v[18:19], v[16:17]
	v_cvt_pk_bf16_f32 v16, v20, v21
	v_mad_i64_i32 v[20:21], s[6:7], v142, s59, v[112:113]
	v_cvt_pk_bf16_f32 v17, v22, v23
	v_cvt_pk_bf16_f32 v18, v24, v25
	v_cvt_pk_bf16_f32 v19, v26, v27
	v_lshl_add_u64 v[20:21], v[20:21], 0, v[114:115]
	v_mul_f32_e32 v22, 0xbfb8aa3b, v12
	v_mul_f32_e32 v23, 0xbfb8aa3b, v13
	v_pk_mul_f32 v[14:15], v[14:15], v[132:133] op_sel_hi:[1,0]
	v_exp_f32_e32 v22, v22
	v_exp_f32_e32 v23, v23
	global_store_dwordx4 v[20:21], v[16:19], off
	v_pk_mul_f32 v[4:5], v[4:5], v[132:133] op_sel_hi:[1,0]
	v_pk_mul_f32 v[8:9], v[8:9], v[132:133] op_sel_hi:[1,0]
	v_mul_f32_e32 v18, 0xbfb8aa3b, v14
	v_mul_f32_e32 v19, 0xbfb8aa3b, v15
	v_exp_f32_e32 v18, v18
	v_exp_f32_e32 v19, v19
	v_add_f32_e32 v16, 1.0, v22
	v_add_f32_e32 v17, 1.0, v23
	v_rcp_f32_e32 v16, v16
	v_rcp_f32_e32 v17, v17
	v_add_f32_e32 v18, 1.0, v18
	v_add_f32_e32 v19, 1.0, v19
	v_rcp_f32_e32 v18, v18
	v_rcp_f32_e32 v19, v19
	v_pk_mul_f32 v[12:13], v[12:13], v[16:17]
	v_pk_mul_f32 v[6:7], v[6:7], v[132:133] op_sel_hi:[1,0]
	v_pk_mul_f32 v[4:5], v[4:5], v[12:13]
	v_pk_mul_f32 v[12:13], v[14:15], v[18:19]
	v_mul_f32_e32 v14, 0xbfb8aa3b, v8
	v_mul_f32_e32 v15, 0xbfb8aa3b, v9
	v_exp_f32_e32 v14, v14
	v_exp_f32_e32 v15, v15
	v_pk_mul_f32 v[10:11], v[10:11], v[132:133] op_sel_hi:[1,0]
	v_pk_mul_f32 v[6:7], v[6:7], v[12:13]
	v_add_f32_e32 v12, 1.0, v14
	v_add_f32_e32 v13, 1.0, v15
	v_mul_f32_e32 v14, 0xbfb8aa3b, v10
	v_mul_f32_e32 v15, 0xbfb8aa3b, v11
	v_exp_f32_e32 v14, v14
	v_exp_f32_e32 v15, v15
	v_rcp_f32_e32 v12, v12
	v_rcp_f32_e32 v13, v13
	v_add_f32_e32 v14, 1.0, v14
	v_add_f32_e32 v15, 1.0, v15
	v_rcp_f32_e32 v14, v14
	v_rcp_f32_e32 v15, v15
	v_pk_mul_f32 v[8:9], v[8:9], v[12:13]
	v_pk_mul_f32 v[0:1], v[0:1], v[132:133] op_sel_hi:[1,0]
	v_pk_mul_f32 v[2:3], v[2:3], v[132:133] op_sel_hi:[1,0]
	v_pk_mul_f32 v[8:9], v[0:1], v[8:9]
	v_pk_mul_f32 v[0:1], v[10:11], v[14:15]
	s_andn2_b64 vcc, exec, s[4:5]
	v_pk_mul_f32 v[10:11], v[2:3], v[0:1]
	v_cvt_pk_bf16_f32 v0, v4, v5
	v_mad_i64_i32 v[4:5], s[6:7], v140, s59, v[112:113]
	v_cvt_pk_bf16_f32 v1, v6, v7
	v_cvt_pk_bf16_f32 v2, v8, v9
	v_cvt_pk_bf16_f32 v3, v10, v11
	v_lshl_add_u64 v[4:5], v[4:5], 0, v[114:115]
	s_mov_b64 s[4:5], -1
	global_store_dwordx4 v[4:5], v[0:3], off
	s_cbranch_vccnz .LBB0_690
	s_andn2_b64 vcc, exec, s[12:13]
	s_cbranch_vccnz .LBB0_689
	s_barrier
	s_branch .LBB0_689

; #define PG8_GAS __attribute__((address_space(1)))
; __device__ __forceinline__ float row_rstd(const float* parts, int r, int fq) {
;     const f32x4 p = *(const PG8_GAS f32x4*)(parts + (size_t)r * 16 + 4 * fq);
;     float s = (p[0] + p[1]) + (p[2] + p[3]);
;     s += __shfl_xor(s, 16); s += __shfl_xor(s, 32);
;     return rsqrtf(s * (1.0f / 1024.0f) + RMS_EPS);
;     __device__ __forceinline__ void operator()(const f32x4 (&acc)[2][2][4][2], const Unit& u, int wr, int wc, int fr, int fq) const {
;         const int row0 = u.pm * BM + wr * 64 + fr, col0 = u.pn * BM + wc * 32 + 8 * fq;
;         float rs8[2][4];
; #pragma unroll
;         for (int ai = 0; ai < 2; ++ai)
; #pragma unroll
;             for (int m = 0; m < 4; ++m) { const int r = row0 + ai * HALF + m * 16; rs8[ai][m] = MODE == 0 ? row_rstd(sc, r, fq) : (MODE == 1 ? ((const PG8_GAS float*)sc)[r] : 1.f); }
.LBB0_847:
	s_lshl_b32 s8, s8, 8
	v_mov_b32_e32 v132, v252
	s_add_i32 s8, s8, s55
	s_nop 0
	v_bfe_u32 v196, v132, 4, 2
	v_and_or_b32 v152, v132, 15, s8
	v_lshlrev_b32_e32 v132, 4, v196
	v_ashrrev_i32_e32 v153, 31, v152
	v_or_b32_e32 v150, 16, v152
	v_lshl_add_u64 v[186:187], s[16:17], 0, v[132:133]
	v_lshlrev_b64 v[140:141], 6, v[152:153]
	v_ashrrev_i32_e32 v151, 31, v150
	v_or_b32_e32 v154, 32, v152
	v_lshl_add_u64 v[140:141], v[186:187], 0, v[140:141]
	v_lshlrev_b64 v[142:143], 6, v[150:151]
	v_ashrrev_i32_e32 v155, 31, v154
	v_lshl_add_u64 v[142:143], v[186:187], 0, v[142:143]
	global_load_dwordx4 v[162:165], v[140:141], off
	global_load_dwordx4 v[166:169], v[142:143], off
	v_lshlrev_b64 v[140:141], 6, v[154:155]
	v_or_b32_e32 v146, 48, v152
	v_lshl_add_u64 v[140:141], v[186:187], 0, v[140:141]
	v_ashrrev_i32_e32 v147, 31, v146
	global_load_dwordx4 v[170:173], v[140:141], off
	v_lshlrev_b64 v[140:141], 6, v[146:147]
	v_lshl_add_u64 v[140:141], v[186:187], 0, v[140:141]
	global_load_dwordx4 v[174:177], v[140:141], off
	v_add_u32_e32 v148, 0x80, v152
	v_ashrrev_i32_e32 v149, 31, v148
	v_lshlrev_b64 v[140:141], 6, v[148:149]
	v_add_u32_e32 v142, 0x90, v152
	v_lshl_add_u64 v[140:141], v[186:187], 0, v[140:141]
	v_ashrrev_i32_e32 v143, 31, v142
	global_load_dwordx4 v[178:181], v[140:141], off
	v_lshlrev_b64 v[140:141], 6, v[142:143]
	v_lshl_add_u64 v[140:141], v[186:187], 0, v[140:141]
	global_load_dwordx4 v[182:185], v[140:141], off
	v_and_b32_e32 v140, 64, v161
	v_add_u32_e32 v147, 64, v140
	v_add_u32_e32 v144, 0xa0, v152
	v_add_u32_e32 v140, 0xb0, v152
	v_ashrrev_i32_e32 v145, 31, v144
	v_ashrrev_i32_e32 v141, 31, v140
	v_lshlrev_b64 v[188:189], 6, v[144:145]
	v_lshlrev_b64 v[190:191], 6, v[140:141]
	v_lshl_add_u64 v[188:189], v[186:187], 0, v[188:189]
	v_lshl_add_u64 v[190:191], v[186:187], 0, v[190:191]
	global_load_dwordx4 v[186:189], v[188:189], off
	s_nop 0
	global_load_dwordx4 v[190:193], v[190:191], off
	v_xor_b32_e32 v132, 16, v161
	v_cmp_lt_i32_e32 vcc, v132, v147
	v_xor_b32_e32 v143, 32, v161
	s_waitcnt vmcnt(0)
	v_mov_b32_e32 v194, v163
	v_mov_b32_e32 v195, v164
	v_mov_b32_e32 v163, v165
	v_mov_b32_e32 v164, v167
	v_mov_b32_e32 v165, v168
	v_mov_b32_e32 v167, v169
	v_pk_add_f32 v[162:163], v[194:195], v[162:163]
	v_mov_b32_e32 v168, v171
	v_mov_b32_e32 v169, v172
	v_mov_b32_e32 v171, v173
	v_mov_b32_e32 v172, v175
	v_mov_b32_e32 v173, v176
	v_mov_b32_e32 v175, v177
	v_pk_add_f32 v[164:165], v[164:165], v[166:167]
	v_cndmask_b32_e32 v132, v161, v132, vcc
	v_mov_b32_e32 v167, v162
	v_pk_add_f32 v[168:169], v[168:169], v[170:171]
	v_pk_add_f32 v[170:171], v[172:173], v[174:175]
	v_mov_b32_e32 v166, v164
	v_mov_b32_e32 v162, v165
	v_lshlrev_b32_e32 v132, 2, v132
	v_mov_b32_e32 v164, v170
	v_mov_b32_e32 v165, v168
	v_mov_b32_e32 v168, v171
	v_pk_add_f32 v[162:163], v[166:167], v[162:163]
	v_pk_add_f32 v[164:165], v[164:165], v[168:169]
	v_mov_b32_e32 v167, v163
	s_nop 1
	v_permlane16_swap_b32_e32 v163, v167
	v_mov_b32_e32 v166, v162
	s_nop 1
	v_permlane16_swap_b32_e32 v162, v166
	v_mov_b32_e32 v169, v165
	s_nop 1
	v_permlane16_swap_b32_e32 v165, v169
	v_mov_b32_e32 v168, v164
	s_nop 1
	v_permlane16_swap_b32_e32 v164, v168
	v_cmp_lt_i32_e32 vcc, v143, v147
	v_mov_b64_e32 v[170:171], s[30:31]
	s_waitcnt lgkmcnt(2)
	v_pk_add_f32 v[162:163], v[162:163], v[166:167]
	v_cndmask_b32_e32 v141, v161, v143, vcc
	v_lshlrev_b32_e32 v141, 2, v141
	s_waitcnt lgkmcnt(0)
	v_pk_add_f32 v[164:165], v[164:165], v[168:169]
	v_mov_b32_e32 v167, v163
	s_nop 1
	v_permlane32_swap_b32_e32 v163, v167
	v_mov_b32_e32 v166, v162
	s_nop 1
	v_permlane32_swap_b32_e32 v162, v166
	v_mov_b32_e32 v169, v165
	s_nop 1
	v_permlane32_swap_b32_e32 v165, v169
	v_mov_b32_e32 v168, v164
	s_nop 1
	v_permlane32_swap_b32_e32 v164, v168
	v_mov_b32_e32 v172, v179
	v_mov_b32_e32 v173, v180
	s_waitcnt lgkmcnt(2)
	v_pk_add_f32 v[162:163], v[162:163], v[166:167]
	v_mov_b32_e32 v179, v181
	s_waitcnt lgkmcnt(0)
	v_pk_add_f32 v[164:165], v[164:165], v[168:169]
	v_pk_fma_f32 v[162:163], v[162:163], s[28:29], v[170:171] op_sel_hi:[1,0,0]
	v_mov_b32_e32 v168, v183
	v_mov_b32_e32 v169, v184
	v_mov_b32_e32 v183, v185
	v_mul_f32_e32 v143, 0x4b800000, v163
	v_cmp_gt_f32_e32 vcc, s60, v163
	v_pk_add_f32 v[166:167], v[172:173], v[178:179]
	v_pk_add_f32 v[168:169], v[168:169], v[182:183]
	v_cndmask_b32_e32 v143, v163, v143, vcc
	v_mov_b32_e32 v172, v168
	v_mov_b32_e32 v173, v166
	v_mov_b32_e32 v166, v169
	v_rsq_f32_e32 v143, v143
	v_pk_add_f32 v[166:167], v[172:173], v[166:167]
	v_mov_b32_e32 v169, v167
	s_nop 1
	v_permlane16_swap_b32_e32 v167, v169
	v_mov_b32_e32 v168, v166
	s_nop 1
	v_permlane16_swap_b32_e32 v166, v168
	v_pk_fma_f32 v[164:165], v[164:165], s[28:29], v[170:171] op_sel_hi:[1,0,0]
	v_mul_f32_e32 v145, 0x4b800000, v162
	v_cmp_gt_f32_e64 s[8:9], s60, v162
	v_mul_f32_e32 v149, 0x45800000, v143
	v_mul_f32_e32 v147, 0x4b800000, v165
	v_cndmask_b32_e64 v145, v162, v145, s[8:9]
	v_cmp_gt_f32_e64 s[10:11], s60, v165
	v_cndmask_b32_e32 v162, v143, v149, vcc
	v_mul_f32_e32 v143, 0x4b800000, v164
	v_cmp_gt_f32_e32 vcc, s60, v164
	v_cndmask_b32_e64 v147, v165, v147, s[10:11]
	v_mov_b32_e32 v174, v191
	v_cndmask_b32_e32 v143, v164, v143, vcc
	s_waitcnt lgkmcnt(0)
	v_pk_add_f32 v[164:165], v[166:167], v[168:169]
	v_mov_b32_e32 v167, v165
	s_nop 1
	v_permlane32_swap_b32_e32 v165, v167
	v_mov_b32_e32 v166, v164
	s_nop 1
	v_permlane32_swap_b32_e32 v164, v166
	v_mov_b32_e32 v175, v192
	v_mov_b32_e32 v191, v193
	v_pk_add_f32 v[174:175], v[174:175], v[190:191]
	v_rsq_f32_e32 v145, v145
	s_waitcnt lgkmcnt(0)
; #define PG8_GAS __attribute__((address_space(1)))
; __device__ __forceinline__ unsigned pk2_(float lo, float hi) { f32x2c_t v = {lo, hi}; bf16x2c_t b = __builtin_convertvector(v, bf16x2c_t); return __builtin_bit_cast(unsigned, b); }
; __device__ __forceinline__ float row_rstd(const float* parts, int r, int fq) {
;     const f32x4 p = *(const PG8_GAS f32x4*)(parts + (size_t)r * 16 + 4 * fq);
;     float s = (p[0] + p[1]) + (p[2] + p[3]);
;     s += __shfl_xor(s, 16); s += __shfl_xor(s, 32);
;     return rsqrtf(s * (1.0f / 1024.0f) + RMS_EPS);
;     __device__ __forceinline__ void operator()(const f32x4 (&acc)[2][2][4][2], const Unit& u, int wr, int wc, int fr, int fq) const {
;     ...
;         for (int ai = 0; ai < 2; ++ai)
; #pragma unroll
;             for (int m = 0; m < 4; ++m) {
;                 const int r = row0 + ai * HALF + m * 16;
;                 const float s = rs8[ai][m];
; #pragma unroll
;                 for (int bj = 0; bj < 2; ++bj) {
;                     f32x4 v0 = acc[ai][bj][m][0], v1 = acc[ai][bj][m][1];
;                     if (MODE == 2) { v0 = v0 * cs[bj][0]; v1 = v1 * cs[bj][1]; } else { v0 = v0 * s; v1 = v1 * s; }
;                     u32x4 w; w.x = pk2_(v0[0], v0[1]); w.y = pk2_(v0[2], v0[3]); w.z = pk2_(v1[0], v1[1]); w.w = pk2_(v1[2], v1[3]);
;                     *(PG8_GAS u32x4*)(O + (size_t)r * ldc + col0 + bj * HALF) = w;
;                 }
	v_pk_add_f32 v[164:165], v[164:165], v[166:167]
	v_mov_b32_e32 v166, v187
	v_mov_b32_e32 v167, v188
	v_mov_b32_e32 v187, v189
	v_pk_add_f32 v[166:167], v[166:167], v[186:187]
	v_mov_b32_e32 v176, v174
	v_mov_b32_e32 v177, v166
	v_mov_b32_e32 v166, v175
	v_rsq_f32_e32 v147, v147
	v_pk_add_f32 v[166:167], v[176:177], v[166:167]
	v_mov_b32_e32 v175, v167
	s_nop 1
	v_permlane16_swap_b32_e32 v167, v175
	v_mov_b32_e32 v174, v166
	s_nop 1
	v_permlane16_swap_b32_e32 v166, v174
	v_mul_f32_e32 v151, 0x45800000, v145
	v_cndmask_b32_e64 v168, v145, v151, s[8:9]
	v_mul_f32_e32 v145, 0x45800000, v147
	v_pk_fma_f32 v[164:165], v[164:165], s[28:29], v[170:171] op_sel_hi:[1,0,0]
	v_cndmask_b32_e64 v172, v147, v145, s[10:11]
	v_mul_f32_e32 v147, 0x4b800000, v165
	v_cmp_gt_f32_e64 s[8:9], s60, v165
	v_mul_f32_e32 v132, 0x4b800000, v164
	v_cmp_gt_f32_e64 s[10:11], s60, v164
	v_cndmask_b32_e64 v147, v165, v147, s[8:9]
	v_rsq_f32_e32 v143, v143
	v_cndmask_b32_e64 v132, v164, v132, s[10:11]
	s_waitcnt lgkmcnt(0)
	v_pk_add_f32 v[164:165], v[166:167], v[174:175]
	v_mov_b32_e32 v167, v165
	s_nop 1
	v_permlane32_swap_b32_e32 v165, v167
	v_mov_b32_e32 v166, v164
	s_nop 1
	v_permlane32_swap_b32_e32 v164, v166
	v_rsq_f32_e32 v147, v147
	v_mul_f32_e32 v145, 0x45800000, v143
	v_cndmask_b32_e32 v174, v143, v145, vcc
	v_rsq_f32_e32 v132, v132
	s_waitcnt lgkmcnt(0)
	v_pk_add_f32 v[164:165], v[164:165], v[166:167]
	v_mul_f32_e32 v141, 0x45800000, v147
	v_pk_fma_f32 v[164:165], v[164:165], s[28:29], v[170:171] op_sel_hi:[1,0,0]
	v_cndmask_b32_e64 v176, v147, v141, s[8:9]
	v_mul_f32_e32 v143, 0x4b800000, v165
	v_cmp_gt_f32_e32 vcc, s60, v165
	v_mul_f32_e32 v145, 0x4b800000, v164
	v_cmp_gt_f32_e64 s[8:9], s60, v164
	v_cndmask_b32_e32 v143, v165, v143, vcc
	v_rsq_f32_e32 v143, v143
	v_cndmask_b32_e64 v145, v164, v145, s[8:9]
	v_rsq_f32_e32 v145, v145
	v_mul_f32_e32 v141, 0x45800000, v132
	v_cndmask_b32_e64 v164, v132, v141, s[10:11]
	v_mul_f32_e32 v132, 0x45800000, v143
	v_cndmask_b32_e32 v156, v143, v132, vcc
	v_mul_f32_e32 v132, 0x45800000, v145
	v_cndmask_b32_e64 v132, v145, v132, s[8:9]
	s_lshl_b32 s8, s62, 8
	v_lshl_or_b32 v141, v196, 3, s8
	v_or_b32_e32 v166, s56, v141
	v_pk_mul_f32 v[126:127], v[126:127], v[162:163] op_sel_hi:[1,0]
	v_pk_mul_f32 v[124:125], v[124:125], v[162:163] op_sel_hi:[1,0]
	v_pk_mul_f32 v[120:121], v[120:121], v[162:163] op_sel_hi:[1,0]
	v_ashrrev_i32_e32 v167, 31, v166
	v_pk_mul_f32 v[122:123], v[122:123], v[162:163] op_sel_hi:[1,0]
	v_cvt_pk_bf16_f32 v124, v124, v125
	v_cvt_pk_bf16_f32 v125, v126, v127
	v_cvt_pk_bf16_f32 v126, v120, v121
	v_mov_b64_e32 v[120:121], s[14:15]
	v_cvt_pk_bf16_f32 v127, v122, v123
	v_mad_i64_i32 v[152:153], s[8:9], v152, s61, v[120:121]
	v_lshlrev_b64 v[122:123], 1, v[166:167]
	v_lshl_add_u64 v[152:153], v[152:153], 0, v[122:123]
	global_store_dwordx4 v[152:153], v[124:127], off
	v_pk_mul_f32 v[114:115], v[114:115], v[162:163] op_sel_hi:[1,0]
	v_pk_mul_f32 v[112:113], v[112:113], v[162:163] op_sel_hi:[1,0]
	v_pk_mul_f32 v[124:125], v[106:107], v[162:163] op_sel_hi:[1,0]
	v_pk_mul_f32 v[106:107], v[104:105], v[162:163] op_sel_hi:[1,0]
	v_cvt_pk_bf16_f32 v104, v112, v113
	v_cvt_pk_bf16_f32 v105, v114, v115
	v_cvt_pk_bf16_f32 v106, v106, v107
	v_cvt_pk_bf16_f32 v107, v124, v125
	global_store_dwordx4 v[152:153], v[104:107], off offset:256
	v_pk_mul_f32 v[108:109], v[108:109], v[168:169] op_sel_hi:[1,0]
	v_pk_mul_f32 v[110:111], v[110:111], v[168:169] op_sel_hi:[1,0]
	v_pk_mul_f32 v[106:107], v[118:119], v[168:169] op_sel_hi:[1,0]
	v_pk_mul_f32 v[104:105], v[116:117], v[168:169] op_sel_hi:[1,0]
	v_pk_mul_f32 v[98:99], v[98:99], v[168:169] op_sel_hi:[1,0]
	v_cvt_pk_bf16_f32 v104, v104, v105
	v_cvt_pk_bf16_f32 v105, v106, v107
	v_cvt_pk_bf16_f32 v106, v108, v109
	v_mad_i64_i32 v[108:109], s[8:9], v150, s61, v[120:121]
	v_cvt_pk_bf16_f32 v107, v110, v111
	v_lshl_add_u64 v[108:109], v[108:109], 0, v[122:123]
	global_store_dwordx4 v[108:109], v[104:107], off
	v_pk_mul_f32 v[96:97], v[96:97], v[168:169] op_sel_hi:[1,0]
	v_pk_mul_f32 v[92:93], v[92:93], v[172:173] op_sel_hi:[1,0]
	v_pk_mul_f32 v[104:105], v[90:91], v[168:169] op_sel_hi:[1,0]
	v_pk_mul_f32 v[90:91], v[88:89], v[168:169] op_sel_hi:[1,0]
	v_cvt_pk_bf16_f32 v88, v96, v97
	v_cvt_pk_bf16_f32 v89, v98, v99
	v_cvt_pk_bf16_f32 v90, v90, v91
	v_cvt_pk_bf16_f32 v91, v104, v105
	global_store_dwordx4 v[108:109], v[88:91], off offset:256
	v_pk_mul_f32 v[94:95], v[94:95], v[172:173] op_sel_hi:[1,0]
	v_pk_mul_f32 v[82:83], v[82:83], v[172:173] op_sel_hi:[1,0]
	v_pk_mul_f32 v[90:91], v[102:103], v[172:173] op_sel_hi:[1,0]
	v_pk_mul_f32 v[88:89], v[100:101], v[172:173] op_sel_hi:[1,0]
	v_pk_mul_f32 v[80:81], v[80:81], v[172:173] op_sel_hi:[1,0]
	v_cvt_pk_bf16_f32 v88, v88, v89
	v_cvt_pk_bf16_f32 v89, v90, v91
	v_cvt_pk_bf16_f32 v90, v92, v93
	v_mad_i64_i32 v[92:93], s[8:9], v154, s61, v[120:121]
	v_cvt_pk_bf16_f32 v91, v94, v95
	v_lshl_add_u64 v[92:93], v[92:93], 0, v[122:123]
	global_store_dwordx4 v[92:93], v[88:91], off
	v_pk_mul_f32 v[76:77], v[76:77], v[174:175] op_sel_hi:[1,0]
	v_pk_mul_f32 v[78:79], v[78:79], v[174:175] op_sel_hi:[1,0]
; #define PG8_GAS __attribute__((address_space(1)))
; __device__ __forceinline__ unsigned pk2_(float lo, float hi) { f32x2c_t v = {lo, hi}; bf16x2c_t b = __builtin_convertvector(v, bf16x2c_t); return __builtin_bit_cast(unsigned, b); }
; #define PG8_BAR __builtin_amdgcn_s_barrier()
;     __device__ __forceinline__ void operator()(const f32x4 (&acc)[2][2][4][2], const Unit& u, int wr, int wc, int fr, int fq) const {
;     ...
;         for (int ai = 0; ai < 2; ++ai)
; #pragma unroll
;             for (int m = 0; m < 4; ++m) {
;                 const int r = row0 + ai * HALF + m * 16;
;                 const float s = rs8[ai][m];
; #pragma unroll
;                 for (int bj = 0; bj < 2; ++bj) {
;                     f32x4 v0 = acc[ai][bj][m][0], v1 = acc[ai][bj][m][1];
;                     if (MODE == 2) { v0 = v0 * cs[bj][0]; v1 = v1 * cs[bj][1]; } else { v0 = v0 * s; v1 = v1 * s; }
;                     u32x4 w; w.x = pk2_(v0[0], v0[1]); w.y = pk2_(v0[2], v0[3]); w.z = pk2_(v1[0], v1[1]); w.w = pk2_(v1[2], v1[3]);
;                     *(PG8_GAS u32x4*)(O + (size_t)r * ldc + col0 + bj * HALF) = w;
;                 }
; template <class Epi, class Sched, bool ALIGN_EPI = false, bool SP2 = false>
; __device__ __forceinline__ void gemm_phase(PG8_LAS unsigned char* lds, const Gemm g, const Sched& S, const Epi& E) {
;     ...
;         if (!has_next) break;
; #pragma unroll
;         for (int a = 0; a < 2; ++a)
; #pragma unroll
;             for (int b = 0; b < 2; ++b)
; #pragma unroll
;                 for (int m = 0; m < 4; ++m)
; #pragma unroll
;                     for (int n = 0; n < 2; ++n) acc[a][b][m][n] = (f32x4){0.f, 0.f, 0.f, 0.f};
;         cur = nxt; cA = nA; cB = nB; ++ui;
;         if constexpr (ALIGN_EPI) { if (wr == 1) PG8_BAR; }
	v_pk_mul_f32 v[88:89], v[74:75], v[172:173] op_sel_hi:[1,0]
	v_pk_mul_f32 v[74:75], v[72:73], v[172:173] op_sel_hi:[1,0]
	v_cvt_pk_bf16_f32 v72, v80, v81
	v_cvt_pk_bf16_f32 v73, v82, v83
	v_cvt_pk_bf16_f32 v74, v74, v75
	v_cvt_pk_bf16_f32 v75, v88, v89
	global_store_dwordx4 v[92:93], v[72:75], off offset:256
	v_pk_mul_f32 v[70:71], v[70:71], v[174:175] op_sel_hi:[1,0]
	v_pk_mul_f32 v[68:69], v[68:69], v[174:175] op_sel_hi:[1,0]
	v_pk_mul_f32 v[74:75], v[86:87], v[174:175] op_sel_hi:[1,0]
	v_pk_mul_f32 v[72:73], v[84:85], v[174:175] op_sel_hi:[1,0]
	v_pk_mul_f32 v[60:61], v[60:61], v[176:177] op_sel_hi:[1,0]
	v_cvt_pk_bf16_f32 v72, v72, v73
	v_cvt_pk_bf16_f32 v73, v74, v75
	v_cvt_pk_bf16_f32 v74, v76, v77
	v_mad_i64_i32 v[76:77], s[8:9], v146, s61, v[120:121]
	v_cvt_pk_bf16_f32 v75, v78, v79
	v_lshl_add_u64 v[76:77], v[76:77], 0, v[122:123]
	global_store_dwordx4 v[76:77], v[72:75], off
	v_pk_mul_f32 v[62:63], v[62:63], v[176:177] op_sel_hi:[1,0]
	v_pk_mul_f32 v[50:51], v[50:51], v[176:177] op_sel_hi:[1,0]
	v_pk_mul_f32 v[72:73], v[66:67], v[174:175] op_sel_hi:[1,0]
	v_pk_mul_f32 v[66:67], v[64:65], v[174:175] op_sel_hi:[1,0]
	v_cvt_pk_bf16_f32 v64, v68, v69
	v_cvt_pk_bf16_f32 v65, v70, v71
	v_cvt_pk_bf16_f32 v66, v66, v67
	v_cvt_pk_bf16_f32 v67, v72, v73
	global_store_dwordx4 v[76:77], v[64:67], off offset:256
	v_pk_mul_f32 v[48:49], v[48:49], v[176:177] op_sel_hi:[1,0]
	v_pk_mul_f32 v[44:45], v[44:45], v[164:165] op_sel_hi:[1,0]
	v_pk_mul_f32 v[64:65], v[58:59], v[176:177] op_sel_hi:[1,0]
	v_pk_mul_f32 v[58:59], v[56:57], v[176:177] op_sel_hi:[1,0]
	v_cvt_pk_bf16_f32 v56, v60, v61
	v_mad_i64_i32 v[60:61], s[8:9], v148, s61, v[120:121]
	v_cvt_pk_bf16_f32 v57, v62, v63
	v_cvt_pk_bf16_f32 v58, v58, v59
	v_cvt_pk_bf16_f32 v59, v64, v65
	v_lshl_add_u64 v[60:61], v[60:61], 0, v[122:123]
	global_store_dwordx4 v[60:61], v[56:59], off
	v_pk_mul_f32 v[46:47], v[46:47], v[164:165] op_sel_hi:[1,0]
	v_pk_mul_f32 v[34:35], v[34:35], v[164:165] op_sel_hi:[1,0]
	v_pk_mul_f32 v[56:57], v[42:43], v[176:177] op_sel_hi:[1,0]
	v_pk_mul_f32 v[42:43], v[40:41], v[176:177] op_sel_hi:[1,0]
	v_cvt_pk_bf16_f32 v40, v48, v49
	v_cvt_pk_bf16_f32 v41, v50, v51
	v_cvt_pk_bf16_f32 v42, v42, v43
	v_cvt_pk_bf16_f32 v43, v56, v57
	global_store_dwordx4 v[60:61], v[40:43], off offset:256
	v_pk_mul_f32 v[32:33], v[32:33], v[164:165] op_sel_hi:[1,0]
	v_pk_mul_f32 v[28:29], v[28:29], v[156:157] op_sel_hi:[1,0]
	v_pk_mul_f32 v[42:43], v[54:55], v[164:165] op_sel_hi:[1,0]
	v_pk_mul_f32 v[40:41], v[52:53], v[164:165] op_sel_hi:[1,0]
	v_pk_mul_f32 v[30:31], v[30:31], v[156:157] op_sel_hi:[1,0]
	v_cvt_pk_bf16_f32 v40, v40, v41
	v_cvt_pk_bf16_f32 v41, v42, v43
	v_cvt_pk_bf16_f32 v42, v44, v45
	v_mad_i64_i32 v[44:45], s[8:9], v142, s61, v[120:121]
	v_cvt_pk_bf16_f32 v43, v46, v47
	v_lshl_add_u64 v[44:45], v[44:45], 0, v[122:123]
	global_store_dwordx4 v[44:45], v[40:43], off
	v_pk_mul_f32 v[18:19], v[18:19], v[156:157] op_sel_hi:[1,0]
	v_pk_mul_f32 v[16:17], v[16:17], v[156:157] op_sel_hi:[1,0]
	v_pk_mul_f32 v[40:41], v[26:27], v[164:165] op_sel_hi:[1,0]
	v_pk_mul_f32 v[26:27], v[24:25], v[164:165] op_sel_hi:[1,0]
	v_cvt_pk_bf16_f32 v24, v32, v33
	v_cvt_pk_bf16_f32 v25, v34, v35
	v_cvt_pk_bf16_f32 v26, v26, v27
	v_cvt_pk_bf16_f32 v27, v40, v41
	global_store_dwordx4 v[44:45], v[24:27], off offset:256
	v_pk_mul_f32 v[12:13], v[12:13], v[132:133] op_sel_hi:[1,0]
	v_pk_mul_f32 v[14:15], v[14:15], v[132:133] op_sel_hi:[1,0]
	v_pk_mul_f32 v[26:27], v[38:39], v[156:157] op_sel_hi:[1,0]
	v_pk_mul_f32 v[24:25], v[36:37], v[156:157] op_sel_hi:[1,0]
	v_pk_mul_f32 v[6:7], v[6:7], v[132:133] op_sel_hi:[1,0]
	v_cvt_pk_bf16_f32 v24, v24, v25
	v_cvt_pk_bf16_f32 v25, v26, v27
	v_cvt_pk_bf16_f32 v26, v28, v29
	v_mad_i64_i32 v[28:29], s[8:9], v144, s61, v[120:121]
	v_cvt_pk_bf16_f32 v27, v30, v31
	v_lshl_add_u64 v[28:29], v[28:29], 0, v[122:123]
	global_store_dwordx4 v[28:29], v[24:27], off
	v_pk_mul_f32 v[4:5], v[4:5], v[132:133] op_sel_hi:[1,0]
	s_andn2_b64 vcc, exec, s[6:7]
	v_pk_mul_f32 v[24:25], v[10:11], v[156:157] op_sel_hi:[1,0]
	v_pk_mul_f32 v[10:11], v[8:9], v[156:157] op_sel_hi:[1,0]
	v_cvt_pk_bf16_f32 v8, v16, v17
	v_cvt_pk_bf16_f32 v9, v18, v19
	v_cvt_pk_bf16_f32 v10, v10, v11
	v_cvt_pk_bf16_f32 v11, v24, v25
	global_store_dwordx4 v[28:29], v[8:11], off offset:256
	s_mov_b64 s[6:7], -1
	s_nop 0
	v_pk_mul_f32 v[10:11], v[22:23], v[132:133] op_sel_hi:[1,0]
	v_pk_mul_f32 v[8:9], v[20:21], v[132:133] op_sel_hi:[1,0]
	s_nop 0
	v_cvt_pk_bf16_f32 v8, v8, v9
	v_cvt_pk_bf16_f32 v9, v10, v11
	v_cvt_pk_bf16_f32 v10, v12, v13
	v_mad_i64_i32 v[12:13], s[8:9], v140, s61, v[120:121]
	v_cvt_pk_bf16_f32 v11, v14, v15
	v_lshl_add_u64 v[12:13], v[12:13], 0, v[122:123]
	global_store_dwordx4 v[12:13], v[8:11], off
	s_nop 1
	v_pk_mul_f32 v[8:9], v[2:3], v[132:133] op_sel_hi:[1,0]
	v_pk_mul_f32 v[2:3], v[0:1], v[132:133] op_sel_hi:[1,0]
	v_cvt_pk_bf16_f32 v0, v4, v5
	v_cvt_pk_bf16_f32 v1, v6, v7
	v_cvt_pk_bf16_f32 v2, v2, v3
	v_cvt_pk_bf16_f32 v3, v8, v9
	global_store_dwordx4 v[12:13], v[0:3], off offset:256
	s_cbranch_vccnz .LBB0_840
	s_andn2_b64 vcc, exec, s[12:13]
	s_cbranch_vccnz .LBB0_839
	s_barrier
	s_branch .LBB0_839

; #define GAS __attribute__((address_space(1)))
; __device__ __forceinline__ unsigned pk2(float lo, float hi) { f32x2_t v = {lo, hi}; bf16x2_t b = __builtin_convertvector(v, bf16x2_t); return __builtin_bit_cast(unsigned, b); }
; __device__ __forceinline__ f32x16 mfma32(bf16x8 a, bf16x8 b, f32x16 c) { return __builtin_amdgcn_mfma_f32_32x32x16_bf16(a, b, c, 0, 0, 0); }
; __device__ __forceinline__ void dsa_unit32(const Args& a, LAS unsigned char* lds, const LAS unsigned long long* maskl, int b, int qb, int tid, int wave, int lane) {
;     ...
;     l += __shfl_xor(l, 32);
;     const float il = 1.f / l;
;     bf16x8 of[8];
; #pragma unroll
;     for (int ks = 0; ks < 8; ++ks) { const int ct = ks >> 1, o8 = 8 * (ks & 1); u32x4 w;
;         w.x = pk2(O[ct][o8 + 0] * il, O[ct][o8 + 1] * il); w.y = pk2(O[ct][o8 + 2] * il, O[ct][o8 + 3] * il);
;         w.z = pk2(O[ct][o8 + 4] * il, O[ct][o8 + 5] * il); w.w = pk2(O[ct][o8 + 6] * il, O[ct][o8 + 7] * il); of[ks] = __builtin_bit_cast(bf16x8, w); }
; #pragma unroll
;     for (int vt = 0; vt < 2; ++vt) {
;         f32x16 acc;
; #pragma unroll
;         for (int i = 0; i < 16; ++i) acc[i] = 0.f;
;         const GAS bf16* wr = wuv + (size_t)(h * 64 + 32 * vt + l31) * 128 + 4 * hi;
; #pragma unroll
;         for (int ks = 0; ks < 8; ++ks) acc = mfma32(cat8(*(const GAS u32x2*)(wr + 16 * ks), *(const GAS u32x2*)(wr + 16 * ks + 8)), of[ks], acc);
.LBB0_1073:
	v_readlane_b32 s0, v254, 32
	v_readlane_b32 s1, v254, 33
	v_lshlrev_b32_e32 v92, 1, v182
	v_or_b32_e32 v90, s0, v5
	v_readlane_b32 s0, v254, 30
	v_mov_b32_e32 v93, v4
	v_readlane_b32 s1, v254, 31
	v_ashrrev_i32_e32 v91, 31, v90
	v_lshlrev_b64 v[0:1], 8, v[90:91]
	v_lshl_add_u64 v[98:99], s[0:1], 0, v[92:93]
	v_lshl_add_u64 v[96:97], v[98:99], 0, v[0:1]
	v_readlane_b32 s0, v254, 34
	v_lshlrev_b64 v[94:95], 11, v[178:179]
	v_readlane_b32 s1, v254, 35
	v_or_b32_e32 v100, 32, v90
	ds_bpermute_b32 v5, v181, v194
	v_lshl_add_u64 v[94:95], s[0:1], 0, v[94:95]
	v_lshl_add_u64 v[102:103], v[94:95], 0, v[92:93]
	v_lshl_add_u64 v[120:121], v[96:97], 0, v[92:93]
	global_load_dwordx4 v[0:3], v[120:121], off
	global_load_dwordx4 v[70:73], v[120:121], off offset:32
	global_load_dwordx4 v[74:77], v[120:121], off offset:64
	global_load_dwordx4 v[78:81], v[120:121], off offset:96
	global_load_dwordx4 v[82:85], v[120:121], off offset:128
	global_load_dwordx4 v[86:89], v[120:121], off offset:160
	global_load_dwordx4 v[90:93], v[120:121], off offset:192
	global_load_dwordx4 v[94:97], v[120:121], off offset:224
	s_nop 0
	s_waitcnt lgkmcnt(0)
	v_add_f32_e32 v5, v194, v5
	v_div_scale_f32 v104, s[0:1], v5, v5, 1.0
	v_rcp_f32_e32 v105, v104
	v_ashrrev_i32_e32 v101, 31, v100
	v_lshlrev_b64 v[100:101], 8, v[100:101]
	v_lshl_add_u64 v[98:99], v[98:99], 0, v[100:101]
	v_lshlrev_b32_e32 v122, 1, v182
	v_mov_b32_e32 v123, v4
	v_lshl_add_u64 v[122:123], v[98:99], 0, v[122:123]
	global_load_dwordx4 v[146:149], v[122:123], off
	global_load_dwordx4 v[150:153], v[122:123], off offset:32
	global_load_dwordx4 v[154:157], v[122:123], off offset:64
	global_load_dwordx4 v[158:161], v[122:123], off offset:96
	global_load_dwordx4 v[162:165], v[122:123], off offset:128
	global_load_dwordx4 v[166:169], v[122:123], off offset:160
	global_load_dwordx4 v[170:173], v[122:123], off offset:192
	global_load_dwordx4 v[174:177], v[122:123], off offset:224
	v_fma_f32 v101, -v104, v105, 1.0
	v_div_scale_f32 v100, vcc, 1.0, v5, 1.0
	v_fmac_f32_e32 v105, v101, v105
	v_mul_f32_e32 v101, v100, v105
	v_fma_f32 v106, -v104, v101, v100
	v_fmac_f32_e32 v101, v106, v105
	v_fma_f32 v100, -v104, v101, v100
	v_div_fmas_f32 v100, v100, v105, v101
	v_div_fixup_f32 v100, v100, v5, 1.0
	v_pk_mul_f32 v[54:55], v[54:55], v[100:101] op_sel_hi:[1,0]
	v_pk_mul_f32 v[56:57], v[56:57], v[100:101] op_sel_hi:[1,0]
	v_pk_mul_f32 v[58:59], v[58:59], v[100:101] op_sel_hi:[1,0]
	v_pk_mul_f32 v[60:61], v[60:61], v[100:101] op_sel_hi:[1,0]
	v_pk_mul_f32 v[112:113], v[38:39], v[100:101] op_sel_hi:[1,0]
	v_pk_mul_f32 v[114:115], v[40:41], v[100:101] op_sel_hi:[1,0]
	v_cvt_pk_bf16_f32 v38, v54, v55
	v_cvt_pk_bf16_f32 v39, v56, v57
	v_cvt_pk_bf16_f32 v40, v58, v59
	v_cvt_pk_bf16_f32 v41, v60, v61
	v_pk_mul_f32 v[104:105], v[62:63], v[100:101] op_sel_hi:[1,0]
	v_pk_mul_f32 v[106:107], v[64:65], v[100:101] op_sel_hi:[1,0]
	v_pk_mul_f32 v[108:109], v[66:67], v[100:101] op_sel_hi:[1,0]
	v_pk_mul_f32 v[110:111], v[68:69], v[100:101] op_sel_hi:[1,0]
	v_pk_mul_f32 v[116:117], v[42:43], v[100:101] op_sel_hi:[1,0]
	v_pk_mul_f32 v[118:119], v[44:45], v[100:101] op_sel_hi:[1,0]
	v_cvt_pk_bf16_f32 v42, v112, v113
	v_cvt_pk_bf16_f32 v43, v114, v115
	v_cvt_pk_bf16_f32 v44, v116, v117
	v_cvt_pk_bf16_f32 v45, v118, v119
	v_pk_mul_f32 v[46:47], v[46:47], v[100:101] op_sel_hi:[1,0]
	v_pk_mul_f32 v[48:49], v[48:49], v[100:101] op_sel_hi:[1,0]
	v_pk_mul_f32 v[50:51], v[50:51], v[100:101] op_sel_hi:[1,0]
	v_pk_mul_f32 v[52:53], v[52:53], v[100:101] op_sel_hi:[1,0]
	v_pk_mul_f32 v[30:31], v[30:31], v[100:101] op_sel_hi:[1,0]
	v_pk_mul_f32 v[32:33], v[32:33], v[100:101] op_sel_hi:[1,0]
	v_pk_mul_f32 v[34:35], v[34:35], v[100:101] op_sel_hi:[1,0]
	v_pk_mul_f32 v[36:37], v[36:37], v[100:101] op_sel_hi:[1,0]
	v_cvt_pk_bf16_f32 v30, v30, v31
	v_cvt_pk_bf16_f32 v31, v32, v33
	v_cvt_pk_bf16_f32 v32, v34, v35
	v_cvt_pk_bf16_f32 v33, v36, v37
	v_pk_mul_f32 v[6:7], v[6:7], v[100:101] op_sel_hi:[1,0]
	v_pk_mul_f32 v[8:9], v[8:9], v[100:101] op_sel_hi:[1,0]
	v_pk_mul_f32 v[10:11], v[10:11], v[100:101] op_sel_hi:[1,0]
	v_pk_mul_f32 v[12:13], v[12:13], v[100:101] op_sel_hi:[1,0]
	v_cvt_pk_bf16_f32 v34, v6, v7
	v_cvt_pk_bf16_f32 v35, v8, v9
	s_waitcnt vmcnt(8)
; #define GAS __attribute__((address_space(1)))
; __device__ __forceinline__ unsigned pk2(float lo, float hi) { f32x2_t v = {lo, hi}; bf16x2_t b = __builtin_convertvector(v, bf16x2_t); return __builtin_bit_cast(unsigned, b); }
; __device__ __forceinline__ f32x16 mfma32(bf16x8 a, bf16x8 b, f32x16 c) { return __builtin_amdgcn_mfma_f32_32x32x16_bf16(a, b, c, 0, 0, 0); }
; __device__ __forceinline__ void dsa_unit32(const Args& a, LAS unsigned char* lds, const LAS unsigned long long* maskl, int b, int qb, int tid, int wave, int lane) {
;     ...
; #pragma unroll
;     for (int vt = 0; vt < 2; ++vt) {
;         f32x16 acc;
; #pragma unroll
;         for (int i = 0; i < 16; ++i) acc[i] = 0.f;
;         const GAS bf16* wr = wuv + (size_t)(h * 64 + 32 * vt + l31) * 128 + 4 * hi;
; #pragma unroll
;         for (int ks = 0; ks < 8; ++ks) acc = mfma32(cat8(*(const GAS u32x2*)(wr + 16 * ks), *(const GAS u32x2*)(wr + 16 * ks + 8)), of[ks], acc);
; #pragma unroll
;         for (int g = 0; g < 4; ++g) { u32x2 w; w.x = pk2(acc[4 * g], acc[4 * g + 1]); w.y = pk2(acc[4 * g + 2], acc[4 * g + 3]);
;             *(GAS u32x2*)(Y + (rowb + t0 + l31) * DM + 512 + h * 64 + 32 * vt + 8 * g + 4 * hi) = w; }
;     }
	v_permlane32_swap_b32_e32 v0, v2
	v_permlane32_swap_b32_e32 v1, v3
	v_permlane32_swap_b32_e32 v70, v72
	v_permlane32_swap_b32_e32 v71, v73
	v_permlane32_swap_b32_e32 v74, v76
	v_permlane32_swap_b32_e32 v75, v77
	v_permlane32_swap_b32_e32 v78, v80
	v_permlane32_swap_b32_e32 v79, v81
	v_permlane32_swap_b32_e32 v82, v84
	v_permlane32_swap_b32_e32 v83, v85
	v_permlane32_swap_b32_e32 v86, v88
	v_permlane32_swap_b32_e32 v87, v89
	v_permlane32_swap_b32_e32 v90, v92
	v_permlane32_swap_b32_e32 v91, v93
	v_permlane32_swap_b32_e32 v94, v96
	v_permlane32_swap_b32_e32 v95, v97
	s_nop 1
	v_mfma_f32_32x32x16_bf16 v[54:69], v[0:3], v[38:41], 0
	v_cvt_pk_bf16_f32 v0, v104, v105
	v_cvt_pk_bf16_f32 v1, v106, v107
	v_cvt_pk_bf16_f32 v2, v108, v109
	v_cvt_pk_bf16_f32 v3, v110, v111
	v_cvt_pk_bf16_f32 v36, v10, v11
	v_cvt_pk_bf16_f32 v37, v12, v13
	v_pk_mul_f32 v[14:15], v[14:15], v[100:101] op_sel_hi:[1,0]
	v_mfma_f32_32x32x16_bf16 v[54:69], v[70:73], v[0:3], v[54:69]
	v_mul_f32_e64 v70, v22, v100
	v_mul_f32_e64 v71, v23, v100
	v_mul_f32_e64 v72, v24, v100
	v_mul_f32_e64 v73, v25, v100
	v_cvt_pk_bf16_f32 v22, v46, v47
	v_cvt_pk_bf16_f32 v23, v48, v49
	v_cvt_pk_bf16_f32 v24, v50, v51
	v_cvt_pk_bf16_f32 v25, v52, v53
	v_pk_mul_f32 v[6:7], v[16:17], v[100:101] op_sel_hi:[1,0]
	v_mfma_f32_32x32x16_bf16 v[54:69], v[74:77], v[42:45], v[54:69]
	v_mul_f32_e64 v74, v26, v100
	v_mul_f32_e64 v75, v27, v100
	v_mul_f32_e64 v76, v28, v100
	v_mul_f32_e64 v77, v29, v100
	v_cvt_pk_bf16_f32 v26, v70, v71
	v_cvt_pk_bf16_f32 v27, v72, v73
	v_cvt_pk_bf16_f32 v28, v74, v75
	v_cvt_pk_bf16_f32 v29, v76, v77
	v_pk_mul_f32 v[8:9], v[18:19], v[100:101] op_sel_hi:[1,0]
	v_mfma_f32_32x32x16_bf16 v[54:69], v[78:81], v[22:25], v[54:69]
	v_mul_f32_e64 v10, v20, v100
	v_mul_f32_e64 v11, v21, v100
	v_cvt_pk_bf16_f32 v46, v14, v15
	v_cvt_pk_bf16_f32 v47, v6, v7
	v_cvt_pk_bf16_f32 v48, v8, v9
	v_cvt_pk_bf16_f32 v49, v10, v11
	s_mov_b64 s[0:1], 0
	v_mfma_f32_32x32x16_bf16 v[54:69], v[82:85], v[26:29], v[54:69]
	v_mfma_f32_32x32x16_bf16 v[54:69], v[86:89], v[30:33], v[54:69]
	v_mfma_f32_32x32x16_bf16 v[54:69], v[90:93], v[34:37], v[54:69]
	v_mfma_f32_32x32x16_bf16 v[54:69], v[94:97], v[46:49], v[54:69]
	s_nop 11
	v_cvt_pk_bf16_f32 v6, v54, v55
	v_cvt_pk_bf16_f32 v7, v56, v57
	v_cvt_pk_bf16_f32 v8, v58, v59
	v_cvt_pk_bf16_f32 v9, v60, v61
	v_cvt_pk_bf16_f32 v10, v62, v63
	v_cvt_pk_bf16_f32 v11, v64, v65
	v_cvt_pk_bf16_f32 v12, v66, v67
	v_cvt_pk_bf16_f32 v13, v68, v69
	global_store_dwordx2 v[102:103], v[6:7], off offset:1024
	global_store_dwordx2 v[102:103], v[8:9], off offset:1040
	global_store_dwordx2 v[102:103], v[10:11], off offset:1056
	global_store_dwordx2 v[102:103], v[12:13], off offset:1072
	s_waitcnt vmcnt(4)
	v_permlane32_swap_b32_e32 v146, v148
	v_permlane32_swap_b32_e32 v147, v149
	v_permlane32_swap_b32_e32 v150, v152
	v_permlane32_swap_b32_e32 v151, v153
	v_permlane32_swap_b32_e32 v154, v156
	v_permlane32_swap_b32_e32 v155, v157
	v_permlane32_swap_b32_e32 v158, v160
	v_permlane32_swap_b32_e32 v159, v161
	v_permlane32_swap_b32_e32 v162, v164
	v_permlane32_swap_b32_e32 v163, v165
	v_permlane32_swap_b32_e32 v166, v168
	v_permlane32_swap_b32_e32 v167, v169
	v_permlane32_swap_b32_e32 v170, v172
	v_permlane32_swap_b32_e32 v171, v173
	v_permlane32_swap_b32_e32 v174, v176
	v_permlane32_swap_b32_e32 v175, v177
	s_nop 1
	v_mfma_f32_32x32x16_bf16 v[6:21], v[146:149], v[38:41], 0
	v_mfma_f32_32x32x16_bf16 v[6:21], v[150:153], v[0:3], v[6:21]
	v_mfma_f32_32x32x16_bf16 v[6:21], v[154:157], v[42:45], v[6:21]
	v_mfma_f32_32x32x16_bf16 v[6:21], v[158:161], v[22:25], v[6:21]
	v_mfma_f32_32x32x16_bf16 v[6:21], v[162:165], v[26:29], v[6:21]
	v_mfma_f32_32x32x16_bf16 v[6:21], v[166:169], v[30:33], v[6:21]
	v_mfma_f32_32x32x16_bf16 v[6:21], v[170:173], v[34:37], v[6:21]
	v_mfma_f32_32x32x16_bf16 v[6:21], v[174:177], v[46:49], v[6:21]
	s_nop 11
	v_cvt_pk_bf16_f32 v0, v6, v7
	v_cvt_pk_bf16_f32 v1, v8, v9
	v_cvt_pk_bf16_f32 v2, v10, v11
	v_cvt_pk_bf16_f32 v3, v12, v13
	v_cvt_pk_bf16_f32 v6, v14, v15
	v_cvt_pk_bf16_f32 v7, v16, v17
	v_cvt_pk_bf16_f32 v8, v18, v19
	v_cvt_pk_bf16_f32 v9, v20, v21
	global_store_dwordx2 v[102:103], v[0:1], off offset:1088
	global_store_dwordx2 v[102:103], v[2:3], off offset:1104
	global_store_dwordx2 v[102:103], v[6:7], off offset:1120
	global_store_dwordx2 v[102:103], v[8:9], off offset:1136

; #define PG8_GAS __attribute__((address_space(1)))
; __device__ __forceinline__ float row_rstd(const float* parts, int r, int fq) {
;     const f32x4 p = *(const PG8_GAS f32x4*)(parts + (size_t)r * 16 + 4 * fq);
;     float s = (p[0] + p[1]) + (p[2] + p[3]);
;     s += __shfl_xor(s, 16); s += __shfl_xor(s, 32);
;     return rsqrtf(s * (1.0f / 1024.0f) + RMS_EPS);
; }
;     __device__ __forceinline__ void operator()(const f32x4 (&acc)[2][2][4][2], const Unit& u, int wr, int wc, int fr, int fq) const {
;         const int row0 = u.pm * BM + wr * 64 + fr, col0 = u.pn * BM + wc * 32 + 8 * fq;
;         float rs8[2][4];
; #pragma unroll
;         for (int ai = 0; ai < 2; ++ai)
; #pragma unroll
;             for (int m = 0; m < 4; ++m) { const int r = row0 + ai * HALF + m * 16; rs8[ai][m] = MODE == 0 ? row_rstd(sc, r, fq) : (MODE == 1 ? ((const PG8_GAS float*)sc)[r] : 1.f); }
.LBB0_1462:
	s_lshl_b32 s8, s8, 8
	v_mov_b32_e32 v132, v252
	s_add_i32 s8, s8, s55
	v_cmp_lt_i32_e32 vcc, v227, v226
	v_bfe_u32 v161, v132, 4, 2
	v_and_or_b32 v154, v132, 15, s8
	v_lshlrev_b32_e32 v132, 4, v161
	v_ashrrev_i32_e32 v155, 31, v154
	v_or_b32_e32 v150, 16, v154
	v_lshl_add_u64 v[186:187], s[16:17], 0, v[132:133]
	v_lshlrev_b64 v[140:141], 6, v[154:155]
	v_ashrrev_i32_e32 v151, 31, v150
	v_or_b32_e32 v152, 32, v154
	v_lshl_add_u64 v[140:141], v[186:187], 0, v[140:141]
	v_lshlrev_b64 v[142:143], 6, v[150:151]
	v_ashrrev_i32_e32 v153, 31, v152
	v_lshl_add_u64 v[142:143], v[186:187], 0, v[142:143]
	global_load_dwordx4 v[162:165], v[140:141], off
	global_load_dwordx4 v[166:169], v[142:143], off
	v_lshlrev_b64 v[140:141], 6, v[152:153]
	v_or_b32_e32 v146, 48, v154
	v_lshl_add_u64 v[140:141], v[186:187], 0, v[140:141]
	v_ashrrev_i32_e32 v147, 31, v146
	global_load_dwordx4 v[170:173], v[140:141], off
	v_lshlrev_b64 v[140:141], 6, v[146:147]
	v_lshl_add_u64 v[140:141], v[186:187], 0, v[140:141]
	global_load_dwordx4 v[174:177], v[140:141], off
	v_add_u32_e32 v148, 0x80, v154
	v_ashrrev_i32_e32 v149, 31, v148
	v_lshlrev_b64 v[140:141], 6, v[148:149]
	v_add_u32_e32 v142, 0x90, v154
	v_lshl_add_u64 v[140:141], v[186:187], 0, v[140:141]
	v_ashrrev_i32_e32 v143, 31, v142
	global_load_dwordx4 v[178:181], v[140:141], off
	v_lshlrev_b64 v[140:141], 6, v[142:143]
	v_lshl_add_u64 v[140:141], v[186:187], 0, v[140:141]
	global_load_dwordx4 v[182:185], v[140:141], off
	v_add_u32_e32 v144, 0xa0, v154
	v_add_u32_e32 v140, 0xb0, v154
	v_ashrrev_i32_e32 v145, 31, v144
	v_ashrrev_i32_e32 v141, 31, v140
	v_lshlrev_b64 v[188:189], 6, v[144:145]
	v_lshlrev_b64 v[190:191], 6, v[140:141]
	v_lshl_add_u64 v[188:189], v[186:187], 0, v[188:189]
	v_lshl_add_u64 v[190:191], v[186:187], 0, v[190:191]
	global_load_dwordx4 v[186:189], v[188:189], off
	s_nop 0
	global_load_dwordx4 v[190:193], v[190:191], off
	v_cndmask_b32_e32 v132, v253, v227, vcc
	v_lshlrev_b32_e32 v132, 2, v132
	v_xor_b32_e32 v156, 32, v253
	v_cmp_lt_i32_e32 vcc, v156, v226
	v_mov_b64_e32 v[194:195], s[30:31]
	s_waitcnt vmcnt(0)
	v_mov_b32_e32 v196, v163
	v_mov_b32_e32 v197, v164
	v_mov_b32_e32 v163, v165
	v_mov_b32_e32 v164, v167
	v_mov_b32_e32 v165, v168
	v_mov_b32_e32 v167, v169
	v_pk_add_f32 v[162:163], v[196:197], v[162:163]
	v_pk_add_f32 v[164:165], v[164:165], v[166:167]
	v_mov_b32_e32 v168, v171
	v_mov_b32_e32 v169, v172
	v_mov_b32_e32 v171, v173
	v_mov_b32_e32 v172, v175
	v_mov_b32_e32 v173, v176
	v_mov_b32_e32 v175, v177
	v_mov_b32_e32 v167, v162
	v_mov_b32_e32 v166, v164
	v_mov_b32_e32 v162, v165
	v_pk_add_f32 v[168:169], v[168:169], v[170:171]
	v_pk_add_f32 v[170:171], v[172:173], v[174:175]
	v_pk_add_f32 v[162:163], v[166:167], v[162:163]
	v_mov_b32_e32 v164, v170
	v_mov_b32_e32 v165, v168
	v_mov_b32_e32 v168, v171
	v_mov_b32_e32 v167, v163
	s_nop 1
	v_permlane16_swap_b32_e32 v163, v167
	v_mov_b32_e32 v166, v162
	s_nop 1
	v_permlane16_swap_b32_e32 v162, v166
	v_pk_add_f32 v[164:165], v[164:165], v[168:169]
	v_mov_b32_e32 v169, v165
	s_nop 1
	v_permlane16_swap_b32_e32 v165, v169
	v_mov_b32_e32 v168, v164
	s_nop 1
	v_permlane16_swap_b32_e32 v164, v168
	v_cndmask_b32_e32 v156, v253, v156, vcc
	v_lshlrev_b32_e32 v156, 2, v156
	s_waitcnt lgkmcnt(2)
	v_pk_add_f32 v[162:163], v[162:163], v[166:167]
	v_mov_b32_e32 v167, v163
	s_nop 1
	v_permlane32_swap_b32_e32 v163, v167
	v_mov_b32_e32 v166, v162
	s_nop 1
	v_permlane32_swap_b32_e32 v162, v166
	s_waitcnt lgkmcnt(2)
	v_pk_add_f32 v[164:165], v[164:165], v[168:169]
	v_mov_b32_e32 v169, v165
	s_nop 1
	v_permlane32_swap_b32_e32 v165, v169
	v_mov_b32_e32 v168, v164
	s_nop 1
	v_permlane32_swap_b32_e32 v164, v168
	v_mov_b32_e32 v170, v179
	s_waitcnt lgkmcnt(2)
	v_pk_add_f32 v[162:163], v[162:163], v[166:167]
	v_mov_b32_e32 v171, v180
	v_pk_fma_f32 v[162:163], v[162:163], s[28:29], v[194:195] op_sel_hi:[1,0,0]
	s_waitcnt lgkmcnt(0)
	v_pk_add_f32 v[164:165], v[164:165], v[168:169]
	v_mul_f32_e32 v166, 0x4b800000, v163
	v_mul_f32_e32 v167, 0x4b800000, v162
	v_cmp_gt_f32_e32 vcc, s60, v163
	v_cmp_gt_f32_e64 s[8:9], s60, v162
	v_mov_b32_e32 v179, v181
	v_pk_fma_f32 v[164:165], v[164:165], s[28:29], v[194:195] op_sel_hi:[1,0,0]
	v_cndmask_b32_e32 v163, v163, v166, vcc
	v_cndmask_b32_e64 v162, v162, v167, s[8:9]
	v_mov_b32_e32 v166, v183
	v_mov_b32_e32 v167, v184
	v_mov_b32_e32 v183, v185
	v_pk_add_f32 v[170:171], v[170:171], v[178:179]
	v_mul_f32_e32 v168, 0x4b800000, v165
	v_cmp_gt_f32_e64 s[10:11], s60, v165
	v_pk_add_f32 v[166:167], v[166:167], v[182:183]
	v_rsq_f32_e32 v172, v162
	v_cndmask_b32_e64 v162, v165, v168, s[10:11]
	v_mov_b32_e32 v168, v166
	v_mov_b32_e32 v169, v170
	v_mov_b32_e32 v170, v167
	v_rsq_f32_e32 v163, v163
	v_pk_add_f32 v[166:167], v[168:169], v[170:171]
	v_mov_b32_e32 v169, v167
	s_nop 1
	v_permlane16_swap_b32_e32 v167, v169
	v_mov_b32_e32 v168, v166
	s_nop 1
	v_permlane16_swap_b32_e32 v166, v168
	v_rsq_f32_e32 v173, v162
	v_mul_f32_e32 v162, 0x45800000, v163
	v_cndmask_b32_e32 v162, v163, v162, vcc
	v_mul_f32_e32 v163, 0x4b800000, v164
	v_cmp_gt_f32_e32 vcc, s60, v164
	v_mul_f32_e32 v174, 0x45800000, v172
	s_nop 0
	v_cndmask_b32_e32 v163, v164, v163, vcc
	s_waitcnt lgkmcnt(0)
	v_pk_add_f32 v[164:165], v[166:167], v[168:169]
	v_mov_b32_e32 v167, v165
	s_nop 1
	v_permlane32_swap_b32_e32 v165, v167
	v_mov_b32_e32 v166, v164
	s_nop 1
	v_permlane32_swap_b32_e32 v164, v166
	v_cndmask_b32_e64 v168, v172, v174, s[8:9]
	v_mul_f32_e32 v169, 0x45800000, v173
	v_cndmask_b32_e64 v170, v173, v169, s[10:11]
	v_mov_b32_e32 v172, v191
	s_waitcnt lgkmcnt(0)
; #define PG8_GAS __attribute__((address_space(1)))
; __device__ __forceinline__ unsigned pk2_(float lo, float hi) { f32x2c_t v = {lo, hi}; bf16x2c_t b = __builtin_convertvector(v, bf16x2c_t); return __builtin_bit_cast(unsigned, b); }
; __device__ __forceinline__ float row_rstd(const float* parts, int r, int fq) {
;     const f32x4 p = *(const PG8_GAS f32x4*)(parts + (size_t)r * 16 + 4 * fq);
;     float s = (p[0] + p[1]) + (p[2] + p[3]);
;     s += __shfl_xor(s, 16); s += __shfl_xor(s, 32);
;     return rsqrtf(s * (1.0f / 1024.0f) + RMS_EPS);
; }
;     __device__ __forceinline__ void operator()(const f32x4 (&acc)[2][2][4][2], const Unit& u, int wr, int wc, int fr, int fq) const {
;     ...
; #pragma unroll
;         for (int ai = 0; ai < 2; ++ai)
; #pragma unroll
;             for (int m = 0; m < 4; ++m) {
;                 const int r = row0 + ai * HALF + m * 16;
;                 const float s = rs8[ai][m];
; #pragma unroll
;                 for (int bj = 0; bj < 2; ++bj) {
;                     f32x4 v0 = acc[ai][bj][m][0], v1 = acc[ai][bj][m][1];
;                     if (MODE == 2) { v0 = v0 * cs[bj][0]; v1 = v1 * cs[bj][1]; } else { v0 = v0 * s; v1 = v1 * s; }
;                     u32x4 w; w.x = pk2_(v0[0], v0[1]); w.y = pk2_(v0[2], v0[3]); w.z = pk2_(v1[0], v1[1]); w.w = pk2_(v1[2], v1[3]);
;                     *(PG8_GAS u32x4*)(O + (size_t)r * ldc + col0 + bj * HALF) = w;
;                 }
	v_pk_add_f32 v[164:165], v[164:165], v[166:167]
	v_mov_b32_e32 v167, v188
	v_pk_fma_f32 v[164:165], v[164:165], s[28:29], v[194:195] op_sel_hi:[1,0,0]
	v_mov_b32_e32 v173, v192
	v_mul_f32_e32 v166, 0x4b800000, v165
	v_cmp_gt_f32_e64 s[8:9], s60, v165
	v_mov_b32_e32 v191, v193
	v_pk_add_f32 v[172:173], v[172:173], v[190:191]
	v_cndmask_b32_e64 v165, v165, v166, s[8:9]
	v_mov_b32_e32 v166, v187
	v_mov_b32_e32 v187, v189
	v_pk_add_f32 v[166:167], v[166:167], v[186:187]
	v_mov_b32_e32 v174, v172
	v_mov_b32_e32 v175, v166
	v_mov_b32_e32 v166, v173
	v_pk_add_f32 v[166:167], v[174:175], v[166:167]
	v_mov_b32_e32 v173, v167
	s_nop 1
	v_permlane16_swap_b32_e32 v167, v173
	v_mov_b32_e32 v172, v166
	s_nop 1
	v_permlane16_swap_b32_e32 v166, v172
	v_mul_f32_e32 v132, 0x4b800000, v164
	v_cmp_gt_f32_e64 s[10:11], s60, v164
	v_rsq_f32_e32 v171, v165
	v_rsq_f32_e32 v163, v163
	v_cndmask_b32_e64 v132, v164, v132, s[10:11]
	s_waitcnt lgkmcnt(0)
	v_pk_add_f32 v[164:165], v[166:167], v[172:173]
	v_mov_b32_e32 v167, v165
	s_nop 1
	v_permlane32_swap_b32_e32 v165, v167
	v_mov_b32_e32 v166, v164
	s_nop 1
	v_permlane32_swap_b32_e32 v164, v166
	v_mul_f32_e32 v169, 0x45800000, v163
	v_cndmask_b32_e32 v172, v163, v169, vcc
	v_mul_f32_e32 v156, 0x45800000, v171
	v_rsq_f32_e32 v132, v132
	s_waitcnt lgkmcnt(0)
	v_pk_add_f32 v[164:165], v[164:165], v[166:167]
	v_cndmask_b32_e64 v174, v171, v156, s[8:9]
	v_pk_fma_f32 v[164:165], v[164:165], s[28:29], v[194:195] op_sel_hi:[1,0,0]
	v_mul_f32_e32 v156, 0x45800000, v132
	v_mul_f32_e32 v163, 0x4b800000, v165
	v_cmp_gt_f32_e32 vcc, s60, v165
	v_cmp_gt_f32_e64 s[8:9], s60, v164
	v_pk_mul_f32 v[108:109], v[108:109], v[168:169] op_sel_hi:[1,0]
	v_cndmask_b32_e32 v163, v165, v163, vcc
	v_mul_f32_e32 v165, 0x4b800000, v164
	v_rsq_f32_e32 v163, v163
	v_cndmask_b32_e64 v164, v164, v165, s[8:9]
	v_rsq_f32_e32 v165, v164
	v_cndmask_b32_e64 v164, v132, v156, s[10:11]
	v_mul_f32_e32 v132, 0x45800000, v163
	v_cndmask_b32_e32 v156, v163, v132, vcc
	v_mul_f32_e32 v132, 0x45800000, v165
	v_cndmask_b32_e64 v132, v165, v132, s[8:9]
	s_lshl_b32 s8, s61, 8
	v_lshl_or_b32 v161, v161, 3, s8
	v_or_b32_e32 v166, s56, v161
	v_pk_mul_f32 v[124:125], v[124:125], v[162:163] op_sel_hi:[1,0]
	v_pk_mul_f32 v[120:121], v[120:121], v[162:163] op_sel_hi:[1,0]
	v_ashrrev_i32_e32 v167, 31, v166
	v_pk_mul_f32 v[126:127], v[126:127], v[162:163] op_sel_hi:[1,0]
	v_pk_mul_f32 v[176:177], v[122:123], v[162:163] op_sel_hi:[1,0]
	v_cvt_pk_bf16_f32 v122, v124, v125
	v_cvt_pk_bf16_f32 v124, v120, v121
	v_lshlrev_b64 v[120:121], 11, v[154:155]
	v_cvt_pk_bf16_f32 v123, v126, v127
	v_lshl_add_u64 v[126:127], s[14:15], 0, v[120:121]
	v_lshlrev_b64 v[120:121], 1, v[166:167]
	v_cvt_pk_bf16_f32 v125, v176, v177
	v_lshl_add_u64 v[126:127], v[126:127], 0, v[120:121]
	global_store_dwordx4 v[126:127], v[122:125], off
	v_pk_mul_f32 v[114:115], v[114:115], v[162:163] op_sel_hi:[1,0]
	v_pk_mul_f32 v[112:113], v[112:113], v[162:163] op_sel_hi:[1,0]
	v_pk_mul_f32 v[122:123], v[106:107], v[162:163] op_sel_hi:[1,0]
	v_pk_mul_f32 v[106:107], v[104:105], v[162:163] op_sel_hi:[1,0]
	v_cvt_pk_bf16_f32 v104, v112, v113
	v_cvt_pk_bf16_f32 v105, v114, v115
	v_cvt_pk_bf16_f32 v106, v106, v107
	v_cvt_pk_bf16_f32 v107, v122, v123
	global_store_dwordx4 v[126:127], v[104:107], off offset:256
	v_pk_mul_f32 v[110:111], v[110:111], v[168:169] op_sel_hi:[1,0]
	v_pk_mul_f32 v[98:99], v[98:99], v[168:169] op_sel_hi:[1,0]
	v_pk_mul_f32 v[106:107], v[118:119], v[168:169] op_sel_hi:[1,0]
	v_pk_mul_f32 v[104:105], v[116:117], v[168:169] op_sel_hi:[1,0]
	v_pk_mul_f32 v[96:97], v[96:97], v[168:169] op_sel_hi:[1,0]
	v_cvt_pk_bf16_f32 v104, v104, v105
	v_cvt_pk_bf16_f32 v105, v106, v107
	v_cvt_pk_bf16_f32 v106, v108, v109
	v_lshlrev_b64 v[108:109], 11, v[150:151]
	v_lshl_add_u64 v[108:109], s[14:15], 0, v[108:109]
	v_cvt_pk_bf16_f32 v107, v110, v111
	v_lshl_add_u64 v[108:109], v[108:109], 0, v[120:121]
	global_store_dwordx4 v[108:109], v[104:107], off
	v_pk_mul_f32 v[92:93], v[92:93], v[170:171] op_sel_hi:[1,0]
	v_pk_mul_f32 v[94:95], v[94:95], v[170:171] op_sel_hi:[1,0]
	v_pk_mul_f32 v[104:105], v[90:91], v[168:169] op_sel_hi:[1,0]
	v_pk_mul_f32 v[90:91], v[88:89], v[168:169] op_sel_hi:[1,0]
	v_cvt_pk_bf16_f32 v88, v96, v97
	v_cvt_pk_bf16_f32 v89, v98, v99
	v_cvt_pk_bf16_f32 v90, v90, v91
	v_cvt_pk_bf16_f32 v91, v104, v105
	global_store_dwordx4 v[108:109], v[88:91], off offset:256
	v_pk_mul_f32 v[82:83], v[82:83], v[170:171] op_sel_hi:[1,0]
	v_pk_mul_f32 v[80:81], v[80:81], v[170:171] op_sel_hi:[1,0]
	v_pk_mul_f32 v[90:91], v[102:103], v[170:171] op_sel_hi:[1,0]
	v_pk_mul_f32 v[88:89], v[100:101], v[170:171] op_sel_hi:[1,0]
	v_pk_mul_f32 v[76:77], v[76:77], v[172:173] op_sel_hi:[1,0]
	v_cvt_pk_bf16_f32 v88, v88, v89
	v_cvt_pk_bf16_f32 v89, v90, v91
	v_cvt_pk_bf16_f32 v90, v92, v93
	v_lshlrev_b64 v[92:93], 11, v[152:153]
	v_lshl_add_u64 v[92:93], s[14:15], 0, v[92:93]
	v_cvt_pk_bf16_f32 v91, v94, v95
	v_lshl_add_u64 v[92:93], v[92:93], 0, v[120:121]
	global_store_dwordx4 v[92:93], v[88:91], off
	v_pk_mul_f32 v[78:79], v[78:79], v[172:173] op_sel_hi:[1,0]
	v_pk_mul_f32 v[70:71], v[70:71], v[172:173] op_sel_hi:[1,0]
	v_pk_mul_f32 v[88:89], v[74:75], v[170:171] op_sel_hi:[1,0]
; #define PG8_GAS __attribute__((address_space(1)))
; __device__ __forceinline__ unsigned pk2_(float lo, float hi) { f32x2c_t v = {lo, hi}; bf16x2c_t b = __builtin_convertvector(v, bf16x2c_t); return __builtin_bit_cast(unsigned, b); }
;     __device__ __forceinline__ void operator()(const f32x4 (&acc)[2][2][4][2], const Unit& u, int wr, int wc, int fr, int fq) const {
;     ...
; #pragma unroll
;         for (int ai = 0; ai < 2; ++ai)
; #pragma unroll
;             for (int m = 0; m < 4; ++m) {
;                 const int r = row0 + ai * HALF + m * 16;
;                 const float s = rs8[ai][m];
; #pragma unroll
;                 for (int bj = 0; bj < 2; ++bj) {
;                     f32x4 v0 = acc[ai][bj][m][0], v1 = acc[ai][bj][m][1];
;                     if (MODE == 2) { v0 = v0 * cs[bj][0]; v1 = v1 * cs[bj][1]; } else { v0 = v0 * s; v1 = v1 * s; }
;                     u32x4 w; w.x = pk2_(v0[0], v0[1]); w.y = pk2_(v0[2], v0[3]); w.z = pk2_(v1[0], v1[1]); w.w = pk2_(v1[2], v1[3]);
;                     *(PG8_GAS u32x4*)(O + (size_t)r * ldc + col0 + bj * HALF) = w;
;                 }
	v_pk_mul_f32 v[74:75], v[72:73], v[170:171] op_sel_hi:[1,0]
	v_cvt_pk_bf16_f32 v72, v80, v81
	v_cvt_pk_bf16_f32 v73, v82, v83
	v_cvt_pk_bf16_f32 v74, v74, v75
	v_cvt_pk_bf16_f32 v75, v88, v89
	global_store_dwordx4 v[92:93], v[72:75], off offset:256
	v_pk_mul_f32 v[68:69], v[68:69], v[172:173] op_sel_hi:[1,0]
	v_pk_mul_f32 v[60:61], v[60:61], v[174:175] op_sel_hi:[1,0]
	v_pk_mul_f32 v[74:75], v[86:87], v[172:173] op_sel_hi:[1,0]
	v_pk_mul_f32 v[72:73], v[84:85], v[172:173] op_sel_hi:[1,0]
	v_pk_mul_f32 v[62:63], v[62:63], v[174:175] op_sel_hi:[1,0]
	v_cvt_pk_bf16_f32 v72, v72, v73
	v_cvt_pk_bf16_f32 v73, v74, v75
	v_cvt_pk_bf16_f32 v74, v76, v77
	v_lshlrev_b64 v[76:77], 11, v[146:147]
	v_lshl_add_u64 v[76:77], s[14:15], 0, v[76:77]
	v_cvt_pk_bf16_f32 v75, v78, v79
	v_lshl_add_u64 v[76:77], v[76:77], 0, v[120:121]
	global_store_dwordx4 v[76:77], v[72:75], off
	v_pk_mul_f32 v[50:51], v[50:51], v[174:175] op_sel_hi:[1,0]
	v_pk_mul_f32 v[48:49], v[48:49], v[174:175] op_sel_hi:[1,0]
	v_pk_mul_f32 v[72:73], v[66:67], v[172:173] op_sel_hi:[1,0]
	v_pk_mul_f32 v[66:67], v[64:65], v[172:173] op_sel_hi:[1,0]
	v_cvt_pk_bf16_f32 v64, v68, v69
	v_cvt_pk_bf16_f32 v65, v70, v71
	v_cvt_pk_bf16_f32 v66, v66, v67
	v_cvt_pk_bf16_f32 v67, v72, v73
	global_store_dwordx4 v[76:77], v[64:67], off offset:256
	v_pk_mul_f32 v[44:45], v[44:45], v[164:165] op_sel_hi:[1,0]
	v_pk_mul_f32 v[46:47], v[46:47], v[164:165] op_sel_hi:[1,0]
	v_pk_mul_f32 v[64:65], v[58:59], v[174:175] op_sel_hi:[1,0]
	v_pk_mul_f32 v[58:59], v[56:57], v[174:175] op_sel_hi:[1,0]
	v_cvt_pk_bf16_f32 v56, v60, v61
	v_lshlrev_b64 v[60:61], 11, v[148:149]
	v_lshl_add_u64 v[60:61], s[14:15], 0, v[60:61]
	v_cvt_pk_bf16_f32 v57, v62, v63
	v_cvt_pk_bf16_f32 v58, v58, v59
	v_cvt_pk_bf16_f32 v59, v64, v65
	v_lshl_add_u64 v[60:61], v[60:61], 0, v[120:121]
	global_store_dwordx4 v[60:61], v[56:59], off
	v_pk_mul_f32 v[34:35], v[34:35], v[164:165] op_sel_hi:[1,0]
	v_pk_mul_f32 v[32:33], v[32:33], v[164:165] op_sel_hi:[1,0]
	v_pk_mul_f32 v[56:57], v[42:43], v[174:175] op_sel_hi:[1,0]
	v_pk_mul_f32 v[42:43], v[40:41], v[174:175] op_sel_hi:[1,0]
	v_cvt_pk_bf16_f32 v40, v48, v49
	v_cvt_pk_bf16_f32 v41, v50, v51
	v_cvt_pk_bf16_f32 v42, v42, v43
	v_cvt_pk_bf16_f32 v43, v56, v57
	global_store_dwordx4 v[60:61], v[40:43], off offset:256
	v_pk_mul_f32 v[28:29], v[28:29], v[156:157] op_sel_hi:[1,0]
	v_pk_mul_f32 v[30:31], v[30:31], v[156:157] op_sel_hi:[1,0]
	v_pk_mul_f32 v[42:43], v[54:55], v[164:165] op_sel_hi:[1,0]
	v_pk_mul_f32 v[40:41], v[52:53], v[164:165] op_sel_hi:[1,0]
	v_pk_mul_f32 v[18:19], v[18:19], v[156:157] op_sel_hi:[1,0]
	v_cvt_pk_bf16_f32 v40, v40, v41
	v_cvt_pk_bf16_f32 v41, v42, v43
	v_cvt_pk_bf16_f32 v42, v44, v45
	v_lshlrev_b64 v[44:45], 11, v[142:143]
	v_lshl_add_u64 v[44:45], s[14:15], 0, v[44:45]
	v_cvt_pk_bf16_f32 v43, v46, v47
	v_lshl_add_u64 v[44:45], v[44:45], 0, v[120:121]
	global_store_dwordx4 v[44:45], v[40:43], off
	v_pk_mul_f32 v[16:17], v[16:17], v[156:157] op_sel_hi:[1,0]
	v_pk_mul_f32 v[12:13], v[12:13], v[132:133] op_sel_hi:[1,0]
	v_pk_mul_f32 v[40:41], v[26:27], v[164:165] op_sel_hi:[1,0]
	v_pk_mul_f32 v[26:27], v[24:25], v[164:165] op_sel_hi:[1,0]
	v_cvt_pk_bf16_f32 v24, v32, v33
	v_cvt_pk_bf16_f32 v25, v34, v35
	v_cvt_pk_bf16_f32 v26, v26, v27
	v_cvt_pk_bf16_f32 v27, v40, v41
	global_store_dwordx4 v[44:45], v[24:27], off offset:256
	v_pk_mul_f32 v[14:15], v[14:15], v[132:133] op_sel_hi:[1,0]
	v_pk_mul_f32 v[6:7], v[6:7], v[132:133] op_sel_hi:[1,0]
	v_pk_mul_f32 v[26:27], v[38:39], v[156:157] op_sel_hi:[1,0]
	v_pk_mul_f32 v[24:25], v[36:37], v[156:157] op_sel_hi:[1,0]
	v_pk_mul_f32 v[4:5], v[4:5], v[132:133] op_sel_hi:[1,0]
	v_cvt_pk_bf16_f32 v24, v24, v25
	v_cvt_pk_bf16_f32 v25, v26, v27
	v_cvt_pk_bf16_f32 v26, v28, v29
	v_lshlrev_b64 v[28:29], 11, v[144:145]
	v_lshl_add_u64 v[28:29], s[14:15], 0, v[28:29]
	v_cvt_pk_bf16_f32 v27, v30, v31
	v_lshl_add_u64 v[28:29], v[28:29], 0, v[120:121]
	global_store_dwordx4 v[28:29], v[24:27], off
	s_andn2_b64 vcc, exec, s[6:7]
	s_mov_b64 s[6:7], -1
	v_pk_mul_f32 v[24:25], v[10:11], v[156:157] op_sel_hi:[1,0]
	v_pk_mul_f32 v[10:11], v[8:9], v[156:157] op_sel_hi:[1,0]
	v_cvt_pk_bf16_f32 v8, v16, v17
	v_cvt_pk_bf16_f32 v9, v18, v19
	v_cvt_pk_bf16_f32 v10, v10, v11
	v_cvt_pk_bf16_f32 v11, v24, v25
	global_store_dwordx4 v[28:29], v[8:11], off offset:256
	s_nop 1
	v_pk_mul_f32 v[10:11], v[22:23], v[132:133] op_sel_hi:[1,0]
	v_pk_mul_f32 v[8:9], v[20:21], v[132:133] op_sel_hi:[1,0]
	s_nop 0
	v_cvt_pk_bf16_f32 v8, v8, v9
	v_cvt_pk_bf16_f32 v9, v10, v11
	v_cvt_pk_bf16_f32 v10, v12, v13
	v_lshlrev_b64 v[12:13], 11, v[140:141]
	v_lshl_add_u64 v[12:13], s[14:15], 0, v[12:13]
	v_cvt_pk_bf16_f32 v11, v14, v15
	v_lshl_add_u64 v[12:13], v[12:13], 0, v[120:121]
	global_store_dwordx4 v[12:13], v[8:11], off
	s_nop 1
	v_pk_mul_f32 v[8:9], v[2:3], v[132:133] op_sel_hi:[1,0]
	v_pk_mul_f32 v[2:3], v[0:1], v[132:133] op_sel_hi:[1,0]
	v_cvt_pk_bf16_f32 v0, v4, v5
	v_cvt_pk_bf16_f32 v1, v6, v7
	v_cvt_pk_bf16_f32 v2, v2, v3
	v_cvt_pk_bf16_f32 v3, v8, v9
	global_store_dwordx4 v[12:13], v[0:3], off offset:256
	s_cbranch_vccnz .LBB0_1451
	s_andn2_b64 vcc, exec, s[12:13]
	s_cbranch_vccnz .LBB0_1450
	s_barrier
	s_branch .LBB0_1450

; __device__ __forceinline__ void xattn_unit(const Args& a, LAS unsigned char* lds, int b, int h, int qb, int tid, int wave, int lane) {
;     ...
;     const int fr = lane & 15, fq = lane >> 4; const size_t qrow = (size_t)b * SEQ + qb * 128 + 16 * wave + fr;
;     bf16x8 qf[8];
; #pragma unroll
;     for (int kk = 0; kk < 8; ++kk) qf[kk] = *(const GAS bf16x8*)(QX + qrow * DM + h * 256 + 32 * kk + 8 * fq);
;     u32x4 rr[2][4];
;     const unsigned vok = (unsigned)((tid >> 5) * DM + 8 * (tid & 31)) * 2u, vov = (unsigned)((tid >> 3) * MEMR + 8 * (tid & 7)) * 2u;
;     const GAS char* kxb = (const GAS char*)KX + ((size_t)b * 256 * DM + h * 256) * 2; const GAS char* vxb = (const GAS char*)VTX + ((size_t)h * 256 * MEMR + b * 256) * 2;
;     auto gload = [&](int j) {
;         if (j < 4) { const GAS char* p_ = kxb + (size_t)j * (64 * DM * 2);
; #pragma unroll
;             for (int i = 0; i < 4; ++i) rr[j & 1][i] = *(const GAS u32x4*)(p_ + (size_t)(vok + (unsigned)(i * 16 * DM * 2)));
;         } else { const GAS char* p_ = vxb + (size_t)(j - 4) * 128;
; #pragma unroll
;             for (int i = 0; i < 4; ++i) rr[j & 1][i] = *(const GAS u32x4*)(p_ + (size_t)(vov + (unsigned)(i * 64 * MEMR * 2)));
;         }
;     };
;     auto lstore = [&](int j) {
;         LAS bf16* base = (LAS bf16*)(lds + (j & 1) * STG);
;         if (j < 4) {
; #pragma unroll
;             for (int i = 0; i < 4; ++i) { const int id = tid + 512 * i; *(LAS u32x4*)(base + (id >> 5) * KS + 8 * (id & 31)) = rr[j & 1][i]; }
;         } else {
; #pragma unroll
;             for (int i = 0; i < 4; ++i) { const int id = tid + 512 * i; *(LAS u32x4*)(base + (id >> 3) * VS + 8 * (id & 7)) = rr[j & 1][i]; }
;         }
;     };
;     f32x4 S[16]; bf16x8 pf[8]; f32x4 O[16]; float l = 0.f;
; #pragma unroll
;     for (int i = 0; i < 16; ++i) { S[i] = (f32x4){0.f, 0.f, 0.f, 0.f}; O[i] = (f32x4){0.f, 0.f, 0.f, 0.f}; }
;     gload(0); gload(1); lstore(0); __syncthreads();
; #pragma unroll
;     for (int j = 0; j < 8; ++j) {
;         if (j < 6) gload(j + 2);
;         const LAS bf16* base = (const LAS bf16*)(lds + (j & 1) * STG);
;         if (j < 4) {
; #pragma unroll
;             for (int rt = 0; rt < 4; ++rt)
; #pragma unroll
;                 for (int kk = 0; kk < 8; ++kk) S[4 * j + rt] = mfma16(*(const LAS bf16x8*)(base + (16 * rt + fr) * KS + 32 * kk + 8 * fq), qf[kk], S[4 * j + rt]);
.LBB0_1513:
	s_bfe_u32 s6, s21, 0x40006
	s_and_b32 s4, s14, 0x780
	v_mov_b32_e32 v216, v252
	s_bfe_u32 s7, s21, 0x20004
	s_lshl_b32 s8, s6, 11
	s_add_i32 s9, s4, s70
	s_lshl_b32 s4, s7, 9
	s_lshl_b32 s22, s6, 19
	v_and_b32_e32 v213, 15, v216
	s_add_i32 s8, s8, s9
	v_or_b32_e32 v200, s8, v213
	s_add_u32 s8, s10, s22
	s_addc_u32 s9, s11, 0
	s_lshl_b32 s7, s7, 21
	s_lshl_b32 s6, s6, 9
	s_or_b32 s6, s7, s6
	s_add_u32 s8, s8, s4
	v_lshlrev_b32_e32 v192, 4, v216
	v_ashrrev_i32_e32 v3, 5, v216
	s_addc_u32 s9, s9, 0
	v_lshlrev_b32_e32 v2, 6, v216
	v_and_b32_e32 v4, 0x1f0, v192
	v_mul_lo_u32 v3, v3, s18
	v_lshlrev_b64 v[202:203], 11, v[200:201]
	s_add_u32 s6, s12, s6
	v_add_u32_e32 v217, 0x200, v216
	v_add_u32_e32 v218, 0x400, v216
	v_add_u32_e32 v219, 0x600, v216
	v_and_or_b32 v193, v2, s16, v4
	v_add3_u32 v200, 0, v3, v4
	v_lshl_add_u64 v[2:3], s[0:1], 0, v[202:203]
	s_addc_u32 s7, s13, 0
	v_mov_b32_e32 v1, v201
	v_and_b32_e32 v215, 63, v216
	v_and_b32_e32 v0, 48, v216
	v_ashrrev_i32_e32 v5, 5, v217
	v_ashrrev_i32_e32 v6, 5, v218
	v_ashrrev_i32_e32 v7, 5, v219
	v_lshl_add_u64 v[2:3], v[2:3], 0, s[4:5]
	s_add_u32 s22, s8, 0x20000
	v_add_u32_e32 v8, 0, v0
	v_or_b32_e32 v214, 48, v215
	v_mul_lo_u32 v5, v5, s18
	v_mul_lo_u32 v6, v6, s18
	v_mul_lo_u32 v7, v7, s18
	v_lshl_add_u64 v[32:33], v[2:3], 0, v[0:1]
	s_addc_u32 s23, s9, 0
	v_mad_u32_u24 v210, v213, s18, v8
	v_mad_u32_u24 v209, v214, s18, v8
	v_add_u32_e32 v194, 0x8000, v193
	v_add_u32_e32 v195, 0x10000, v193
	v_add_u32_e32 v196, 0x18000, v193
	v_add3_u32 v211, 0, v5, v4
	v_add3_u32 v212, 0, v6, v4
	v_add3_u32 v221, 0, v7, v4
	global_load_dwordx4 v[12:15], v193, s[8:9]
	global_load_dwordx4 v[16:19], v194, s[8:9]
	global_load_dwordx4 v[20:23], v195, s[8:9]
	global_load_dwordx4 v[24:27], v196, s[8:9]
	global_load_dwordx4 v[140:143], v[32:33], off
	global_load_dwordx4 v[156:159], v[32:33], off offset:64
	global_load_dwordx4 v[68:71], v[32:33], off offset:128
	global_load_dwordx4 v[64:67], v[32:33], off offset:192
	global_load_dwordx4 v[28:31], v[32:33], off offset:256
	global_load_dwordx4 v[8:11], v[32:33], off offset:320
	global_load_dwordx4 v[4:7], v[32:33], off offset:384
	global_load_dwordx4 v[0:3], v[32:33], off offset:448
	s_nop 0
	global_load_dwordx4 v[32:35], v193, s[22:23]
	global_load_dwordx4 v[36:39], v194, s[22:23]
	global_load_dwordx4 v[40:43], v195, s[22:23]
	global_load_dwordx4 v[44:47], v196, s[22:23]
	s_add_u32 s22, s8, 0x40000
	s_addc_u32 s23, s9, 0
	s_add_u32 s8, s8, 0x60000
	s_addc_u32 s9, s9, 0
	v_and_b32_e32 v220, 0x70, v192
	v_cmp_lt_i32_e32 vcc, v227, v226
	v_lshrrev_b32_e32 v217, 3, v217
	v_lshrrev_b32_e32 v218, 3, v218
	s_add_i32 s21, s21, s76
	s_add_i32 s14, s14, s15
	s_cmpk_lt_i32 s21, 0x400
	s_waitcnt vmcnt(0)
	ds_write_b128 v200, v[12:15]
	ds_write_b128 v211, v[16:19]
	ds_write_b128 v212, v[20:23]
	ds_write_b128 v221, v[24:27]
	s_waitcnt lgkmcnt(0)
	s_barrier
	global_load_dwordx4 v[12:15], v193, s[22:23]
	global_load_dwordx4 v[16:19], v194, s[22:23]
	global_load_dwordx4 v[20:23], v195, s[22:23]
	global_load_dwordx4 v[24:27], v196, s[22:23]
	ds_read_b128 v[48:51], v210
	ds_read_b128 v[52:55], v210 offset:64
	ds_read_b128 v[56:59], v210 offset:128
	ds_read_b128 v[60:63], v210 offset:192
	ds_read_b128 v[72:75], v210 offset:256
	ds_read_b128 v[76:79], v210 offset:320
	ds_read_b128 v[80:83], v210 offset:384
	ds_read_b128 v[84:87], v210 offset:448
	ds_read_b128 v[88:91], v210 offset:8448
	ds_read_b128 v[92:95], v210 offset:8512
	ds_read_b128 v[96:99], v210 offset:8576
	ds_read_b128 v[100:103], v210 offset:8640
	ds_read_b128 v[104:107], v210 offset:8704
	ds_read_b128 v[108:111], v210 offset:8768
	ds_read_b128 v[112:115], v210 offset:8832
	ds_read_b128 v[116:119], v210 offset:8896
	ds_read_b128 v[120:123], v210 offset:16896
	ds_read_b128 v[124:127], v210 offset:16960
	s_waitcnt lgkmcnt(14)
	v_mfma_f32_16x16x32_bf16 v[48:51], v[48:51], v[140:143], 0
	ds_read_b128 v[128:131], v210 offset:17024
	ds_read_b128 v[132:135], v210 offset:17088
	ds_read_b128 v[136:139], v209
	ds_read_b128 v[144:147], v210 offset:17152
	ds_read_b128 v[148:151], v210 offset:17216
	ds_read_b128 v[152:155], v210 offset:17280
	ds_read_b128 v[160:163], v210 offset:17344
	ds_read_b128 v[164:167], v209 offset:64
	ds_read_b128 v[168:171], v209 offset:128
	s_waitcnt lgkmcnt(14)
	v_mfma_f32_16x16x32_bf16 v[88:91], v[88:91], v[140:143], 0
	ds_read_b128 v[172:175], v209 offset:192
	ds_read_b128 v[176:179], v209 offset:256
	ds_read_b128 v[180:183], v209 offset:320
	s_waitcnt lgkmcnt(13)
	v_mfma_f32_16x16x32_bf16 v[120:123], v[120:123], v[140:143], 0
	v_mfma_f32_16x16x32_bf16 v[48:51], v[52:55], v[156:159], v[48:51]
	ds_read_b128 v[52:55], v209 offset:384
	ds_read_b128 v[184:187], v209 offset:448
	ds_write_b128 v200, v[32:35] offset:36864
	ds_write_b128 v211, v[36:39] offset:36864
	ds_write_b128 v212, v[40:43] offset:36864
	ds_write_b128 v221, v[44:47] offset:36864
	v_mfma_f32_16x16x32_bf16 v[32:35], v[92:95], v[156:159], v[88:91]
	s_waitcnt lgkmcnt(0)
	s_barrier
; #define LAS __attribute__((address_space(3)))
; #define GAS __attribute__((address_space(1)))
; __device__ __forceinline__ f32x4 mfma16(bf16x8 a, bf16x8 b, f32x4 c) { return __builtin_amdgcn_mfma_f32_16x16x32_bf16(a, b, c, 0, 0, 0); }
; __device__ __forceinline__ void xattn_unit(const Args& a, LAS unsigned char* lds, int b, int h, int qb, int tid, int wave, int lane) {
;     ...
;     auto gload = [&](int j) {
;         if (j < 4) { const GAS char* p_ = kxb + (size_t)j * (64 * DM * 2);
; #pragma unroll
;             for (int i = 0; i < 4; ++i) rr[j & 1][i] = *(const GAS u32x4*)(p_ + (size_t)(vok + (unsigned)(i * 16 * DM * 2)));
;         } else { const GAS char* p_ = vxb + (size_t)(j - 4) * 128;
; #pragma unroll
;             for (int i = 0; i < 4; ++i) rr[j & 1][i] = *(const GAS u32x4*)(p_ + (size_t)(vov + (unsigned)(i * 64 * MEMR * 2)));
;         }
;     };
;     auto lstore = [&](int j) {
;         LAS bf16* base = (LAS bf16*)(lds + (j & 1) * STG);
;         if (j < 4) {
; #pragma unroll
;             for (int i = 0; i < 4; ++i) { const int id = tid + 512 * i; *(LAS u32x4*)(base + (id >> 5) * KS + 8 * (id & 31)) = rr[j & 1][i]; }
;         } else {
; #pragma unroll
;             for (int i = 0; i < 4; ++i) { const int id = tid + 512 * i; *(LAS u32x4*)(base + (id >> 3) * VS + 8 * (id & 7)) = rr[j & 1][i]; }
;         }
;     };
;     f32x4 S[16]; bf16x8 pf[8]; f32x4 O[16]; float l = 0.f;
; #pragma unroll
;     for (int i = 0; i < 16; ++i) { S[i] = (f32x4){0.f, 0.f, 0.f, 0.f}; O[i] = (f32x4){0.f, 0.f, 0.f, 0.f}; }
;     gload(0); gload(1); lstore(0); __syncthreads();
; #pragma unroll
;     for (int j = 0; j < 8; ++j) {
;         if (j < 6) gload(j + 2);
;         const LAS bf16* base = (const LAS bf16*)(lds + (j & 1) * STG);
;         if (j < 4) {
; #pragma unroll
;             for (int rt = 0; rt < 4; ++rt)
; #pragma unroll
;                 for (int kk = 0; kk < 8; ++kk) S[4 * j + rt] = mfma16(*(const LAS bf16x8*)(base + (16 * rt + fr) * KS + 32 * kk + 8 * fq), qf[kk], S[4 * j + rt]);
	ds_read_b128 v[44:47], v210 offset:36864
	ds_read_b128 v[88:91], v210 offset:36928
	v_mfma_f32_16x16x32_bf16 v[136:139], v[136:139], v[140:143], 0
	v_mfma_f32_16x16x32_bf16 v[36:39], v[124:127], v[156:159], v[120:123]
	ds_read_b128 v[92:95], v210 offset:45312
	s_nop 1
	ds_read_b128 v[120:123], v210 offset:45376
	s_waitcnt lgkmcnt(3)
	v_mfma_f32_16x16x32_bf16 v[44:47], v[44:47], v[140:143], 0
	v_mfma_f32_16x16x32_bf16 v[48:51], v[56:59], v[68:71], v[48:51]
	v_mfma_f32_16x16x32_bf16 v[40:43], v[164:167], v[156:159], v[136:139]
	ds_read_b128 v[124:127], v210 offset:53760
	s_nop 1
	ds_read_b128 v[136:139], v210 offset:53824
	ds_read_b128 v[164:167], v209 offset:36864
	ds_read_b128 v[188:191], v209 offset:36928
	s_waitcnt lgkmcnt(5)
	v_mfma_f32_16x16x32_bf16 v[92:95], v[92:95], v[140:143], 0
	v_mfma_f32_16x16x32_bf16 v[32:35], v[96:99], v[68:71], v[32:35]
	v_mfma_f32_16x16x32_bf16 v[44:47], v[88:91], v[156:159], v[44:47]
	v_mfma_f32_16x16x32_bf16 v[48:51], v[60:63], v[64:67], v[48:51]
	ds_read_b128 v[60:63], v210 offset:36992
	ds_read_b128 v[96:99], v210 offset:37056
	s_waitcnt lgkmcnt(5)
	v_mfma_f32_16x16x32_bf16 v[124:127], v[124:127], v[140:143], 0
	v_mfma_f32_16x16x32_bf16 v[56:59], v[120:123], v[156:159], v[92:95]
	v_mfma_f32_16x16x32_bf16 v[32:35], v[100:103], v[64:67], v[32:35]
	s_waitcnt lgkmcnt(1)
	v_mfma_f32_16x16x32_bf16 v[44:47], v[60:63], v[68:71], v[44:47]
	ds_read_b128 v[60:63], v210 offset:45440
	ds_read_b128 v[100:103], v210 offset:45504
	v_mfma_f32_16x16x32_bf16 v[164:167], v[164:167], v[140:143], 0
	v_mfma_f32_16x16x32_bf16 v[88:91], v[136:139], v[156:159], v[124:127]
	s_waitcnt lgkmcnt(1)
	v_mfma_f32_16x16x32_bf16 v[56:59], v[60:63], v[68:71], v[56:59]
	ds_read_b128 v[60:63], v210 offset:53888
	ds_read_b128 v[120:123], v210 offset:53952
	v_mfma_f32_16x16x32_bf16 v[92:95], v[188:191], v[156:159], v[164:167]
	s_waitcnt lgkmcnt(1)
	v_mfma_f32_16x16x32_bf16 v[60:63], v[60:63], v[68:71], v[88:91]
	s_nop 2
	ds_read_b128 v[88:91], v209 offset:36992
	ds_read_b128 v[124:127], v209 offset:37056
	v_mfma_f32_16x16x32_bf16 v[40:43], v[168:171], v[68:71], v[40:43]
	s_waitcnt lgkmcnt(1)
	v_mfma_f32_16x16x32_bf16 v[88:91], v[88:91], v[68:71], v[92:95]
	v_mfma_f32_16x16x32_bf16 v[48:51], v[72:75], v[28:31], v[48:51]
	v_mfma_f32_16x16x32_bf16 v[40:43], v[172:175], v[64:67], v[40:43]
	v_mfma_f32_16x16x32_bf16 v[44:47], v[96:99], v[64:67], v[44:47]
	s_waitcnt lgkmcnt(0)
	v_mfma_f32_16x16x32_bf16 v[72:75], v[124:127], v[64:67], v[88:91]
	v_mfma_f32_16x16x32_bf16 v[48:51], v[76:79], v[8:11], v[48:51]
	ds_read_b128 v[76:79], v210 offset:37120
	s_nop 0
	ds_read_b128 v[88:91], v210 offset:37184
	v_mfma_f32_16x16x32_bf16 v[32:35], v[104:107], v[28:31], v[32:35]
	v_mfma_f32_16x16x32_bf16 v[40:43], v[176:179], v[28:31], v[40:43]
	v_mfma_f32_16x16x32_bf16 v[56:59], v[100:103], v[64:67], v[56:59]
	s_waitcnt lgkmcnt(1)
	v_mfma_f32_16x16x32_bf16 v[44:47], v[76:79], v[28:31], v[44:47]
	ds_read_b128 v[76:79], v210 offset:45568
	ds_read_b128 v[92:95], v210 offset:45632
	v_mfma_f32_16x16x32_bf16 v[60:63], v[120:123], v[64:67], v[60:63]
	v_mfma_f32_16x16x32_bf16 v[32:35], v[108:111], v[8:11], v[32:35]
	v_mfma_f32_16x16x32_bf16 v[40:43], v[180:183], v[8:11], v[40:43]
	s_waitcnt lgkmcnt(1)
	v_mfma_f32_16x16x32_bf16 v[56:59], v[76:79], v[28:31], v[56:59]
	ds_read_b128 v[76:79], v210 offset:54016
	ds_read_b128 v[96:99], v210 offset:54080
	v_mfma_f32_16x16x32_bf16 v[36:39], v[128:131], v[68:71], v[36:39]
	s_waitcnt lgkmcnt(1)
	v_mfma_f32_16x16x32_bf16 v[60:63], v[76:79], v[28:31], v[60:63]
	ds_read_b128 v[76:79], v209 offset:37120
	ds_read_b128 v[100:103], v209 offset:37184
	v_mfma_f32_16x16x32_bf16 v[48:51], v[80:83], v[4:7], v[48:51]
	v_mfma_f32_16x16x32_bf16 v[32:35], v[112:115], v[4:7], v[32:35]
	v_mfma_f32_16x16x32_bf16 v[52:55], v[52:55], v[4:7], v[40:43]
	v_mfma_f32_16x16x32_bf16 v[36:39], v[132:135], v[64:67], v[36:39]
	s_waitcnt lgkmcnt(1)
	v_mfma_f32_16x16x32_bf16 v[72:75], v[76:79], v[28:31], v[72:75]
	v_mfma_f32_16x16x32_bf16 v[76:79], v[88:91], v[8:11], v[44:47]
	v_mfma_f32_16x16x32_bf16 v[44:47], v[84:87], v[0:3], v[48:51]
	v_mfma_f32_16x16x32_bf16 v[40:43], v[116:119], v[0:3], v[32:35]
	v_mfma_f32_16x16x32_bf16 v[32:35], v[184:187], v[0:3], v[52:55]
	s_nop 0
	ds_read_b128 v[48:51], v210 offset:37248
	s_nop 0
	ds_read_b128 v[52:55], v210 offset:37312
	v_mfma_f32_16x16x32_bf16 v[36:39], v[144:147], v[28:31], v[36:39]
	v_mfma_f32_16x16x32_bf16 v[56:59], v[92:95], v[8:11], v[56:59]
	v_lshlrev_b32_e32 v92, 10, v216
	v_and_or_b32 v205, v92, s17, v220
	v_add_u32_e32 v206, 0x80000, v205
	s_waitcnt lgkmcnt(1)
	v_mfma_f32_16x16x32_bf16 v[48:51], v[48:51], v[4:7], v[76:79]
	s_nop 2
	ds_read_b128 v[76:79], v210 offset:45696
	ds_read_b128 v[80:83], v210 offset:45760
	v_add_u32_e32 v207, 0x100000, v205
	v_add_u32_e32 v208, 0x180000, v205
	v_mfma_f32_16x16x32_bf16 v[36:39], v[148:151], v[8:11], v[36:39]
	v_mfma_f32_16x16x32_bf16 v[60:63], v[96:99], v[8:11], v[60:63]
	s_waitcnt lgkmcnt(1)
	v_mfma_f32_16x16x32_bf16 v[56:59], v[76:79], v[4:7], v[56:59]
	ds_read_b128 v[76:79], v210 offset:54144
	ds_read_b128 v[84:87], v210 offset:54208
	v_mfma_f32_16x16x32_bf16 v[36:39], v[152:155], v[4:7], v[36:39]
	s_waitcnt lgkmcnt(1)
	v_mfma_f32_16x16x32_bf16 v[60:63], v[76:79], v[4:7], v[60:63]
	ds_read_b128 v[76:79], v209 offset:37248
	ds_read_b128 v[88:91], v209 offset:37312
	global_load_dwordx4 v[144:147], v193, s[8:9]
	global_load_dwordx4 v[148:151], v194, s[8:9]
	global_load_dwordx4 v[152:155], v195, s[8:9]
	global_load_dwordx4 v[172:175], v196, s[8:9]
	v_mfma_f32_16x16x32_bf16 v[72:75], v[100:103], v[8:11], v[72:75]
	s_waitcnt vmcnt(7)
	ds_write_b128 v200, v[12:15]
	s_waitcnt vmcnt(6)
	ds_write_b128 v211, v[16:19]
	s_waitcnt vmcnt(5)
	ds_write_b128 v212, v[20:23]
	s_waitcnt vmcnt(4)
	ds_write_b128 v221, v[24:27]
	s_waitcnt lgkmcnt(0)
	s_barrier
; #define LAS __attribute__((address_space(3)))
; #define GAS __attribute__((address_space(1)))
; __device__ __forceinline__ f32x4 mfma16(bf16x8 a, bf16x8 b, f32x4 c) { return __builtin_amdgcn_mfma_f32_16x16x32_bf16(a, b, c, 0, 0, 0); }
; __device__ __forceinline__ void xattn_unit(const Args& a, LAS unsigned char* lds, int b, int h, int qb, int tid, int wave, int lane) {
;     ...
;     auto gload = [&](int j) {
;         if (j < 4) { const GAS char* p_ = kxb + (size_t)j * (64 * DM * 2);
; #pragma unroll
;             for (int i = 0; i < 4; ++i) rr[j & 1][i] = *(const GAS u32x4*)(p_ + (size_t)(vok + (unsigned)(i * 16 * DM * 2)));
;         } else { const GAS char* p_ = vxb + (size_t)(j - 4) * 128;
; #pragma unroll
;             for (int i = 0; i < 4; ++i) rr[j & 1][i] = *(const GAS u32x4*)(p_ + (size_t)(vov + (unsigned)(i * 64 * MEMR * 2)));
;         }
;     };
;     auto lstore = [&](int j) {
;         LAS bf16* base = (LAS bf16*)(lds + (j & 1) * STG);
;         if (j < 4) {
; #pragma unroll
;             for (int i = 0; i < 4; ++i) { const int id = tid + 512 * i; *(LAS u32x4*)(base + (id >> 5) * KS + 8 * (id & 31)) = rr[j & 1][i]; }
;         } else {
; #pragma unroll
;             for (int i = 0; i < 4; ++i) { const int id = tid + 512 * i; *(LAS u32x4*)(base + (id >> 3) * VS + 8 * (id & 7)) = rr[j & 1][i]; }
;         }
;     };
;     f32x4 S[16]; bf16x8 pf[8]; f32x4 O[16]; float l = 0.f;
; #pragma unroll
;     for (int i = 0; i < 16; ++i) { S[i] = (f32x4){0.f, 0.f, 0.f, 0.f}; O[i] = (f32x4){0.f, 0.f, 0.f, 0.f}; }
;     gload(0); gload(1); lstore(0); __syncthreads();
; #pragma unroll
;     for (int j = 0; j < 8; ++j) {
;         if (j < 6) gload(j + 2);
;         const LAS bf16* base = (const LAS bf16*)(lds + (j & 1) * STG);
;         if (j < 4) {
; #pragma unroll
;             for (int rt = 0; rt < 4; ++rt)
; #pragma unroll
;                 for (int kk = 0; kk < 8; ++kk) S[4 * j + rt] = mfma16(*(const LAS bf16x8*)(base + (16 * rt + fr) * KS + 32 * kk + 8 * fq), qf[kk], S[4 * j + rt]);
;             if (j == 3) {
;                 float mx = -3.0e38f;
; #pragma unroll
;                 for (int i = 0; i < 16; ++i) mx = fmaxf(mx, fmaxf(fmaxf(S[i][0], S[i][1]), fmaxf(S[i][2], S[i][3])));
	v_mfma_f32_16x16x32_bf16 v[72:75], v[76:79], v[4:7], v[72:75]
	global_load_dwordx4 v[12:15], v205, s[6:7]
	global_load_dwordx4 v[16:19], v206, s[6:7]
	global_load_dwordx4 v[20:23], v207, s[6:7]
	global_load_dwordx4 v[24:27], v208, s[6:7]
	v_mfma_f32_16x16x32_bf16 v[36:39], v[160:163], v[0:3], v[36:39]
	v_mfma_f32_16x16x32_bf16 v[52:55], v[52:55], v[0:3], v[48:51]
	v_mfma_f32_16x16x32_bf16 v[56:59], v[80:83], v[0:3], v[56:59]
	v_mfma_f32_16x16x32_bf16 v[60:63], v[84:87], v[0:3], v[60:63]
	v_mfma_f32_16x16x32_bf16 v[48:51], v[88:91], v[0:3], v[72:75]
	ds_read_b128 v[84:87], v210
	ds_read_b128 v[92:95], v210 offset:64
	ds_read_b128 v[176:179], v210 offset:128
	ds_read_b128 v[160:163], v210 offset:192
	ds_read_b128 v[116:119], v210 offset:256
	ds_read_b128 v[108:111], v210 offset:320
	ds_read_b128 v[80:83], v210 offset:384
	ds_read_b128 v[72:75], v210 offset:448
	ds_read_b128 v[96:99], v210 offset:8448
	ds_read_b128 v[180:183], v210 offset:8512
	ds_read_b128 v[228:231], v210 offset:8576
	ds_read_b128 v[164:167], v210 offset:8640
	ds_read_b128 v[124:127], v210 offset:8704
	ds_read_b128 v[112:115], v210 offset:8768
	ds_read_b128 v[88:91], v210 offset:8832
	ds_read_b128 v[76:79], v210 offset:8896
	ds_read_b128 v[100:103], v210 offset:16896
	ds_read_b128 v[184:187], v210 offset:16960
	ds_read_b128 v[232:235], v210 offset:17024
	ds_read_b128 v[168:171], v210 offset:17088
	ds_read_b128 v[104:107], v209
	s_waitcnt lgkmcnt(14)
	v_mfma_f32_16x16x32_bf16 v[188:191], v[84:87], v[140:143], 0
	s_waitcnt lgkmcnt(12)
	v_mfma_f32_16x16x32_bf16 v[192:195], v[96:99], v[140:143], 0
	ds_read_b128 v[128:131], v210 offset:17152
	ds_read_b128 v[120:123], v210 offset:17216
	ds_read_b128 v[96:99], v210 offset:17280
	ds_read_b128 v[84:87], v210 offset:17344
	ds_read_b128 v[236:239], v209 offset:64
	ds_read_b128 v[240:243], v209 offset:128
	s_waitcnt lgkmcnt(6)
	v_mfma_f32_16x16x32_bf16 v[244:247], v[104:107], v[140:143], 0
	ds_read_b128 v[136:139], v209 offset:192
	ds_read_b128 v[132:135], v209 offset:256
	ds_read_b128 v[104:107], v209 offset:320
	v_mfma_f32_16x16x32_bf16 v[196:199], v[100:103], v[140:143], 0
	v_mfma_f32_16x16x32_bf16 v[248:251], v[92:95], v[156:159], v[188:191]
	ds_read_b128 v[100:103], v209 offset:384
	ds_read_b128 v[92:95], v209 offset:448
	s_waitcnt vmcnt(7)
	ds_write_b128 v200, v[144:147] offset:36864
	s_waitcnt vmcnt(6)
	ds_write_b128 v211, v[148:151] offset:36864
	s_waitcnt vmcnt(5)
	ds_write_b128 v212, v[152:155] offset:36864
	s_waitcnt vmcnt(4)
	ds_write_b128 v221, v[172:175] offset:36864
	s_waitcnt lgkmcnt(0)
	s_barrier
	v_mfma_f32_16x16x32_bf16 v[236:239], v[236:239], v[156:159], v[244:247]
	ds_read_b128 v[148:151], v210 offset:36864
	s_nop 1
	ds_read_b128 v[244:247], v210 offset:36928
	v_mfma_f32_16x16x32_bf16 v[144:147], v[180:183], v[156:159], v[192:195]
	s_waitcnt lgkmcnt(1)
	v_mfma_f32_16x16x32_bf16 v[222:225], v[148:151], v[140:143], 0
	ds_read_b128 v[152:155], v210 offset:45312
	ds_read_b128 v[148:151], v210 offset:45376
	ds_read_b128 v[180:183], v210 offset:53760
	ds_read_b128 v[192:195], v210 offset:53824
	v_mfma_f32_16x16x32_bf16 v[172:175], v[184:187], v[156:159], v[196:199]
	s_waitcnt lgkmcnt(1)
	v_mfma_f32_16x16x32_bf16 v[196:199], v[180:183], v[140:143], 0
	ds_read_b128 v[180:183], v209 offset:36864
	ds_read_b128 v[184:187], v209 offset:36928
	v_mfma_f32_16x16x32_bf16 v[152:155], v[152:155], v[140:143], 0
	s_waitcnt lgkmcnt(1)
	v_mfma_f32_16x16x32_bf16 v[188:191], v[180:183], v[140:143], 0
	v_mfma_f32_16x16x32_bf16 v[180:183], v[176:179], v[68:71], v[248:251]
	v_mfma_f32_16x16x32_bf16 v[176:179], v[228:231], v[68:71], v[144:147]
	v_mfma_f32_16x16x32_bf16 v[140:143], v[240:243], v[68:71], v[236:239]
	s_nop 1
	v_cndmask_b32_e32 v144, v253, v227, vcc
	v_cmp_lt_i32_e32 vcc, v204, v226
	v_lshlrev_b32_e32 v211, 2, v144
	v_mfma_f32_16x16x32_bf16 v[148:151], v[148:151], v[156:159], v[152:155]
	v_cndmask_b32_e32 v200, v253, v204, vcc
	v_lshlrev_b32_e32 v212, 2, v200
	v_lshrrev_b32_e32 v200, 1, v216
	v_mfma_f32_16x16x32_bf16 v[152:155], v[192:195], v[156:159], v[196:199]
	v_lshrrev_b32_e32 v194, 3, v219
	v_lshrrev_b32_e32 v216, 3, v216
	v_mul_lo_u32 v216, v216, s20
	v_mfma_f32_16x16x32_bf16 v[160:163], v[160:163], v[64:67], v[180:183]
	v_and_b32_e32 v200, 24, v200
	v_or_b32_e32 v192, 0x70, v215
	v_or_b32_e32 v193, 0xb0, v215
	v_mul_lo_u32 v180, v217, s20
	v_mul_lo_u32 v181, v218, s20
	v_mul_lo_u32 v182, v194, s20
	v_mfma_f32_16x16x32_bf16 v[144:147], v[244:247], v[156:159], v[222:225]
	s_waitcnt lgkmcnt(0)
	v_mfma_f32_16x16x32_bf16 v[156:159], v[184:187], v[156:159], v[188:191]
	v_add3_u32 v184, 0, v216, v220
	v_or_b32_e32 v185, 0xf0, v215
	v_mfma_f32_16x16x32_bf16 v[164:167], v[164:167], v[64:67], v[176:179]
	s_nop 2
	v_add3_u32 v176, 0, v180, v220
	v_add3_u32 v177, 0, v181, v220
	v_add3_u32 v178, 0, v182, v220
	v_mfma_f32_16x16x32_bf16 v[180:183], v[136:139], v[64:67], v[140:143]
	ds_read_b128 v[136:139], v210 offset:36992
	ds_read_b128 v[186:189], v210 offset:37056
	s_waitcnt lgkmcnt(1)
	v_mfma_f32_16x16x32_bf16 v[194:197], v[136:139], v[68:71], v[144:147]
	ds_read_b128 v[136:139], v210 offset:45440
	ds_read_b128 v[216:219], v210 offset:45504
	s_nop 0
	v_max_f32_e32 v147, v43, v43
	v_mfma_f32_16x16x32_bf16 v[172:175], v[232:235], v[68:71], v[172:175]
	s_waitcnt lgkmcnt(1)
	v_mfma_f32_16x16x32_bf16 v[148:151], v[136:139], v[68:71], v[148:151]
	ds_read_b128 v[136:139], v210 offset:53888
	ds_read_b128 v[220:223], v210 offset:53952
	v_mfma_f32_16x16x32_bf16 v[168:171], v[168:171], v[64:67], v[172:175]
	s_waitcnt lgkmcnt(1)
; #define LAS __attribute__((address_space(3)))
; __device__ __forceinline__ f32x4 mfma16(bf16x8 a, bf16x8 b, f32x4 c) { return __builtin_amdgcn_mfma_f32_16x16x32_bf16(a, b, c, 0, 0, 0); }
; __device__ __forceinline__ void xattn_unit(const Args& a, LAS unsigned char* lds, int b, int h, int qb, int tid, int wave, int lane) {
;     ...
;     for (int j = 0; j < 8; ++j) {
;         if (j < 6) gload(j + 2);
;         const LAS bf16* base = (const LAS bf16*)(lds + (j & 1) * STG);
;         if (j < 4) {
; #pragma unroll
;             for (int rt = 0; rt < 4; ++rt)
; #pragma unroll
;                 for (int kk = 0; kk < 8; ++kk) S[4 * j + rt] = mfma16(*(const LAS bf16x8*)(base + (16 * rt + fr) * KS + 32 * kk + 8 * fq), qf[kk], S[4 * j + rt]);
;             if (j == 3) {
;                 float mx = -3.0e38f;
; #pragma unroll
;                 for (int i = 0; i < 16; ++i) mx = fmaxf(mx, fmaxf(fmaxf(S[i][0], S[i][1]), fmaxf(S[i][2], S[i][3])));
;                 mx = fmaxf(mx, __shfl_xor(mx, 16)); mx = fmaxf(mx, __shfl_xor(mx, 32));
; #pragma unroll
;                 for (int i = 0; i < 16; ++i)
; #pragma unroll
;                     for (int k = 0; k < 4; ++k) { S[i][k] = __builtin_amdgcn_exp2f(S[i][k] - mx); l += S[i][k]; }
	v_mfma_f32_16x16x32_bf16 v[152:155], v[136:139], v[68:71], v[152:155]
	ds_read_b128 v[136:139], v209 offset:36992
	ds_read_b128 v[228:231], v209 offset:37056
	v_add_u32_e32 v172, 0, v200
	v_mad_u32_u24 v173, v213, s20, v172
	s_waitcnt lgkmcnt(1)
	v_mfma_f32_16x16x32_bf16 v[68:71], v[136:139], v[68:71], v[156:159]
	v_mad_u32_u24 v138, v192, s20, v172
	v_mad_u32_u24 v137, v193, s20, v172
	v_mad_u32_u24 v139, v214, s20, v172
	v_mfma_f32_16x16x32_bf16 v[156:159], v[116:119], v[28:31], v[160:163]
	v_mad_u32_u24 v136, v185, s20, v172
	v_add_u32_e32 v146, 0x1000, v173
	v_add_u32_e32 v144, 0x2000, v173
	v_mfma_f32_16x16x32_bf16 v[160:163], v[124:127], v[28:31], v[164:167]
	v_add_u32_e32 v142, 0x2800, v173
	v_add_u32_e32 v143, 0x3000, v173
	v_add_u32_e32 v141, 0x4800, v173
	v_mfma_f32_16x16x32_bf16 v[164:167], v[128:131], v[28:31], v[168:171]
	v_add_u32_e32 v140, 0x5000, v173
	v_add_u32_e32 v145, 0x800, v173
	v_lshl_add_u64 v[174:175], s[2:3], 0, v[202:203]
	v_mfma_f32_16x16x32_bf16 v[168:171], v[132:135], v[28:31], v[180:183]
	v_add_u32_e32 v135, 0x5800, v173
	v_add_u32_e32 v132, 0x6800, v173
	v_add_u32_e32 v133, 0x7000, v173
	v_mfma_f32_16x16x32_bf16 v[180:183], v[186:189], v[64:67], v[194:197]
	v_add_u32_e32 v134, 0x7800, v173
	v_lshl_add_u64 v[174:175], v[174:175], 0, s[4:5]
	v_add_u32_e32 v131, 0x9000, v173
	v_mfma_f32_16x16x32_bf16 v[148:151], v[216:219], v[64:67], v[148:151]
	v_add_u32_e32 v129, 0x9800, v173
	v_add_u32_e32 v130, 0xa000, v173
	v_add_u32_e32 v128, 0x9000, v139
	v_mfma_f32_16x16x32_bf16 v[152:155], v[220:223], v[64:67], v[152:155]
	v_add_u32_e32 v126, 0xb000, v173
	v_add_u32_e32 v127, 0xb800, v173
	v_add_u32_e32 v125, 0xc000, v173
	s_waitcnt lgkmcnt(0)
	v_mfma_f32_16x16x32_bf16 v[64:67], v[228:231], v[64:67], v[68:71]
	v_add_u32_e32 v124, 0x9000, v138
	v_add_u32_e32 v119, 0xd800, v173
	v_add_u32_e32 v118, 0xe000, v173
	v_mfma_f32_16x16x32_bf16 v[68:71], v[108:111], v[8:11], v[156:159]
	v_lshl_add_u64 v[108:109], v[174:175], 0, v[200:201]
	v_add_u32_e32 v116, 0xe800, v173
	v_add_u32_e32 v117, 0x9000, v137
	v_mfma_f32_16x16x32_bf16 v[156:159], v[112:115], v[8:11], v[160:163]
	v_max_f32_e32 v114, v47, v47
	v_max_f32_e32 v115, v46, v46
	v_max_f32_e32 v114, v115, v114
	v_mfma_f32_16x16x32_bf16 v[120:123], v[120:123], v[8:11], v[164:167]
	ds_read_b128 v[160:163], v210 offset:37120
	s_nop 1
	ds_read_b128 v[164:167], v210 offset:37184
	v_add_u32_e32 v111, 0xf800, v173
	v_add_u32_e32 v113, 0x7000, v131
	v_mfma_f32_16x16x32_bf16 v[104:107], v[104:107], v[8:11], v[168:171]
	v_add_u32_e32 v112, 0x7800, v131
	v_add_u32_e32 v110, 0x9000, v136
	s_waitcnt lgkmcnt(1)
	v_mfma_f32_16x16x32_bf16 v[160:163], v[160:163], v[28:31], v[180:183]
	ds_read_b128 v[168:171], v210 offset:45568
	s_nop 1
	ds_read_b128 v[180:183], v210 offset:45632
	s_waitcnt lgkmcnt(1)
	v_mfma_f32_16x16x32_bf16 v[148:151], v[168:171], v[28:31], v[148:151]
	ds_read_b128 v[168:171], v210 offset:54016
	ds_read_b128 v[186:189], v210 offset:54080
	s_waitcnt lgkmcnt(1)
	v_mfma_f32_16x16x32_bf16 v[152:155], v[168:171], v[28:31], v[152:155]
	ds_read_b128 v[168:171], v209 offset:37120
	ds_read_b128 v[190:193], v209 offset:37184
	s_waitcnt lgkmcnt(1)
	v_mfma_f32_16x16x32_bf16 v[28:31], v[168:171], v[28:31], v[64:67]
	v_max_f32_e32 v168, v42, v42
	v_max_f32_e32 v169, v39, v39
	v_max_f32_e32 v170, v38, v38
	v_mfma_f32_16x16x32_bf16 v[64:67], v[80:83], v[4:7], v[68:71]
	v_mfma_f32_16x16x32_bf16 v[68:71], v[88:91], v[4:7], v[156:159]
	v_max_f32_e32 v88, v35, v35
	v_max_f32_e32 v89, v34, v34
	v_max_f32_e32 v115, v89, v88
	v_mfma_f32_16x16x32_bf16 v[80:83], v[96:99], v[4:7], v[120:123]
	v_max_f32_e32 v96, v168, v147
	v_max_f32_e32 v97, v170, v169
	v_max_f32_e32 v147, v59, v59
	v_mfma_f32_16x16x32_bf16 v[88:91], v[100:103], v[4:7], v[104:107]
	v_max3_f32 v100, v44, v45, v114
	v_max3_f32 v101, v40, v41, v96
	v_max3_f32 v102, v36, v37, v97
	v_max3_f32 v103, v32, v33, v115
	v_max3_f32 v100, v100, s19, v101
	v_max3_f32 v114, v100, v102, v103
	v_mfma_f32_16x16x32_bf16 v[100:103], v[180:183], v[8:11], v[148:151]
	v_max_f32_e32 v115, v55, v55
	v_max_f32_e32 v120, v54, v54
	s_nop 0
	v_max_f32_e32 v148, v58, v58
	v_mfma_f32_16x16x32_bf16 v[96:99], v[164:167], v[8:11], v[160:163]
	v_max_f32_e32 v149, v63, v63
	v_max_f32_e32 v150, v62, v62
	v_mfma_f32_16x16x32_bf16 v[104:107], v[186:189], v[8:11], v[152:155]
	s_waitcnt lgkmcnt(0)
	v_mfma_f32_16x16x32_bf16 v[8:11], v[190:193], v[8:11], v[28:31]
	s_nop 2
	v_max_f32_e32 v28, v51, v51
	v_max_f32_e32 v29, v50, v50
	v_max_f32_e32 v30, v120, v115
	v_max_f32_e32 v31, v148, v147
	v_mfma_f32_16x16x32_bf16 v[120:123], v[72:75], v[0:3], v[64:67]
	v_max_f32_e32 v28, v29, v28
	v_max3_f32 v29, v52, v53, v30
	v_max3_f32 v30, v56, v57, v31
	v_max_f32_e32 v64, v150, v149
	v_max3_f32 v31, v60, v61, v64
	v_max3_f32 v28, v48, v49, v28
	v_max3_f32 v29, v114, v29, v30
	v_max3_f32 v114, v29, v31, v28
	ds_read_b128 v[28:31], v210 offset:37248
	ds_read_b128 v[72:75], v210 offset:37312
	v_mfma_f32_16x16x32_bf16 v[80:83], v[84:87], v[0:3], v[80:83]
	v_max_f32_e32 v115, v123, v123
	v_max_f32_e32 v147, v122, v122
	v_mfma_f32_16x16x32_bf16 v[84:87], v[92:95], v[0:3], v[88:91]
	s_waitcnt lgkmcnt(1)
	v_mfma_f32_16x16x32_bf16 v[88:91], v[28:31], v[4:7], v[96:99]
	ds_read_b128 v[28:31], v210 offset:45696
	ds_read_b128 v[92:95], v210 offset:45760
	s_waitcnt lgkmcnt(1)
	v_mfma_f32_16x16x32_bf16 v[96:99], v[28:31], v[4:7], v[100:103]
	ds_read_b128 v[28:31], v210 offset:54144
	s_nop 1
	ds_read_b128 v[100:103], v210 offset:54208
	s_waitcnt lgkmcnt(1)
	v_mfma_f32_16x16x32_bf16 v[104:107], v[28:31], v[4:7], v[104:107]
	ds_read_b128 v[28:31], v209 offset:37248
	ds_read_b128 v[148:151], v209 offset:37312
	v_mfma_f32_16x16x32_bf16 v[76:79], v[76:79], v[0:3], v[68:71]
	s_waitcnt lgkmcnt(1)
	v_mfma_f32_16x16x32_bf16 v[4:7], v[28:31], v[4:7], v[8:11]
	s_nop 0
	global_load_dwordx4 v[68:71], v205, s[6:7] offset:128
	global_load_dwordx4 v[28:31], v206, s[6:7] offset:128
	global_load_dwordx4 v[64:67], v207, s[6:7] offset:128
	v_mfma_f32_16x16x32_bf16 v[8:11], v[72:75], v[0:3], v[88:91]
	global_load_dwordx4 v[72:75], v208, s[6:7] offset:128
	s_waitcnt vmcnt(7)
	ds_write_b128 v184, v[12:15]
	s_waitcnt vmcnt(6)
	ds_write_b128 v176, v[16:19]
	s_waitcnt vmcnt(5)
	ds_write_b128 v177, v[20:23]
	s_waitcnt vmcnt(4)
	ds_write_b128 v178, v[24:27]
	s_waitcnt lgkmcnt(0)
	v_mfma_f32_16x16x32_bf16 v[88:91], v[92:95], v[0:3], v[96:99]
	s_barrier
; #define LAS __attribute__((address_space(3)))
; __device__ __forceinline__ f32x4 mfma16(bf16x8 a, bf16x8 b, f32x4 c) { return __builtin_amdgcn_mfma_f32_16x16x32_bf16(a, b, c, 0, 0, 0); }
; __device__ __forceinline__ bf16x8 pack8(f32x4 a, f32x4 b) { u32x4 w; w.x = pk2(a[0], a[1]); w.y = pk2(a[2], a[3]); w.z = pk2(b[0], b[1]); w.w = pk2(b[2], b[3]); return __builtin_bit_cast(bf16x8, w); }
; __device__ __forceinline__ void xattn_unit(const Args& a, LAS unsigned char* lds, int b, int h, int qb, int tid, int wave, int lane) {
;     ...
;             if (j == 3) {
;                 float mx = -3.0e38f;
; #pragma unroll
;                 for (int i = 0; i < 16; ++i) mx = fmaxf(mx, fmaxf(fmaxf(S[i][0], S[i][1]), fmaxf(S[i][2], S[i][3])));
;                 mx = fmaxf(mx, __shfl_xor(mx, 16)); mx = fmaxf(mx, __shfl_xor(mx, 32));
; #pragma unroll
;                 for (int i = 0; i < 16; ++i)
; #pragma unroll
;                     for (int k = 0; k < 4; ++k) { S[i][k] = __builtin_amdgcn_exp2f(S[i][k] - mx); l += S[i][k]; }
;                 l += __shfl_xor(l, 16); l += __shfl_xor(l, 32);
; #pragma unroll
;                 for (int c2 = 0; c2 < 8; ++c2) pf[c2] = pack8(S[2 * c2], S[2 * c2 + 1]);
;             }
;         } else {
;             const int mt = j - 4;
; #pragma unroll
;             for (int dt = 0; dt < 16; ++dt) {
;                 const LAS bf16* vr = base + (16 * dt + fr) * VS + 4 * fq;
;                 O[dt] = mfma16(cat8(*(const LAS u32x2*)vr, *(const LAS u32x2*)(vr + 16)), pf[2 * mt], O[dt]);
;                 O[dt] = mfma16(cat8(*(const LAS u32x2*)(vr + 32), *(const LAS u32x2*)(vr + 48)), pf[2 * mt + 1], O[dt]);
;             }
	ds_read2_b64 v[12:15], v173 offset1:4
	ds_read2_b64 v[16:19], v145 offset0:32 offset1:36
	v_max_f32_e32 v96, v79, v79
	v_max_f32_e32 v97, v78, v78
	v_max_f32_e32 v98, v83, v83
	v_mfma_f32_16x16x32_bf16 v[92:95], v[100:103], v[0:3], v[104:107]
	v_max_f32_e32 v99, v82, v82
	v_max_f32_e32 v100, v87, v87
	v_max_f32_e32 v101, v86, v86
	v_mfma_f32_16x16x32_bf16 v[0:3], v[148:151], v[0:3], v[4:7]
	ds_read2_b64 v[20:23], v146 offset0:64 offset1:68
	ds_read2_b64 v[24:27], v139 offset1:4
	ds_read2_b64 v[148:151], v173 offset0:8 offset1:12
	v_max_f32_e32 v4, v147, v115
	v_max_f32_e32 v5, v97, v96
	v_max_f32_e32 v6, v99, v98
	v_max_f32_e32 v7, v101, v100
	v_max3_f32 v4, v120, v121, v4
	v_max3_f32 v5, v76, v77, v5
	v_max3_f32 v6, v80, v81, v6
	v_max3_f32 v7, v84, v85, v7
	v_max3_f32 v4, v114, v4, v5
	v_max3_f32 v4, v4, v6, v7
	v_max_f32_e32 v5, v11, v11
	v_max_f32_e32 v6, v10, v10
	v_max_f32_e32 v7, v91, v91
	v_max_f32_e32 v96, v90, v90
	v_max_f32_e32 v97, v95, v95
	v_max_f32_e32 v98, v94, v94
	v_max_f32_e32 v99, v3, v3
	v_max_f32_e32 v100, v2, v2
	v_max_f32_e32 v5, v6, v5
	v_max_f32_e32 v6, v96, v7
	v_max_f32_e32 v7, v98, v97
	v_max_f32_e32 v96, v100, v99
	v_max3_f32 v5, v8, v9, v5
	v_max3_f32 v6, v88, v89, v6
	v_max3_f32 v7, v92, v93, v7
	v_max3_f32 v96, v0, v1, v96
	v_max3_f32 v4, v4, v5, v6
	v_max3_f32 v4, v4, v7, v96
	ds_bpermute_b32 v5, v211, v4
	s_waitcnt lgkmcnt(0)
	v_max_f32_e32 v5, v5, v5
	v_max_f32_e32 v4, v4, v5
	ds_bpermute_b32 v5, v212, v4
	s_waitcnt lgkmcnt(0)
	v_max_f32_e32 v5, v5, v5
	v_max_f32_e32 v4, v4, v5
	v_sub_f32_e32 v5, v44, v4
	v_sub_f32_e32 v6, v45, v4
	v_sub_f32_e32 v7, v46, v4
	v_sub_f32_e32 v44, v47, v4
	v_sub_f32_e32 v40, v40, v4
	v_sub_f32_e32 v41, v41, v4
	v_sub_f32_e32 v42, v42, v4
	v_sub_f32_e32 v43, v43, v4
	v_sub_f32_e32 v36, v36, v4
	v_sub_f32_e32 v37, v37, v4
	v_sub_f32_e32 v38, v38, v4
	v_sub_f32_e32 v39, v39, v4
	v_sub_f32_e32 v32, v32, v4
	v_sub_f32_e32 v33, v33, v4
	v_sub_f32_e32 v34, v34, v4
	v_sub_f32_e32 v35, v35, v4
	v_sub_f32_e32 v45, v52, v4
	v_sub_f32_e32 v46, v53, v4
	v_sub_f32_e32 v47, v54, v4
	v_sub_f32_e32 v52, v55, v4
	v_sub_f32_e32 v53, v56, v4
	v_sub_f32_e32 v54, v57, v4
	v_sub_f32_e32 v55, v58, v4
	v_sub_f32_e32 v56, v59, v4
	v_sub_f32_e32 v57, v60, v4
	v_sub_f32_e32 v58, v61, v4
	v_sub_f32_e32 v59, v62, v4
	v_sub_f32_e32 v60, v63, v4
	v_sub_f32_e32 v48, v48, v4
	v_sub_f32_e32 v49, v49, v4
	v_sub_f32_e32 v50, v50, v4
	v_sub_f32_e32 v51, v51, v4
	v_sub_f32_e32 v61, v120, v4
	v_sub_f32_e32 v62, v121, v4
	v_sub_f32_e32 v63, v122, v4
	v_sub_f32_e32 v96, v123, v4
	v_sub_f32_e32 v76, v76, v4
	v_sub_f32_e32 v77, v77, v4
	v_sub_f32_e32 v78, v78, v4
	v_sub_f32_e32 v79, v79, v4
	v_sub_f32_e32 v80, v80, v4
	v_sub_f32_e32 v81, v81, v4
	v_sub_f32_e32 v82, v82, v4
	v_sub_f32_e32 v83, v83, v4
	v_sub_f32_e32 v84, v84, v4
	v_sub_f32_e32 v85, v85, v4
	v_sub_f32_e32 v86, v86, v4
	v_sub_f32_e32 v87, v87, v4
	v_sub_f32_e32 v8, v8, v4
	v_sub_f32_e32 v9, v9, v4
	v_sub_f32_e32 v10, v10, v4
	v_sub_f32_e32 v11, v11, v4
	v_sub_f32_e32 v88, v88, v4
	v_sub_f32_e32 v89, v89, v4
	v_sub_f32_e32 v90, v90, v4
	v_sub_f32_e32 v91, v91, v4
	v_sub_f32_e32 v92, v92, v4
	v_sub_f32_e32 v93, v93, v4
	v_sub_f32_e32 v94, v94, v4
	v_sub_f32_e32 v95, v95, v4
	v_sub_f32_e32 v0, v0, v4
	v_sub_f32_e32 v1, v1, v4
	v_sub_f32_e32 v2, v2, v4
	v_sub_f32_e32 v3, v3, v4
	v_exp_f32_e32 v4, v5
	v_exp_f32_e32 v97, v6
	v_exp_f32_e32 v98, v7
	v_exp_f32_e32 v99, v44
	v_exp_f32_e32 v100, v40
	v_exp_f32_e32 v190, v52
	v_add_f32_e32 v52, 0, v4
	v_exp_f32_e32 v101, v41
	v_add_f32_e32 v52, v97, v52
	v_exp_f32_e32 v102, v42
	v_add_f32_e32 v52, v98, v52
	v_exp_f32_e32 v103, v43
	v_add_f32_e32 v52, v99, v52
	v_exp_f32_e32 v104, v36
	v_add_f32_e32 v52, v100, v52
	v_exp_f32_e32 v105, v37
	v_add_f32_e32 v52, v101, v52
	v_exp_f32_e32 v106, v38
	v_exp_f32_e32 v114, v39
	v_add_f32_e32 v52, v102, v52
	v_add_f32_e32 v52, v103, v52
	v_add_f32_e32 v52, v104, v52
	v_add_f32_e32 v52, v105, v52
	v_exp_f32_e32 v191, v53
	v_exp_f32_e32 v192, v54
	v_exp_f32_e32 v193, v55
	v_exp_f32_e32 v194, v56
	v_exp_f32_e32 v195, v57
	v_exp_f32_e32 v196, v58
	v_exp_f32_e32 v197, v59
	v_exp_f32_e32 v198, v60
	v_exp_f32_e32 v209, v61
	v_exp_f32_e32 v210, v62
	v_exp_f32_e32 v213, v63
	v_exp_f32_e32 v214, v96
	v_exp_f32_e32 v215, v76
	v_exp_f32_e32 v216, v77
	v_exp_f32_e32 v217, v78
	v_exp_f32_e32 v218, v79
	v_exp_f32_e32 v219, v80
	v_exp_f32_e32 v220, v81
	v_exp_f32_e32 v221, v82
	v_exp_f32_e32 v222, v83
	v_exp_f32_e32 v223, v84
	v_exp_f32_e32 v224, v85
	v_exp_f32_e32 v225, v86
	v_exp_f32_e32 v228, v87
	v_exp_f32_e32 v233, v88
	v_exp_f32_e32 v234, v89
	v_exp_f32_e32 v235, v90
	v_exp_f32_e32 v236, v91
	v_exp_f32_e32 v237, v92
	v_exp_f32_e32 v238, v93
	v_exp_f32_e32 v239, v94
	v_exp_f32_e32 v240, v95
	v_cvt_pk_bf16_f32 v36, v4, v97
	v_cvt_pk_bf16_f32 v37, v98, v99
	v_cvt_pk_bf16_f32 v38, v100, v101
	v_cvt_pk_bf16_f32 v39, v102, v103
	v_cvt_pk_bf16_f32 v40, v104, v105
	v_cvt_pk_bf16_f32 v41, v106, v114
	v_add_f32_e32 v156, v106, v52
	ds_read2_b64 v[52:55], v144 offset0:128 offset1:132
	ds_read2_b64 v[56:59], v142 offset0:160 offset1:164
	ds_read2_b64 v[60:63], v143 offset0:192 offset1:196
	ds_read2_b64 v[76:79], v138 offset1:4
	ds_read2_b64 v[80:83], v141 offset1:4
	ds_read2_b64 v[84:87], v140 offset0:32 offset1:36
	ds_read2_b64 v[88:91], v135 offset0:64 offset1:68
	ds_read2_b64 v[92:95], v137 offset1:4
	ds_read2_b64 v[96:99], v132 offset0:128 offset1:132
	ds_read2_b64 v[100:103], v133 offset0:160 offset1:164
	ds_read2_b64 v[104:107], v134 offset0:192 offset1:196
	ds_read2_b64 v[120:123], v136 offset1:4
	v_exp_f32_e32 v115, v32
	v_exp_f32_e32 v147, v33
	v_exp_f32_e32 v172, v34
	v_exp_f32_e32 v174, v35
	v_mfma_f32_16x16x32_bf16 v[12:15], v[12:15], v[36:39], 0
	v_cvt_pk_bf16_f32 v42, v115, v147
	v_add_f32_e32 v114, v114, v156
	v_cvt_pk_bf16_f32 v43, v172, v174
	v_mfma_f32_16x16x32_bf16 v[16:19], v[16:19], v[36:39], 0
	v_exp_f32_e32 v175, v45
	v_exp_f32_e32 v179, v46
	v_exp_f32_e32 v185, v47
	v_mfma_f32_16x16x32_bf16 v[20:23], v[20:23], v[36:39], 0
	v_cvt_pk_bf16_f32 v46, v191, v192
	v_cvt_pk_bf16_f32 v44, v175, v179
	v_cvt_pk_bf16_f32 v45, v185, v190
	v_mfma_f32_16x16x32_bf16 v[24:27], v[24:27], v[36:39], 0
	v_cvt_pk_bf16_f32 v47, v193, v194
	v_exp_f32_e32 v199, v48
	v_exp_f32_e32 v200, v49
	s_waitcnt lgkmcnt(11)
; #define LAS __attribute__((address_space(3)))
; __device__ __forceinline__ f32x4 mfma16(bf16x8 a, bf16x8 b, f32x4 c) { return __builtin_amdgcn_mfma_f32_16x16x32_bf16(a, b, c, 0, 0, 0); }
; __device__ __forceinline__ void xattn_unit(const Args& a, LAS unsigned char* lds, int b, int h, int qb, int tid, int wave, int lane) {
;     ...
;         } else {
;             const int mt = j - 4;
; #pragma unroll
;             for (int dt = 0; dt < 16; ++dt) {
;                 const LAS bf16* vr = base + (16 * dt + fr) * VS + 4 * fq;
;                 O[dt] = mfma16(cat8(*(const LAS u32x2*)vr, *(const LAS u32x2*)(vr + 16)), pf[2 * mt], O[dt]);
;                 O[dt] = mfma16(cat8(*(const LAS u32x2*)(vr + 32), *(const LAS u32x2*)(vr + 48)), pf[2 * mt + 1], O[dt]);
;             }
;         }
;         if (j < 7) lstore(j + 1);
	v_mfma_f32_16x16x32_bf16 v[52:55], v[52:55], v[36:39], 0
	v_exp_f32_e32 v202, v50
	v_exp_f32_e32 v203, v51
	v_cvt_pk_bf16_f32 v48, v195, v196
	s_waitcnt lgkmcnt(10)
	v_mfma_f32_16x16x32_bf16 v[56:59], v[56:59], v[36:39], 0
	v_cvt_pk_bf16_f32 v49, v197, v198
	v_cvt_pk_bf16_f32 v50, v199, v200
	v_cvt_pk_bf16_f32 v51, v202, v203
	s_waitcnt lgkmcnt(9)
	v_mfma_f32_16x16x32_bf16 v[60:63], v[60:63], v[36:39], 0
	v_add_f32_e32 v114, v115, v114
	v_add_f32_e32 v114, v147, v114
	v_add_f32_e32 v114, v172, v114
	s_waitcnt lgkmcnt(8)
	v_mfma_f32_16x16x32_bf16 v[76:79], v[76:79], v[36:39], 0
	v_add_f32_e32 v114, v174, v114
	v_add_f32_e32 v114, v175, v114
	v_add_f32_e32 v114, v179, v114
	s_waitcnt lgkmcnt(7)
	v_mfma_f32_16x16x32_bf16 v[80:83], v[80:83], v[36:39], 0
	v_add_f32_e32 v114, v185, v114
	v_add_f32_e32 v114, v190, v114
	v_add_f32_e32 v114, v191, v114
	s_waitcnt lgkmcnt(6)
	v_mfma_f32_16x16x32_bf16 v[84:87], v[84:87], v[36:39], 0
	v_add_f32_e32 v114, v192, v114
	v_add_f32_e32 v114, v193, v114
	v_add_f32_e32 v114, v194, v114
	s_waitcnt lgkmcnt(5)
	v_mfma_f32_16x16x32_bf16 v[88:91], v[88:91], v[36:39], 0
	v_exp_f32_e32 v229, v8
	v_exp_f32_e32 v230, v9
	v_exp_f32_e32 v231, v10
	s_waitcnt lgkmcnt(4)
	v_mfma_f32_16x16x32_bf16 v[92:95], v[92:95], v[36:39], 0
	v_exp_f32_e32 v232, v11
	v_exp_f32_e32 v241, v0
	v_exp_f32_e32 v242, v1
	s_waitcnt lgkmcnt(3)
	v_mfma_f32_16x16x32_bf16 v[96:99], v[96:99], v[36:39], 0
	v_exp_f32_e32 v243, v2
	v_exp_f32_e32 v244, v3
	v_cvt_pk_bf16_f32 v32, v209, v210
	s_waitcnt lgkmcnt(2)
	v_mfma_f32_16x16x32_bf16 v[100:103], v[100:103], v[36:39], 0
	v_cvt_pk_bf16_f32 v33, v213, v214
	v_cvt_pk_bf16_f32 v34, v215, v216
	v_cvt_pk_bf16_f32 v35, v217, v218
	s_waitcnt lgkmcnt(1)
	v_mfma_f32_16x16x32_bf16 v[104:107], v[104:107], v[36:39], 0
	v_cvt_pk_bf16_f32 v8, v219, v220
	v_cvt_pk_bf16_f32 v9, v221, v222
	v_cvt_pk_bf16_f32 v10, v223, v224
	s_waitcnt lgkmcnt(0)
	v_mfma_f32_16x16x32_bf16 v[36:39], v[120:123], v[36:39], 0
	ds_read2_b64 v[120:123], v145 offset0:40 offset1:44
	v_cvt_pk_bf16_f32 v11, v225, v228
	v_cvt_pk_bf16_f32 v4, v229, v230
	v_mfma_f32_16x16x32_bf16 v[12:15], v[148:151], v[40:43], v[12:15]
	ds_read2_b64 v[148:151], v146 offset0:72 offset1:76
	v_cvt_pk_bf16_f32 v5, v231, v232
	v_cvt_pk_bf16_f32 v6, v233, v234
	s_waitcnt lgkmcnt(1)
	v_mfma_f32_16x16x32_bf16 v[16:19], v[120:123], v[40:43], v[16:19]
	ds_read2_b64 v[120:123], v139 offset0:8 offset1:12
	v_cvt_pk_bf16_f32 v7, v235, v236
	v_cvt_pk_bf16_f32 v0, v237, v238
	s_waitcnt lgkmcnt(1)
	v_mfma_f32_16x16x32_bf16 v[20:23], v[148:151], v[40:43], v[20:23]
	ds_read2_b64 v[148:151], v144 offset0:136 offset1:140
	v_cvt_pk_bf16_f32 v1, v239, v240
	v_cvt_pk_bf16_f32 v2, v241, v242
	s_waitcnt lgkmcnt(1)
	v_mfma_f32_16x16x32_bf16 v[24:27], v[120:123], v[40:43], v[24:27]
	ds_read2_b64 v[120:123], v142 offset0:168 offset1:172
	v_cvt_pk_bf16_f32 v3, v243, v244
	s_waitcnt lgkmcnt(1)
	v_mfma_f32_16x16x32_bf16 v[52:55], v[148:151], v[40:43], v[52:55]
	ds_read2_b64 v[148:151], v143 offset0:200 offset1:204
	s_waitcnt lgkmcnt(1)
	v_mfma_f32_16x16x32_bf16 v[56:59], v[120:123], v[40:43], v[56:59]
	ds_read2_b64 v[120:123], v138 offset0:8 offset1:12
	s_waitcnt lgkmcnt(1)
	v_mfma_f32_16x16x32_bf16 v[60:63], v[148:151], v[40:43], v[60:63]
	ds_read2_b64 v[148:151], v141 offset0:8 offset1:12
	ds_read2_b64 v[152:155], v140 offset0:40 offset1:44
	ds_read2_b64 v[156:159], v135 offset0:72 offset1:76
	s_waitcnt lgkmcnt(3)
	v_mfma_f32_16x16x32_bf16 v[76:79], v[120:123], v[40:43], v[76:79]
	global_load_dwordx4 v[120:123], v205, s[6:7] offset:256
	s_waitcnt lgkmcnt(2)
	v_mfma_f32_16x16x32_bf16 v[80:83], v[148:151], v[40:43], v[80:83]
	global_load_dwordx4 v[148:151], v206, s[6:7] offset:256
	global_load_dwordx4 v[160:163], v207, s[6:7] offset:256
	ds_read2_b64 v[164:167], v137 offset0:8 offset1:12
	s_waitcnt lgkmcnt(2)
	v_mfma_f32_16x16x32_bf16 v[84:87], v[152:155], v[40:43], v[84:87]
	global_load_dwordx4 v[152:155], v208, s[6:7] offset:256
	ds_read2_b64 v[168:171], v132 offset0:136 offset1:140
	ds_read2_b64 v[180:183], v133 offset0:168 offset1:172
	s_waitcnt lgkmcnt(3)
	v_mfma_f32_16x16x32_bf16 v[88:91], v[156:159], v[40:43], v[88:91]
	ds_read2_b64 v[156:159], v134 offset0:200 offset1:204
	ds_read2_b64 v[186:189], v136 offset0:8 offset1:12
	s_waitcnt vmcnt(7)
	ds_write_b128 v184, v[68:71] offset:36864
	s_waitcnt vmcnt(6)
	ds_write_b128 v176, v[28:31] offset:36864
	s_waitcnt vmcnt(5)
	ds_write_b128 v177, v[64:67] offset:36864
	s_waitcnt vmcnt(4)
	ds_write_b128 v178, v[72:75] offset:36864
	s_waitcnt lgkmcnt(0)
	s_barrier
; #define LAS __attribute__((address_space(3)))
; __device__ __forceinline__ f32x4 mfma16(bf16x8 a, bf16x8 b, f32x4 c) { return __builtin_amdgcn_mfma_f32_16x16x32_bf16(a, b, c, 0, 0, 0); }
; __device__ __forceinline__ void xattn_unit(const Args& a, LAS unsigned char* lds, int b, int h, int qb, int tid, int wave, int lane) {
;     ...
;         } else {
;             const int mt = j - 4;
; #pragma unroll
;             for (int dt = 0; dt < 16; ++dt) {
;                 const LAS bf16* vr = base + (16 * dt + fr) * VS + 4 * fq;
;                 O[dt] = mfma16(cat8(*(const LAS u32x2*)vr, *(const LAS u32x2*)(vr + 16)), pf[2 * mt], O[dt]);
;                 O[dt] = mfma16(cat8(*(const LAS u32x2*)(vr + 32), *(const LAS u32x2*)(vr + 48)), pf[2 * mt + 1], O[dt]);
;             }
;         }
;         if (j < 7) lstore(j + 1);
;         __syncthreads();
	ds_read2_b64 v[72:75], v131 offset1:4
	v_mfma_f32_16x16x32_bf16 v[92:95], v[164:167], v[40:43], v[92:95]
	v_mfma_f32_16x16x32_bf16 v[68:71], v[168:171], v[40:43], v[96:99]
	v_mfma_f32_16x16x32_bf16 v[28:31], v[180:183], v[40:43], v[100:103]
	v_mfma_f32_16x16x32_bf16 v[64:67], v[156:159], v[40:43], v[104:107]
	v_mfma_f32_16x16x32_bf16 v[36:39], v[186:189], v[40:43], v[36:39]
	ds_read2_b64 v[40:43], v129 offset0:32 offset1:36
	s_waitcnt lgkmcnt(1)
	v_mfma_f32_16x16x32_bf16 v[12:15], v[72:75], v[44:47], v[12:15]
	ds_read2_b64 v[72:75], v130 offset0:64 offset1:68
	s_waitcnt lgkmcnt(1)
	v_mfma_f32_16x16x32_bf16 v[16:19], v[40:43], v[44:47], v[16:19]
	ds_read2_b64 v[40:43], v128 offset1:4
	s_waitcnt lgkmcnt(1)
	v_mfma_f32_16x16x32_bf16 v[20:23], v[72:75], v[44:47], v[20:23]
	ds_read2_b64 v[72:75], v126 offset0:128 offset1:132
	s_waitcnt lgkmcnt(1)
	v_mfma_f32_16x16x32_bf16 v[24:27], v[40:43], v[44:47], v[24:27]
	ds_read2_b64 v[40:43], v127 offset0:160 offset1:164
	s_waitcnt lgkmcnt(1)
	v_mfma_f32_16x16x32_bf16 v[52:55], v[72:75], v[44:47], v[52:55]
	ds_read2_b64 v[72:75], v125 offset0:192 offset1:196
	s_waitcnt lgkmcnt(1)
	v_mfma_f32_16x16x32_bf16 v[40:43], v[40:43], v[44:47], v[56:59]
	s_nop 2
	ds_read2_b64 v[56:59], v124 offset1:4
	s_waitcnt lgkmcnt(1)
	v_mfma_f32_16x16x32_bf16 v[60:63], v[72:75], v[44:47], v[60:63]
	ds_read2_b64 v[72:75], v119 offset1:4
	s_waitcnt lgkmcnt(1)
	v_mfma_f32_16x16x32_bf16 v[56:59], v[56:59], v[44:47], v[76:79]
	s_nop 2
	ds_read2_b64 v[76:79], v118 offset0:32 offset1:36
	s_waitcnt lgkmcnt(1)
	v_mfma_f32_16x16x32_bf16 v[72:75], v[72:75], v[44:47], v[80:83]
	s_nop 2
	ds_read2_b64 v[80:83], v116 offset0:64 offset1:68
	s_waitcnt lgkmcnt(1)
	v_mfma_f32_16x16x32_bf16 v[76:79], v[76:79], v[44:47], v[84:87]
	s_nop 2
	ds_read2_b64 v[84:87], v117 offset1:4
	s_waitcnt lgkmcnt(1)
	v_mfma_f32_16x16x32_bf16 v[80:83], v[80:83], v[44:47], v[88:91]
	s_nop 2
	ds_read2_b64 v[88:91], v111 offset0:128 offset1:132
	s_waitcnt lgkmcnt(1)
	v_mfma_f32_16x16x32_bf16 v[84:87], v[84:87], v[44:47], v[92:95]
	s_nop 2
	ds_read2_b64 v[92:95], v113 offset0:160 offset1:164
	s_waitcnt lgkmcnt(1)
	v_mfma_f32_16x16x32_bf16 v[68:71], v[88:91], v[44:47], v[68:71]
	ds_read2_b64 v[88:91], v112 offset0:192 offset1:196
	s_waitcnt lgkmcnt(1)
	v_mfma_f32_16x16x32_bf16 v[28:31], v[92:95], v[44:47], v[28:31]
	ds_read2_b64 v[92:95], v110 offset1:4
	s_waitcnt lgkmcnt(1)
	v_mfma_f32_16x16x32_bf16 v[64:67], v[88:91], v[44:47], v[64:67]
	ds_read2_b64 v[88:91], v131 offset0:8 offset1:12
	s_waitcnt lgkmcnt(1)
	v_mfma_f32_16x16x32_bf16 v[36:39], v[92:95], v[44:47], v[36:39]
	ds_read2_b64 v[44:47], v129 offset0:40 offset1:44
	s_waitcnt lgkmcnt(1)
	v_mfma_f32_16x16x32_bf16 v[12:15], v[88:91], v[48:51], v[12:15]
	ds_read2_b64 v[88:91], v130 offset0:72 offset1:76
	s_waitcnt lgkmcnt(1)
	v_mfma_f32_16x16x32_bf16 v[16:19], v[44:47], v[48:51], v[16:19]
	ds_read2_b64 v[44:47], v128 offset0:8 offset1:12
	s_waitcnt lgkmcnt(1)
	v_mfma_f32_16x16x32_bf16 v[20:23], v[88:91], v[48:51], v[20:23]
	ds_read2_b64 v[88:91], v126 offset0:136 offset1:140
	s_waitcnt lgkmcnt(1)
	v_mfma_f32_16x16x32_bf16 v[24:27], v[44:47], v[48:51], v[24:27]
	ds_read2_b64 v[44:47], v127 offset0:168 offset1:172
	s_waitcnt lgkmcnt(1)
	v_mfma_f32_16x16x32_bf16 v[52:55], v[88:91], v[48:51], v[52:55]
	ds_read2_b64 v[88:91], v125 offset0:200 offset1:204
	ds_read2_b64 v[92:95], v124 offset0:8 offset1:12
	ds_read2_b64 v[96:99], v119 offset0:8 offset1:12
	s_waitcnt lgkmcnt(3)
	v_mfma_f32_16x16x32_bf16 v[40:43], v[44:47], v[48:51], v[40:43]
	global_load_dwordx4 v[44:47], v205, s[6:7] offset:384
	s_waitcnt lgkmcnt(2)
	v_mfma_f32_16x16x32_bf16 v[60:63], v[88:91], v[48:51], v[60:63]
	global_load_dwordx4 v[88:91], v206, s[6:7] offset:384
	global_load_dwordx4 v[100:103], v207, s[6:7] offset:384
	ds_read2_b64 v[104:107], v118 offset0:40 offset1:44
	s_waitcnt lgkmcnt(2)
	v_mfma_f32_16x16x32_bf16 v[56:59], v[92:95], v[48:51], v[56:59]
	global_load_dwordx4 v[92:95], v208, s[6:7] offset:384
	ds_read2_b64 v[156:159], v116 offset0:72 offset1:76
	ds_read2_b64 v[164:167], v117 offset0:8 offset1:12
	s_waitcnt lgkmcnt(3)
	v_mfma_f32_16x16x32_bf16 v[72:75], v[96:99], v[48:51], v[72:75]
	ds_read2_b64 v[96:99], v111 offset0:136 offset1:140
	ds_read2_b64 v[168:171], v113 offset0:168 offset1:172
	ds_read2_b64 v[180:183], v112 offset0:200 offset1:204
	s_waitcnt lgkmcnt(5)
	v_mfma_f32_16x16x32_bf16 v[76:79], v[104:107], v[48:51], v[76:79]
	ds_read2_b64 v[104:107], v110 offset0:8 offset1:12
	s_waitcnt vmcnt(7)
	ds_write_b128 v184, v[120:123]
	s_waitcnt vmcnt(6)
	ds_write_b128 v176, v[148:151]
	s_waitcnt vmcnt(5)
	ds_write_b128 v177, v[160:163]
	s_waitcnt vmcnt(4)
	ds_write_b128 v178, v[152:155]
	s_waitcnt lgkmcnt(0)
	v_mfma_f32_16x16x32_bf16 v[68:71], v[96:99], v[48:51], v[68:71]
	v_add_f32_e32 v96, v195, v114
	v_add_f32_e32 v96, v196, v96
	v_add_f32_e32 v96, v197, v96
	v_add_f32_e32 v96, v198, v96
	v_add_f32_e32 v96, v199, v96
	v_add_f32_e32 v96, v200, v96
	v_add_f32_e32 v96, v202, v96
	v_add_f32_e32 v96, v203, v96
	v_add_f32_e32 v96, v209, v96
	v_mfma_f32_16x16x32_bf16 v[80:83], v[156:159], v[48:51], v[80:83]
	s_barrier
; #define LAS __attribute__((address_space(3)))
; __device__ __forceinline__ f32x4 mfma16(bf16x8 a, bf16x8 b, f32x4 c) { return __builtin_amdgcn_mfma_f32_16x16x32_bf16(a, b, c, 0, 0, 0); }
; __device__ __forceinline__ bf16x8 pack8(f32x4 a, f32x4 b) { u32x4 w; w.x = pk2(a[0], a[1]); w.y = pk2(a[2], a[3]); w.z = pk2(b[0], b[1]); w.w = pk2(b[2], b[3]); return __builtin_bit_cast(bf16x8, w); }
; __device__ __forceinline__ void xattn_unit(const Args& a, LAS unsigned char* lds, int b, int h, int qb, int tid, int wave, int lane) {
;     ...
;                 l += __shfl_xor(l, 16); l += __shfl_xor(l, 32);
; #pragma unroll
;                 for (int c2 = 0; c2 < 8; ++c2) pf[c2] = pack8(S[2 * c2], S[2 * c2 + 1]);
;             }
;         } else {
;             const int mt = j - 4;
; #pragma unroll
;             for (int dt = 0; dt < 16; ++dt) {
;                 const LAS bf16* vr = base + (16 * dt + fr) * VS + 4 * fq;
;                 O[dt] = mfma16(cat8(*(const LAS u32x2*)vr, *(const LAS u32x2*)(vr + 16)), pf[2 * mt], O[dt]);
;                 O[dt] = mfma16(cat8(*(const LAS u32x2*)(vr + 32), *(const LAS u32x2*)(vr + 48)), pf[2 * mt + 1], O[dt]);
;             }
;         }
;         if (j < 7) lstore(j + 1);
;         __syncthreads();
;     }
;     const float il = 1.f / l;
	v_mfma_f32_16x16x32_bf16 v[84:87], v[164:167], v[48:51], v[84:87]
	v_mfma_f32_16x16x32_bf16 v[28:31], v[168:171], v[48:51], v[28:31]
	v_mfma_f32_16x16x32_bf16 v[64:67], v[180:183], v[48:51], v[64:67]
	v_mfma_f32_16x16x32_bf16 v[36:39], v[104:107], v[48:51], v[36:39]
	v_add_f32_e32 v48, v210, v96
	v_add_f32_e32 v48, v213, v48
	v_add_f32_e32 v48, v214, v48
	v_add_f32_e32 v48, v215, v48
	v_add_f32_e32 v48, v216, v48
	v_add_f32_e32 v48, v217, v48
	v_add_f32_e32 v48, v218, v48
	v_add_f32_e32 v48, v219, v48
	v_add_f32_e32 v48, v220, v48
	v_add_f32_e32 v48, v221, v48
	v_add_f32_e32 v48, v222, v48
	v_add_f32_e32 v48, v223, v48
	v_add_f32_e32 v48, v224, v48
	v_add_f32_e32 v48, v225, v48
	v_add_f32_e32 v48, v228, v48
	v_add_f32_e32 v48, v229, v48
	v_add_f32_e32 v48, v230, v48
	v_add_f32_e32 v48, v231, v48
	v_add_f32_e32 v48, v232, v48
	v_add_f32_e32 v48, v233, v48
	v_add_f32_e32 v48, v234, v48
	v_add_f32_e32 v48, v235, v48
	v_add_f32_e32 v48, v236, v48
	v_add_f32_e32 v48, v237, v48
	v_add_f32_e32 v48, v238, v48
	v_add_f32_e32 v48, v239, v48
	v_add_f32_e32 v48, v240, v48
	v_add_f32_e32 v48, v241, v48
	v_add_f32_e32 v48, v242, v48
	v_add_f32_e32 v48, v243, v48
	v_add_f32_e32 v48, v244, v48
	ds_bpermute_b32 v49, v211, v48
	s_waitcnt lgkmcnt(0)
	v_add_f32_e32 v48, v48, v49
	ds_bpermute_b32 v49, v212, v48
	s_waitcnt lgkmcnt(0)
	v_add_f32_e32 v48, v48, v49
	v_div_scale_f32 v49, s[6:7], v48, v48, 1.0
	v_rcp_f32_e32 v51, v49
	v_div_scale_f32 v50, vcc, 1.0, v48, 1.0
	v_fma_f32 v96, -v49, v51, 1.0
	v_fmac_f32_e32 v51, v96, v51
	v_mul_f32_e32 v96, v50, v51
	v_fma_f32 v97, -v49, v96, v50
	v_fmac_f32_e32 v96, v97, v51
	v_fma_f32 v49, -v49, v96, v50
	v_div_fmas_f32 v49, v49, v51, v96
	v_div_fixup_f32 v114, v49, v48, 1.0
	ds_read2_b64 v[48:51], v173 offset1:4
	ds_read2_b64 v[96:99], v145 offset0:32 offset1:36
	s_waitcnt lgkmcnt(1)
	v_mfma_f32_16x16x32_bf16 v[12:15], v[48:51], v[32:35], v[12:15]
	ds_read2_b64 v[48:51], v146 offset0:64 offset1:68
	s_waitcnt lgkmcnt(1)
	v_mfma_f32_16x16x32_bf16 v[16:19], v[96:99], v[32:35], v[16:19]
	ds_read2_b64 v[96:99], v139 offset1:4
	s_waitcnt lgkmcnt(1)
	v_mfma_f32_16x16x32_bf16 v[20:23], v[48:51], v[32:35], v[20:23]
	ds_read2_b64 v[48:51], v144 offset0:128 offset1:132
	s_waitcnt lgkmcnt(1)
	v_mfma_f32_16x16x32_bf16 v[24:27], v[96:99], v[32:35], v[24:27]
	ds_read2_b64 v[96:99], v142 offset0:160 offset1:164
	s_waitcnt lgkmcnt(1)
	v_mfma_f32_16x16x32_bf16 v[48:51], v[48:51], v[32:35], v[52:55]
	s_nop 2
	ds_read2_b64 v[52:55], v143 offset0:192 offset1:196
	s_waitcnt lgkmcnt(1)
	v_mfma_f32_16x16x32_bf16 v[40:43], v[96:99], v[32:35], v[40:43]
	ds_read2_b64 v[96:99], v138 offset1:4
	s_waitcnt lgkmcnt(1)
	v_mfma_f32_16x16x32_bf16 v[52:55], v[52:55], v[32:35], v[60:63]
	s_nop 2
	ds_read2_b64 v[60:63], v141 offset1:4
	s_waitcnt lgkmcnt(1)
	v_mfma_f32_16x16x32_bf16 v[56:59], v[96:99], v[32:35], v[56:59]
	ds_read2_b64 v[96:99], v140 offset0:32 offset1:36
	s_waitcnt lgkmcnt(1)
	v_mfma_f32_16x16x32_bf16 v[60:63], v[60:63], v[32:35], v[72:75]
	s_nop 2
	ds_read2_b64 v[72:75], v135 offset0:64 offset1:68
	s_waitcnt lgkmcnt(1)
	v_mfma_f32_16x16x32_bf16 v[76:79], v[96:99], v[32:35], v[76:79]
	ds_read2_b64 v[96:99], v137 offset1:4
	s_waitcnt lgkmcnt(1)
	v_mfma_f32_16x16x32_bf16 v[72:75], v[72:75], v[32:35], v[80:83]
	s_nop 2
	ds_read2_b64 v[80:83], v132 offset0:128 offset1:132
	s_waitcnt lgkmcnt(1)
	v_mfma_f32_16x16x32_bf16 v[84:87], v[96:99], v[32:35], v[84:87]
	ds_read2_b64 v[96:99], v133 offset0:160 offset1:164
	s_waitcnt lgkmcnt(1)
	v_mfma_f32_16x16x32_bf16 v[68:71], v[80:83], v[32:35], v[68:71]
	ds_read2_b64 v[80:83], v134 offset0:192 offset1:196
	s_waitcnt lgkmcnt(1)
	v_mfma_f32_16x16x32_bf16 v[28:31], v[96:99], v[32:35], v[28:31]
	ds_read2_b64 v[96:99], v136 offset1:4
	s_waitcnt lgkmcnt(1)
	v_mfma_f32_16x16x32_bf16 v[64:67], v[80:83], v[32:35], v[64:67]
	ds_read2_b64 v[80:83], v173 offset0:8 offset1:12
	s_waitcnt lgkmcnt(1)
	v_mfma_f32_16x16x32_bf16 v[32:35], v[96:99], v[32:35], v[36:39]
	s_nop 2
	ds_read2_b64 v[36:39], v145 offset0:40 offset1:44
	s_waitcnt lgkmcnt(1)
	v_mfma_f32_16x16x32_bf16 v[12:15], v[80:83], v[8:11], v[12:15]
	ds_read2_b64 v[80:83], v146 offset0:72 offset1:76
	s_waitcnt lgkmcnt(1)
	v_mfma_f32_16x16x32_bf16 v[16:19], v[36:39], v[8:11], v[16:19]
	ds_read2_b64 v[36:39], v139 offset0:8 offset1:12
	s_waitcnt lgkmcnt(1)
	v_mfma_f32_16x16x32_bf16 v[20:23], v[80:83], v[8:11], v[20:23]
	ds_read2_b64 v[80:83], v144 offset0:136 offset1:140
	s_waitcnt lgkmcnt(1)
	v_mfma_f32_16x16x32_bf16 v[24:27], v[36:39], v[8:11], v[24:27]
	ds_read2_b64 v[36:39], v142 offset0:168 offset1:172
	s_waitcnt lgkmcnt(1)
	v_mfma_f32_16x16x32_bf16 v[48:51], v[80:83], v[8:11], v[48:51]
	ds_read2_b64 v[80:83], v143 offset0:200 offset1:204
	s_waitcnt lgkmcnt(1)
	v_mfma_f32_16x16x32_bf16 v[36:39], v[36:39], v[8:11], v[40:43]
	s_nop 2
	ds_read2_b64 v[40:43], v138 offset0:8 offset1:12
	s_waitcnt lgkmcnt(1)
	v_mfma_f32_16x16x32_bf16 v[52:55], v[80:83], v[8:11], v[52:55]
	ds_read2_b64 v[80:83], v141 offset0:8 offset1:12
	s_waitcnt lgkmcnt(1)
	v_mfma_f32_16x16x32_bf16 v[40:43], v[40:43], v[8:11], v[56:59]
	s_nop 2
	ds_read2_b64 v[56:59], v140 offset0:40 offset1:44
	s_waitcnt lgkmcnt(1)
	v_mfma_f32_16x16x32_bf16 v[60:63], v[80:83], v[8:11], v[60:63]
	ds_read2_b64 v[80:83], v135 offset0:72 offset1:76
	s_waitcnt lgkmcnt(1)
	v_mfma_f32_16x16x32_bf16 v[56:59], v[56:59], v[8:11], v[76:79]
	s_nop 2
	ds_read2_b64 v[76:79], v137 offset0:8 offset1:12
	s_waitcnt lgkmcnt(1)
	v_mfma_f32_16x16x32_bf16 v[72:75], v[80:83], v[8:11], v[72:75]
	ds_read2_b64 v[80:83], v132 offset0:136 offset1:140
	ds_read2_b64 v[96:99], v133 offset0:168 offset1:172
	s_waitcnt lgkmcnt(2)
	v_mfma_f32_16x16x32_bf16 v[76:79], v[76:79], v[8:11], v[84:87]
	s_nop 2
	ds_read2_b64 v[84:87], v134 offset0:200 offset1:204
	ds_read2_b64 v[104:107], v136 offset0:8 offset1:12
	s_waitcnt vmcnt(3)
	ds_write_b128 v184, v[44:47] offset:36864
	s_waitcnt vmcnt(2)
	ds_write_b128 v176, v[88:91] offset:36864
	s_waitcnt vmcnt(1)
	ds_write_b128 v177, v[100:103] offset:36864
	s_waitcnt vmcnt(0)
	ds_write_b128 v178, v[92:95] offset:36864
	s_waitcnt lgkmcnt(7)
	v_mfma_f32_16x16x32_bf16 v[44:47], v[80:83], v[8:11], v[68:71]
	s_waitcnt lgkmcnt(0)
	s_barrier
; #define LAS __attribute__((address_space(3)))
; __device__ __forceinline__ unsigned pk2(float lo, float hi) { f32x2_t v = {lo, hi}; bf16x2_t b = __builtin_convertvector(v, bf16x2_t); return __builtin_bit_cast(unsigned, b); }
; __device__ __forceinline__ f32x4 mfma16(bf16x8 a, bf16x8 b, f32x4 c) { return __builtin_amdgcn_mfma_f32_16x16x32_bf16(a, b, c, 0, 0, 0); }
; __device__ __forceinline__ void xattn_unit(const Args& a, LAS unsigned char* lds, int b, int h, int qb, int tid, int wave, int lane) {
;     ...
;         } else {
;             const int mt = j - 4;
; #pragma unroll
;             for (int dt = 0; dt < 16; ++dt) {
;                 const LAS bf16* vr = base + (16 * dt + fr) * VS + 4 * fq;
;                 O[dt] = mfma16(cat8(*(const LAS u32x2*)vr, *(const LAS u32x2*)(vr + 16)), pf[2 * mt], O[dt]);
;                 O[dt] = mfma16(cat8(*(const LAS u32x2*)(vr + 32), *(const LAS u32x2*)(vr + 48)), pf[2 * mt + 1], O[dt]);
;             }
;         }
;         if (j < 7) lstore(j + 1);
;         __syncthreads();
;     }
;     const float il = 1.f / l;
; #pragma unroll
;     for (int dt = 0; dt < 16; ++dt) { u32x2 w; w.x = pk2(O[dt][0] * il, O[dt][1] * il); w.y = pk2(O[dt][2] * il, O[dt][3] * il);
	v_mfma_f32_16x16x32_bf16 v[28:31], v[96:99], v[8:11], v[28:31]
	ds_read2_b64 v[68:71], v131 offset1:4
	v_mfma_f32_16x16x32_bf16 v[64:67], v[84:87], v[8:11], v[64:67]
	v_mfma_f32_16x16x32_bf16 v[8:11], v[104:107], v[8:11], v[32:35]
	s_nop 2
	ds_read2_b64 v[32:35], v129 offset0:32 offset1:36
	s_waitcnt lgkmcnt(1)
	v_mfma_f32_16x16x32_bf16 v[12:15], v[68:71], v[4:7], v[12:15]
	ds_read2_b64 v[68:71], v130 offset0:64 offset1:68
	s_waitcnt lgkmcnt(1)
	v_mfma_f32_16x16x32_bf16 v[16:19], v[32:35], v[4:7], v[16:19]
	ds_read2_b64 v[32:35], v128 offset1:4
	s_waitcnt lgkmcnt(1)
	v_mfma_f32_16x16x32_bf16 v[20:23], v[68:71], v[4:7], v[20:23]
	ds_read2_b64 v[68:71], v126 offset0:128 offset1:132
	s_waitcnt lgkmcnt(1)
	v_mfma_f32_16x16x32_bf16 v[24:27], v[32:35], v[4:7], v[24:27]
	ds_read2_b64 v[32:35], v127 offset0:160 offset1:164
	s_waitcnt lgkmcnt(1)
	v_mfma_f32_16x16x32_bf16 v[48:51], v[68:71], v[4:7], v[48:51]
	ds_read2_b64 v[68:71], v125 offset0:192 offset1:196
	s_waitcnt lgkmcnt(1)
	v_mfma_f32_16x16x32_bf16 v[32:35], v[32:35], v[4:7], v[36:39]
	s_nop 2
	ds_read2_b64 v[36:39], v124 offset1:4
	s_waitcnt lgkmcnt(1)
	v_mfma_f32_16x16x32_bf16 v[52:55], v[68:71], v[4:7], v[52:55]
	ds_read2_b64 v[68:71], v119 offset1:4
	s_waitcnt lgkmcnt(1)
	v_mfma_f32_16x16x32_bf16 v[36:39], v[36:39], v[4:7], v[40:43]
	s_nop 2
	ds_read2_b64 v[40:43], v118 offset0:32 offset1:36
	s_waitcnt lgkmcnt(1)
	v_mfma_f32_16x16x32_bf16 v[60:63], v[68:71], v[4:7], v[60:63]
	ds_read2_b64 v[68:71], v116 offset0:64 offset1:68
	s_waitcnt lgkmcnt(1)
	v_mfma_f32_16x16x32_bf16 v[40:43], v[40:43], v[4:7], v[56:59]
	s_nop 2
	ds_read2_b64 v[56:59], v117 offset1:4
	s_waitcnt lgkmcnt(1)
	v_mfma_f32_16x16x32_bf16 v[68:71], v[68:71], v[4:7], v[72:75]
	s_nop 2
	ds_read2_b64 v[72:75], v111 offset0:128 offset1:132
	s_waitcnt lgkmcnt(1)
	v_mfma_f32_16x16x32_bf16 v[56:59], v[56:59], v[4:7], v[76:79]
	s_nop 2
	ds_read2_b64 v[76:79], v113 offset0:160 offset1:164
	s_waitcnt lgkmcnt(1)
	v_mfma_f32_16x16x32_bf16 v[44:47], v[72:75], v[4:7], v[44:47]
	ds_read2_b64 v[72:75], v112 offset0:192 offset1:196
	s_waitcnt lgkmcnt(1)
	v_mfma_f32_16x16x32_bf16 v[28:31], v[76:79], v[4:7], v[28:31]
	ds_read2_b64 v[76:79], v110 offset1:4
	s_waitcnt lgkmcnt(1)
	v_mfma_f32_16x16x32_bf16 v[64:67], v[72:75], v[4:7], v[64:67]
	ds_read2_b64 v[72:75], v131 offset0:8 offset1:12
	s_waitcnt lgkmcnt(1)
	v_mfma_f32_16x16x32_bf16 v[4:7], v[76:79], v[4:7], v[8:11]
	s_nop 2
	ds_read2_b64 v[8:11], v129 offset0:40 offset1:44
	s_waitcnt lgkmcnt(1)
	v_mfma_f32_16x16x32_bf16 v[12:15], v[72:75], v[0:3], v[12:15]
	ds_read2_b64 v[72:75], v130 offset0:72 offset1:76
	s_waitcnt lgkmcnt(1)
	v_mfma_f32_16x16x32_bf16 v[8:11], v[8:11], v[0:3], v[16:19]
	s_nop 2
	ds_read2_b64 v[16:19], v128 offset0:8 offset1:12
	s_waitcnt lgkmcnt(1)
	v_mfma_f32_16x16x32_bf16 v[20:23], v[72:75], v[0:3], v[20:23]
	ds_read2_b64 v[72:75], v126 offset0:136 offset1:140
	s_nop 0
	v_pk_mul_f32 v[8:9], v[114:115], v[8:9] op_sel_hi:[0,1]
	v_pk_mul_f32 v[10:11], v[114:115], v[10:11] op_sel_hi:[0,1]
	s_waitcnt lgkmcnt(1)
	v_mfma_f32_16x16x32_bf16 v[16:19], v[16:19], v[0:3], v[24:27]
	s_nop 2
	ds_read2_b64 v[24:27], v127 offset0:168 offset1:172
	s_waitcnt lgkmcnt(1)
	v_mfma_f32_16x16x32_bf16 v[48:51], v[72:75], v[0:3], v[48:51]
	ds_read2_b64 v[72:75], v125 offset0:200 offset1:204
	s_nop 0
	v_pk_mul_f32 v[16:17], v[114:115], v[16:17] op_sel_hi:[0,1]
	v_pk_mul_f32 v[18:19], v[114:115], v[18:19] op_sel_hi:[0,1]
	s_waitcnt lgkmcnt(1)
	v_mfma_f32_16x16x32_bf16 v[24:27], v[24:27], v[0:3], v[32:35]
	s_nop 2
	ds_read2_b64 v[32:35], v124 offset0:8 offset1:12
	s_waitcnt lgkmcnt(1)
	v_mfma_f32_16x16x32_bf16 v[52:55], v[72:75], v[0:3], v[52:55]
	ds_read2_b64 v[72:75], v119 offset0:8 offset1:12
	s_nop 0
	v_pk_mul_f32 v[24:25], v[114:115], v[24:25] op_sel_hi:[0,1]
	v_pk_mul_f32 v[26:27], v[114:115], v[26:27] op_sel_hi:[0,1]
	s_waitcnt lgkmcnt(1)
	v_mfma_f32_16x16x32_bf16 v[32:35], v[32:35], v[0:3], v[36:39]
	s_nop 2
	ds_read2_b64 v[36:39], v118 offset0:40 offset1:44
	s_waitcnt lgkmcnt(1)
	v_mfma_f32_16x16x32_bf16 v[60:63], v[72:75], v[0:3], v[60:63]
	ds_read2_b64 v[72:75], v116 offset0:72 offset1:76
	s_nop 0
	v_pk_mul_f32 v[32:33], v[114:115], v[32:33] op_sel_hi:[0,1]
	v_pk_mul_f32 v[34:35], v[114:115], v[34:35] op_sel_hi:[0,1]
	s_waitcnt lgkmcnt(1)
	v_mfma_f32_16x16x32_bf16 v[36:39], v[36:39], v[0:3], v[40:43]
	s_nop 2
	ds_read2_b64 v[40:43], v117 offset0:8 offset1:12
	s_waitcnt lgkmcnt(1)
	v_mfma_f32_16x16x32_bf16 v[68:71], v[72:75], v[0:3], v[68:71]
	ds_read2_b64 v[72:75], v111 offset0:136 offset1:140
	s_nop 0
	v_pk_mul_f32 v[36:37], v[114:115], v[36:37] op_sel_hi:[0,1]
	v_pk_mul_f32 v[38:39], v[114:115], v[38:39] op_sel_hi:[0,1]
	s_waitcnt lgkmcnt(1)
	v_mfma_f32_16x16x32_bf16 v[40:43], v[40:43], v[0:3], v[56:59]
	s_nop 2
	ds_read2_b64 v[56:59], v113 offset0:168 offset1:172
	s_waitcnt lgkmcnt(1)
	v_mfma_f32_16x16x32_bf16 v[44:47], v[72:75], v[0:3], v[44:47]
	ds_read2_b64 v[72:75], v112 offset0:200 offset1:204
	s_nop 0
	v_pk_mul_f32 v[40:41], v[114:115], v[40:41] op_sel_hi:[0,1]
	v_pk_mul_f32 v[42:43], v[114:115], v[42:43] op_sel_hi:[0,1]
	s_waitcnt lgkmcnt(1)
	v_mfma_f32_16x16x32_bf16 v[28:31], v[56:59], v[0:3], v[28:31]
	ds_read2_b64 v[56:59], v110 offset0:8 offset1:12
	s_nop 0
	v_pk_mul_f32 v[44:45], v[114:115], v[44:45] op_sel_hi:[0,1]
	v_pk_mul_f32 v[46:47], v[114:115], v[46:47] op_sel_hi:[0,1]
	s_waitcnt lgkmcnt(1)
	v_mfma_f32_16x16x32_bf16 v[64:67], v[72:75], v[0:3], v[64:67]
	s_nop 1
	v_mul_f32_e64 v28, v114, v28
	v_mul_f32_e64 v29, v114, v29
	v_pk_mul_f32 v[30:31], v[114:115], v[30:31] op_sel_hi:[0,1]
	s_waitcnt lgkmcnt(0)
	v_mfma_f32_16x16x32_bf16 v[0:3], v[56:59], v[0:3], v[4:7]
	v_mul_f32_e64 v56, v114, v68
	v_mul_f32_e64 v57, v114, v69
	s_nop 0
	v_pk_mul_f32 v[4:5], v[114:115], v[12:13] op_sel_hi:[0,1]
	v_pk_mul_f32 v[6:7], v[114:115], v[14:15] op_sel_hi:[0,1]
	v_pk_mul_f32 v[12:13], v[114:115], v[20:21] op_sel_hi:[0,1]
	v_pk_mul_f32 v[14:15], v[114:115], v[22:23] op_sel_hi:[0,1]
	v_pk_mul_f32 v[20:21], v[114:115], v[48:49] op_sel_hi:[0,1]
	v_pk_mul_f32 v[22:23], v[114:115], v[50:51] op_sel_hi:[0,1]
	v_pk_mul_f32 v[48:49], v[114:115], v[52:53] op_sel_hi:[0,1]
	v_pk_mul_f32 v[50:51], v[114:115], v[54:55] op_sel_hi:[0,1]
	v_pk_mul_f32 v[52:53], v[114:115], v[60:61] op_sel_hi:[0,1]
	v_pk_mul_f32 v[54:55], v[114:115], v[62:63] op_sel_hi:[0,1]
	v_pk_mul_f32 v[58:59], v[114:115], v[70:71] op_sel_hi:[0,1]
	v_pk_mul_f32 v[60:61], v[114:115], v[64:65] op_sel_hi:[0,1]
	v_pk_mul_f32 v[62:63], v[114:115], v[66:67] op_sel_hi:[0,1]
	v_pk_mul_f32 v[0:1], v[114:115], v[0:1] op_sel_hi:[0,1]
	v_pk_mul_f32 v[2:3], v[114:115], v[2:3] op_sel_hi:[0,1]
	v_cvt_pk_bf16_f32 v4, v4, v5
	v_cvt_pk_bf16_f32 v5, v6, v7
	s_barrier
; #define GAS __attribute__((address_space(1)))
; __device__ __forceinline__ unsigned pk2(float lo, float hi) { f32x2_t v = {lo, hi}; bf16x2_t b = __builtin_convertvector(v, bf16x2_t); return __builtin_bit_cast(unsigned, b); }
; __device__ __forceinline__ void xattn_unit(const Args& a, LAS unsigned char* lds, int b, int h, int qb, int tid, int wave, int lane) {
;     ...
;     const float il = 1.f / l;
; #pragma unroll
;     for (int dt = 0; dt < 16; ++dt) { u32x2 w; w.x = pk2(O[dt][0] * il, O[dt][1] * il); w.y = pk2(O[dt][2] * il, O[dt][3] * il);
;         *(GAS u32x2*)(XO + qrow * DM + h * 256 + 16 * dt + 4 * fq) = w; }
	v_cvt_pk_bf16_f32 v6, v8, v9
	v_cvt_pk_bf16_f32 v7, v10, v11
	v_cvt_pk_bf16_f32 v8, v12, v13
	v_cvt_pk_bf16_f32 v9, v14, v15
	v_cvt_pk_bf16_f32 v10, v16, v17
	v_cvt_pk_bf16_f32 v11, v18, v19
	v_cvt_pk_bf16_f32 v12, v20, v21
	v_cvt_pk_bf16_f32 v13, v22, v23
	v_cvt_pk_bf16_f32 v14, v24, v25
	v_cvt_pk_bf16_f32 v15, v26, v27
	v_cvt_pk_bf16_f32 v16, v48, v49
	v_cvt_pk_bf16_f32 v17, v50, v51
	v_cvt_pk_bf16_f32 v18, v32, v33
	v_cvt_pk_bf16_f32 v19, v34, v35
	v_cvt_pk_bf16_f32 v20, v52, v53
	v_cvt_pk_bf16_f32 v21, v54, v55
	v_cvt_pk_bf16_f32 v22, v36, v37
	v_cvt_pk_bf16_f32 v23, v38, v39
	v_cvt_pk_bf16_f32 v24, v56, v57
	v_cvt_pk_bf16_f32 v25, v58, v59
	v_cvt_pk_bf16_f32 v26, v40, v41
	v_cvt_pk_bf16_f32 v27, v42, v43
	v_cvt_pk_bf16_f32 v36, v44, v45
	v_cvt_pk_bf16_f32 v37, v46, v47
	v_cvt_pk_bf16_f32 v38, v28, v29
	v_cvt_pk_bf16_f32 v39, v30, v31
	v_cvt_pk_bf16_f32 v40, v60, v61
	v_cvt_pk_bf16_f32 v41, v62, v63
	v_cvt_pk_bf16_f32 v42, v0, v1
	v_cvt_pk_bf16_f32 v43, v2, v3
	v_bfe_u32 v44, v252, 4, 1
	v_mul_u32_u24_e32 v44, 24, v44
	v_mov_b32_e32 v45, 0
	v_lshl_add_u64 v[44:45], v[108:109], 0, v[44:45]
	v_permlane16_swap_b32_e32 v4, v6
	v_permlane16_swap_b32_e32 v5, v7
	v_permlane16_swap_b32_e32 v8, v10
	v_permlane16_swap_b32_e32 v9, v11
	v_permlane16_swap_b32_e32 v12, v14
	v_permlane16_swap_b32_e32 v13, v15
	v_permlane16_swap_b32_e32 v16, v18
	v_permlane16_swap_b32_e32 v17, v19
	v_permlane16_swap_b32_e32 v20, v22
	v_permlane16_swap_b32_e32 v21, v23
	v_permlane16_swap_b32_e32 v24, v26
	v_permlane16_swap_b32_e32 v25, v27
	v_permlane16_swap_b32_e32 v36, v38
	v_permlane16_swap_b32_e32 v37, v39
	v_permlane16_swap_b32_e32 v40, v42
	v_permlane16_swap_b32_e32 v41, v43
	global_store_dwordx4 v[44:45], v[4:7], off
	global_store_dwordx4 v[44:45], v[8:11], off offset:64
	global_store_dwordx4 v[44:45], v[12:15], off offset:128
	global_store_dwordx4 v[44:45], v[16:19], off offset:192
	global_store_dwordx4 v[44:45], v[20:23], off offset:256
	global_store_dwordx4 v[44:45], v[24:27], off offset:320
	global_store_dwordx4 v[44:45], v[36:39], off offset:384
	global_store_dwordx4 v[44:45], v[40:43], off offset:448
	s_cbranch_scc1 .LBB0_1513

; __device__ __forceinline__ void xattn_unit(const Args& a, LAS unsigned char* lds, int b, int h, int qb, int tid, int wave, int lane) {
;     ...
;     const int fr = lane & 15, fq = lane >> 4; const size_t qrow = (size_t)b * SEQ + qb * 128 + 16 * wave + fr;
;     bf16x8 qf[8];
; #pragma unroll
;     for (int kk = 0; kk < 8; ++kk) qf[kk] = *(const GAS bf16x8*)(QX + qrow * DM + h * 256 + 32 * kk + 8 * fq);
;     u32x4 rr[2][4];
;     const unsigned vok = (unsigned)((tid >> 5) * DM + 8 * (tid & 31)) * 2u, vov = (unsigned)((tid >> 3) * MEMR + 8 * (tid & 7)) * 2u;
;     const GAS char* kxb = (const GAS char*)KX + ((size_t)b * 256 * DM + h * 256) * 2; const GAS char* vxb = (const GAS char*)VTX + ((size_t)h * 256 * MEMR + b * 256) * 2;
;     auto gload = [&](int j) {
;         if (j < 4) { const GAS char* p_ = kxb + (size_t)j * (64 * DM * 2);
; #pragma unroll
;             for (int i = 0; i < 4; ++i) rr[j & 1][i] = *(const GAS u32x4*)(p_ + (size_t)(vok + (unsigned)(i * 16 * DM * 2)));
;         } else { const GAS char* p_ = vxb + (size_t)(j - 4) * 128;
; #pragma unroll
;             for (int i = 0; i < 4; ++i) rr[j & 1][i] = *(const GAS u32x4*)(p_ + (size_t)(vov + (unsigned)(i * 64 * MEMR * 2)));
;         }
;     };
;     auto lstore = [&](int j) {
;         LAS bf16* base = (LAS bf16*)(lds + (j & 1) * STG);
;         if (j < 4) {
; #pragma unroll
;             for (int i = 0; i < 4; ++i) { const int id = tid + 512 * i; *(LAS u32x4*)(base + (id >> 5) * KS + 8 * (id & 31)) = rr[j & 1][i]; }
;         } else {
; #pragma unroll
;             for (int i = 0; i < 4; ++i) { const int id = tid + 512 * i; *(LAS u32x4*)(base + (id >> 3) * VS + 8 * (id & 7)) = rr[j & 1][i]; }
;         }
;     };
;     f32x4 S[16]; bf16x8 pf[8]; f32x4 O[16]; float l = 0.f;
; #pragma unroll
;     for (int i = 0; i < 16; ++i) { S[i] = (f32x4){0.f, 0.f, 0.f, 0.f}; O[i] = (f32x4){0.f, 0.f, 0.f, 0.f}; }
;     gload(0); gload(1); lstore(0); __syncthreads();
; #pragma unroll
; __global__ void __launch_bounds__(512, 2) mk_fwd(Args a) {
;     ...
;     if ((G & 7) == 0) { const int x = vb & 7, r = vb >> 3, nr = G >> 3;
;         const int per = (128 + nr - 1) / nr;
;         for (int w = r * per; w < 128 && w < (r + 1) * per; ++w) { int tu = threadIdx.x; asm volatile("" : "+v"(tu)); const int pr = x * 8 + (w >> 4); xattn_unit(a6, lds, pr >> 2, pr & 3, w & 15, tu, wave, tu & 63); } }
.LBB0_1518:
	s_ashr_i32 s0, s10, 4
	s_and_b32 s6, s17, 0x780
	s_add_i32 s7, s0, s12
	v_mov_b32_e32 v200, v252
	s_and_b32 s23, s0, 3
	s_add_i32 s0, s6, s70
	s_ashr_i32 s6, s7, 2
	s_ashr_i32 s7, s6, 31
	v_lshlrev_b32_e32 v192, 4, v200
	v_add_u32_e32 v216, 0x200, v200
	v_lshlrev_b32_e32 v2, 6, v200
	v_and_b32_e32 v4, 0x1f0, v192
	v_ashrrev_i32_e32 v5, 5, v216
	s_lshl_b64 s[8:9], s[6:7], 11
	v_and_b32_e32 v213, 15, v200
	v_and_or_b32 v193, v2, s18, v4
	v_mul_lo_u32 v2, v5, s20
	s_add_u32 s0, s8, s0
	v_add3_u32 v212, 0, v2, v4
	s_addc_u32 s24, s9, 0
	v_or_b32_e32 v2, s0, v213
	s_lshl_b32 s0, s23, 9
	s_lshl_b64 s[8:9], s[6:7], 19
	v_ashrrev_i32_e32 v3, 5, v200
	v_add_u32_e32 v217, 0x400, v200
	s_add_u32 s8, s13, s8
	v_mul_lo_u32 v3, v3, s20
	v_ashrrev_i32_e32 v6, 5, v217
	s_addc_u32 s9, s14, s9
	s_lshl_b32 s6, s6, 8
	v_add3_u32 v211, 0, v3, v4
	v_mul_lo_u32 v3, v6, s20
	s_lshl_b32 s7, s23, 20
	s_ashr_i32 s23, s6, 31
	v_add3_u32 v224, 0, v3, v4
	v_mov_b32_e32 v3, s24
	s_add_u32 s6, s6, s7
	v_lshlrev_b64 v[202:203], 11, v[2:3]
	s_addc_u32 s7, s23, 0
	v_add_u32_e32 v218, 0x600, v200
	v_lshl_add_u64 v[2:3], s[2:3], 0, v[202:203]
	s_lshl_b64 s[6:7], s[6:7], 1
	v_mov_b32_e32 v1, v201
	v_and_b32_e32 v214, 63, v200
	v_and_b32_e32 v0, 48, v200
	v_ashrrev_i32_e32 v7, 5, v218
	v_lshl_add_u64 v[2:3], v[2:3], 0, s[0:1]
	s_add_u32 s8, s8, s0
	v_add_u32_e32 v8, 0, v0
	v_or_b32_e32 v215, 48, v214
	v_mul_lo_u32 v5, v7, s20
	v_lshl_add_u64 v[12:13], v[2:3], 0, v[0:1]
	s_addc_u32 s9, s9, 0
	v_mad_u32_u24 v210, v213, s20, v8
	v_mad_u32_u24 v209, v215, s20, v8
	v_add_u32_e32 v194, 0x8000, v193
	v_add_u32_e32 v195, 0x10000, v193
	v_add_u32_e32 v196, 0x18000, v193
	v_add3_u32 v225, 0, v5, v4
	global_load_dwordx4 v[156:159], v[12:13], off
	global_load_dwordx4 v[120:123], v[12:13], off offset:64
	global_load_dwordx4 v[112:115], v[12:13], off offset:128
	global_load_dwordx4 v[104:107], v[12:13], off offset:192
	global_load_dwordx4 v[28:31], v[12:13], off offset:256
	global_load_dwordx4 v[8:11], v[12:13], off offset:320
	global_load_dwordx4 v[4:7], v[12:13], off offset:384
	global_load_dwordx4 v[0:3], v[12:13], off offset:448
	s_nop 0
	global_load_dwordx4 v[12:15], v193, s[8:9]
	global_load_dwordx4 v[16:19], v194, s[8:9]
	global_load_dwordx4 v[20:23], v195, s[8:9]
	global_load_dwordx4 v[24:27], v196, s[8:9]
	s_add_u32 s6, s15, s6
	s_addc_u32 s7, s16, s7
	s_add_u32 s24, s8, 0x20000
	s_addc_u32 s25, s9, 0
	global_load_dwordx4 v[32:35], v193, s[24:25]
	global_load_dwordx4 v[36:39], v194, s[24:25]
	global_load_dwordx4 v[40:43], v195, s[24:25]
	global_load_dwordx4 v[44:47], v196, s[24:25]
	s_add_u32 s24, s8, 0x40000
	s_addc_u32 s25, s9, 0
	s_add_u32 s8, s8, 0x60000
	s_addc_u32 s9, s9, 0
	v_and_b32_e32 v219, 0x70, v192
	v_lshrrev_b32_e32 v216, 3, v216
	v_cmp_lt_i32_e32 vcc, v227, v226
	s_add_i32 s10, s10, 1
	s_addk_i32 s17, 0x80
	s_cmp_ge_i32 s10, s11
	s_waitcnt vmcnt(0)
	ds_write_b128 v211, v[12:15]
	ds_write_b128 v212, v[16:19]
	ds_write_b128 v224, v[20:23]
	ds_write_b128 v225, v[24:27]
	s_waitcnt lgkmcnt(0)
	s_barrier
	global_load_dwordx4 v[12:15], v193, s[24:25]
	global_load_dwordx4 v[16:19], v194, s[24:25]
	global_load_dwordx4 v[20:23], v195, s[24:25]
	global_load_dwordx4 v[24:27], v196, s[24:25]
	ds_read_b128 v[48:51], v210
	ds_read_b128 v[52:55], v210 offset:64
	ds_read_b128 v[56:59], v210 offset:128
	ds_read_b128 v[60:63], v210 offset:192
	ds_read_b128 v[64:67], v210 offset:256
	ds_read_b128 v[68:71], v210 offset:320
	ds_read_b128 v[72:75], v210 offset:384
	ds_read_b128 v[76:79], v210 offset:448
	ds_read_b128 v[80:83], v210 offset:8448
	ds_read_b128 v[84:87], v210 offset:8512
	ds_read_b128 v[88:91], v210 offset:8576
	ds_read_b128 v[92:95], v210 offset:8640
	ds_read_b128 v[96:99], v210 offset:8704
	ds_read_b128 v[100:103], v210 offset:8768
	ds_read_b128 v[108:111], v210 offset:8832
	ds_read_b128 v[116:119], v210 offset:8896
	ds_read_b128 v[124:127], v210 offset:16896
	ds_read_b128 v[128:131], v210 offset:16960
	s_waitcnt lgkmcnt(14)
	v_mfma_f32_16x16x32_bf16 v[48:51], v[48:51], v[156:159], 0
	ds_read_b128 v[132:135], v210 offset:17024
	ds_read_b128 v[136:139], v210 offset:17088
	ds_read_b128 v[140:143], v209
	ds_read_b128 v[144:147], v210 offset:17152
	ds_read_b128 v[148:151], v210 offset:17216
	ds_read_b128 v[152:155], v210 offset:17280
	ds_read_b128 v[160:163], v210 offset:17344
	ds_read_b128 v[164:167], v209 offset:64
	ds_read_b128 v[168:171], v209 offset:128
	s_waitcnt lgkmcnt(14)
	v_mfma_f32_16x16x32_bf16 v[80:83], v[80:83], v[156:159], 0
	ds_read_b128 v[172:175], v209 offset:192
	ds_read_b128 v[176:179], v209 offset:256
	ds_read_b128 v[180:183], v209 offset:320
	s_waitcnt lgkmcnt(13)
	v_mfma_f32_16x16x32_bf16 v[124:127], v[124:127], v[156:159], 0
	v_mfma_f32_16x16x32_bf16 v[48:51], v[52:55], v[120:123], v[48:51]
	ds_read_b128 v[52:55], v209 offset:384
	ds_read_b128 v[184:187], v209 offset:448
	ds_write_b128 v211, v[32:35] offset:36864
	ds_write_b128 v212, v[36:39] offset:36864
	ds_write_b128 v224, v[40:43] offset:36864
	ds_write_b128 v225, v[44:47] offset:36864
	v_mfma_f32_16x16x32_bf16 v[32:35], v[84:87], v[120:123], v[80:83]
	s_waitcnt lgkmcnt(0)
	s_barrier
; #define LAS __attribute__((address_space(3)))
; #define GAS __attribute__((address_space(1)))
; __device__ __forceinline__ f32x4 mfma16(bf16x8 a, bf16x8 b, f32x4 c) { return __builtin_amdgcn_mfma_f32_16x16x32_bf16(a, b, c, 0, 0, 0); }
; __device__ __forceinline__ void xattn_unit(const Args& a, LAS unsigned char* lds, int b, int h, int qb, int tid, int wave, int lane) {
;     ...
;     auto gload = [&](int j) {
;         if (j < 4) { const GAS char* p_ = kxb + (size_t)j * (64 * DM * 2);
; #pragma unroll
;             for (int i = 0; i < 4; ++i) rr[j & 1][i] = *(const GAS u32x4*)(p_ + (size_t)(vok + (unsigned)(i * 16 * DM * 2)));
;         } else { const GAS char* p_ = vxb + (size_t)(j - 4) * 128;
; #pragma unroll
;             for (int i = 0; i < 4; ++i) rr[j & 1][i] = *(const GAS u32x4*)(p_ + (size_t)(vov + (unsigned)(i * 64 * MEMR * 2)));
;         }
;     };
;     auto lstore = [&](int j) {
;         LAS bf16* base = (LAS bf16*)(lds + (j & 1) * STG);
;         if (j < 4) {
; #pragma unroll
;             for (int i = 0; i < 4; ++i) { const int id = tid + 512 * i; *(LAS u32x4*)(base + (id >> 5) * KS + 8 * (id & 31)) = rr[j & 1][i]; }
;         } else {
; #pragma unroll
;             for (int i = 0; i < 4; ++i) { const int id = tid + 512 * i; *(LAS u32x4*)(base + (id >> 3) * VS + 8 * (id & 7)) = rr[j & 1][i]; }
;         }
;     };
;     f32x4 S[16]; bf16x8 pf[8]; f32x4 O[16]; float l = 0.f;
; #pragma unroll
;     for (int i = 0; i < 16; ++i) { S[i] = (f32x4){0.f, 0.f, 0.f, 0.f}; O[i] = (f32x4){0.f, 0.f, 0.f, 0.f}; }
;     gload(0); gload(1); lstore(0); __syncthreads();
; #pragma unroll
;     for (int j = 0; j < 8; ++j) {
;         if (j < 6) gload(j + 2);
;         const LAS bf16* base = (const LAS bf16*)(lds + (j & 1) * STG);
;         if (j < 4) {
; #pragma unroll
;             for (int rt = 0; rt < 4; ++rt)
; #pragma unroll
;                 for (int kk = 0; kk < 8; ++kk) S[4 * j + rt] = mfma16(*(const LAS bf16x8*)(base + (16 * rt + fr) * KS + 32 * kk + 8 * fq), qf[kk], S[4 * j + rt]);
	ds_read_b128 v[44:47], v210 offset:36864
	ds_read_b128 v[80:83], v210 offset:36928
	v_mfma_f32_16x16x32_bf16 v[140:143], v[140:143], v[156:159], 0
	v_mfma_f32_16x16x32_bf16 v[36:39], v[128:131], v[120:123], v[124:127]
	ds_read_b128 v[84:87], v210 offset:45312
	s_nop 1
	ds_read_b128 v[124:127], v210 offset:45376
	s_waitcnt lgkmcnt(3)
	v_mfma_f32_16x16x32_bf16 v[44:47], v[44:47], v[156:159], 0
	v_mfma_f32_16x16x32_bf16 v[48:51], v[56:59], v[112:115], v[48:51]
	v_mfma_f32_16x16x32_bf16 v[40:43], v[164:167], v[120:123], v[140:143]
	ds_read_b128 v[128:131], v210 offset:53760
	s_nop 1
	ds_read_b128 v[140:143], v210 offset:53824
	ds_read_b128 v[164:167], v209 offset:36864
	ds_read_b128 v[188:191], v209 offset:36928
	s_waitcnt lgkmcnt(5)
	v_mfma_f32_16x16x32_bf16 v[84:87], v[84:87], v[156:159], 0
	v_mfma_f32_16x16x32_bf16 v[32:35], v[88:91], v[112:115], v[32:35]
	v_mfma_f32_16x16x32_bf16 v[44:47], v[80:83], v[120:123], v[44:47]
	v_mfma_f32_16x16x32_bf16 v[48:51], v[60:63], v[104:107], v[48:51]
	ds_read_b128 v[60:63], v210 offset:36992
	ds_read_b128 v[88:91], v210 offset:37056
	s_waitcnt lgkmcnt(5)
	v_mfma_f32_16x16x32_bf16 v[128:131], v[128:131], v[156:159], 0
	v_mfma_f32_16x16x32_bf16 v[56:59], v[124:127], v[120:123], v[84:87]
	v_mfma_f32_16x16x32_bf16 v[32:35], v[92:95], v[104:107], v[32:35]
	s_waitcnt lgkmcnt(1)
	v_mfma_f32_16x16x32_bf16 v[44:47], v[60:63], v[112:115], v[44:47]
	ds_read_b128 v[60:63], v210 offset:45440
	ds_read_b128 v[92:95], v210 offset:45504
	v_mfma_f32_16x16x32_bf16 v[164:167], v[164:167], v[156:159], 0
	v_mfma_f32_16x16x32_bf16 v[80:83], v[140:143], v[120:123], v[128:131]
	s_waitcnt lgkmcnt(1)
	v_mfma_f32_16x16x32_bf16 v[56:59], v[60:63], v[112:115], v[56:59]
	ds_read_b128 v[60:63], v210 offset:53888
	ds_read_b128 v[124:127], v210 offset:53952
	v_mfma_f32_16x16x32_bf16 v[84:87], v[188:191], v[120:123], v[164:167]
	s_waitcnt lgkmcnt(1)
	v_mfma_f32_16x16x32_bf16 v[60:63], v[60:63], v[112:115], v[80:83]
	s_nop 2
	ds_read_b128 v[80:83], v209 offset:36992
	ds_read_b128 v[128:131], v209 offset:37056
	v_mfma_f32_16x16x32_bf16 v[40:43], v[168:171], v[112:115], v[40:43]
	s_waitcnt lgkmcnt(1)
	v_mfma_f32_16x16x32_bf16 v[80:83], v[80:83], v[112:115], v[84:87]
	v_mfma_f32_16x16x32_bf16 v[48:51], v[64:67], v[28:31], v[48:51]
	v_mfma_f32_16x16x32_bf16 v[40:43], v[172:175], v[104:107], v[40:43]
	v_mfma_f32_16x16x32_bf16 v[44:47], v[88:91], v[104:107], v[44:47]
	s_waitcnt lgkmcnt(0)
	v_mfma_f32_16x16x32_bf16 v[64:67], v[128:131], v[104:107], v[80:83]
	v_mfma_f32_16x16x32_bf16 v[48:51], v[68:71], v[8:11], v[48:51]
	ds_read_b128 v[68:71], v210 offset:37120
	s_nop 0
	ds_read_b128 v[80:83], v210 offset:37184
	v_mfma_f32_16x16x32_bf16 v[32:35], v[96:99], v[28:31], v[32:35]
	v_mfma_f32_16x16x32_bf16 v[40:43], v[176:179], v[28:31], v[40:43]
	v_mfma_f32_16x16x32_bf16 v[56:59], v[92:95], v[104:107], v[56:59]
	s_waitcnt lgkmcnt(1)
	v_mfma_f32_16x16x32_bf16 v[44:47], v[68:71], v[28:31], v[44:47]
	ds_read_b128 v[68:71], v210 offset:45568
	ds_read_b128 v[84:87], v210 offset:45632
	v_mfma_f32_16x16x32_bf16 v[36:39], v[132:135], v[112:115], v[36:39]
	v_mfma_f32_16x16x32_bf16 v[60:63], v[124:127], v[104:107], v[60:63]
	v_mfma_f32_16x16x32_bf16 v[32:35], v[100:103], v[8:11], v[32:35]
	v_mfma_f32_16x16x32_bf16 v[40:43], v[180:183], v[8:11], v[40:43]
	s_waitcnt lgkmcnt(1)
	v_mfma_f32_16x16x32_bf16 v[56:59], v[68:71], v[28:31], v[56:59]
	ds_read_b128 v[68:71], v210 offset:54016
	ds_read_b128 v[88:91], v210 offset:54080
	v_mfma_f32_16x16x32_bf16 v[36:39], v[136:139], v[104:107], v[36:39]
	s_waitcnt lgkmcnt(1)
	v_mfma_f32_16x16x32_bf16 v[60:63], v[68:71], v[28:31], v[60:63]
	ds_read_b128 v[68:71], v209 offset:37120
	ds_read_b128 v[92:95], v209 offset:37184
	v_mfma_f32_16x16x32_bf16 v[48:51], v[72:75], v[4:7], v[48:51]
	v_mfma_f32_16x16x32_bf16 v[32:35], v[108:111], v[4:7], v[32:35]
	v_mfma_f32_16x16x32_bf16 v[52:55], v[52:55], v[4:7], v[40:43]
	v_mfma_f32_16x16x32_bf16 v[36:39], v[144:147], v[28:31], v[36:39]
	s_waitcnt lgkmcnt(1)
	v_mfma_f32_16x16x32_bf16 v[64:67], v[68:71], v[28:31], v[64:67]
	v_mfma_f32_16x16x32_bf16 v[68:71], v[80:83], v[8:11], v[44:47]
	v_mfma_f32_16x16x32_bf16 v[44:47], v[76:79], v[0:3], v[48:51]
	v_mfma_f32_16x16x32_bf16 v[40:43], v[116:119], v[0:3], v[32:35]
	v_mfma_f32_16x16x32_bf16 v[32:35], v[184:187], v[0:3], v[52:55]
	s_nop 0
	ds_read_b128 v[48:51], v210 offset:37248
	s_nop 0
	ds_read_b128 v[52:55], v210 offset:37312
	v_mfma_f32_16x16x32_bf16 v[36:39], v[148:151], v[8:11], v[36:39]
	v_mfma_f32_16x16x32_bf16 v[56:59], v[84:87], v[8:11], v[56:59]
	v_lshlrev_b32_e32 v84, 10, v200
	v_and_or_b32 v205, v84, s19, v219
	v_add_u32_e32 v206, 0x80000, v205
	s_waitcnt lgkmcnt(1)
	v_mfma_f32_16x16x32_bf16 v[48:51], v[48:51], v[4:7], v[68:71]
	s_nop 2
	ds_read_b128 v[68:71], v210 offset:45696
	ds_read_b128 v[72:75], v210 offset:45760
	v_add_u32_e32 v207, 0x100000, v205
	v_add_u32_e32 v208, 0x180000, v205
	v_mfma_f32_16x16x32_bf16 v[36:39], v[152:155], v[4:7], v[36:39]
	v_mfma_f32_16x16x32_bf16 v[60:63], v[88:91], v[8:11], v[60:63]
	s_waitcnt lgkmcnt(1)
	v_mfma_f32_16x16x32_bf16 v[56:59], v[68:71], v[4:7], v[56:59]
	ds_read_b128 v[68:71], v210 offset:54144
	ds_read_b128 v[76:79], v210 offset:54208
	v_mfma_f32_16x16x32_bf16 v[36:39], v[160:163], v[0:3], v[36:39]
	s_waitcnt lgkmcnt(1)
	v_mfma_f32_16x16x32_bf16 v[60:63], v[68:71], v[4:7], v[60:63]
	ds_read_b128 v[68:71], v209 offset:37248
	ds_read_b128 v[80:83], v209 offset:37312
	global_load_dwordx4 v[160:163], v193, s[8:9]
	global_load_dwordx4 v[164:167], v194, s[8:9]
	global_load_dwordx4 v[168:171], v195, s[8:9]
	global_load_dwordx4 v[172:175], v196, s[8:9]
	v_mfma_f32_16x16x32_bf16 v[64:67], v[92:95], v[8:11], v[64:67]
	s_waitcnt vmcnt(7)
	ds_write_b128 v211, v[12:15]
	s_waitcnt vmcnt(6)
	ds_write_b128 v212, v[16:19]
	s_waitcnt vmcnt(5)
	ds_write_b128 v224, v[20:23]
	s_waitcnt vmcnt(4)
	ds_write_b128 v225, v[24:27]
	s_waitcnt lgkmcnt(0)
	s_barrier
; #define LAS __attribute__((address_space(3)))
; #define GAS __attribute__((address_space(1)))
; __device__ __forceinline__ f32x4 mfma16(bf16x8 a, bf16x8 b, f32x4 c) { return __builtin_amdgcn_mfma_f32_16x16x32_bf16(a, b, c, 0, 0, 0); }
; __device__ __forceinline__ void xattn_unit(const Args& a, LAS unsigned char* lds, int b, int h, int qb, int tid, int wave, int lane) {
;     ...
;     auto gload = [&](int j) {
;         if (j < 4) { const GAS char* p_ = kxb + (size_t)j * (64 * DM * 2);
; #pragma unroll
;             for (int i = 0; i < 4; ++i) rr[j & 1][i] = *(const GAS u32x4*)(p_ + (size_t)(vok + (unsigned)(i * 16 * DM * 2)));
;         } else { const GAS char* p_ = vxb + (size_t)(j - 4) * 128;
; #pragma unroll
;             for (int i = 0; i < 4; ++i) rr[j & 1][i] = *(const GAS u32x4*)(p_ + (size_t)(vov + (unsigned)(i * 64 * MEMR * 2)));
;         }
;     };
;     auto lstore = [&](int j) {
;         LAS bf16* base = (LAS bf16*)(lds + (j & 1) * STG);
;         if (j < 4) {
; #pragma unroll
;             for (int i = 0; i < 4; ++i) { const int id = tid + 512 * i; *(LAS u32x4*)(base + (id >> 5) * KS + 8 * (id & 31)) = rr[j & 1][i]; }
;         } else {
; #pragma unroll
;             for (int i = 0; i < 4; ++i) { const int id = tid + 512 * i; *(LAS u32x4*)(base + (id >> 3) * VS + 8 * (id & 7)) = rr[j & 1][i]; }
;         }
;     };
;     f32x4 S[16]; bf16x8 pf[8]; f32x4 O[16]; float l = 0.f;
; #pragma unroll
;     for (int i = 0; i < 16; ++i) { S[i] = (f32x4){0.f, 0.f, 0.f, 0.f}; O[i] = (f32x4){0.f, 0.f, 0.f, 0.f}; }
;     gload(0); gload(1); lstore(0); __syncthreads();
; #pragma unroll
;     for (int j = 0; j < 8; ++j) {
;         if (j < 6) gload(j + 2);
;         const LAS bf16* base = (const LAS bf16*)(lds + (j & 1) * STG);
;         if (j < 4) {
; #pragma unroll
;             for (int rt = 0; rt < 4; ++rt)
; #pragma unroll
;                 for (int kk = 0; kk < 8; ++kk) S[4 * j + rt] = mfma16(*(const LAS bf16x8*)(base + (16 * rt + fr) * KS + 32 * kk + 8 * fq), qf[kk], S[4 * j + rt]);
;             if (j == 3) {
;                 float mx = -3.0e38f;
; #pragma unroll
;                 for (int i = 0; i < 16; ++i) mx = fmaxf(mx, fmaxf(fmaxf(S[i][0], S[i][1]), fmaxf(S[i][2], S[i][3])));
	v_mfma_f32_16x16x32_bf16 v[64:67], v[68:71], v[4:7], v[64:67]
	global_load_dwordx4 v[12:15], v205, s[6:7]
	global_load_dwordx4 v[16:19], v206, s[6:7]
	global_load_dwordx4 v[20:23], v207, s[6:7]
	global_load_dwordx4 v[24:27], v208, s[6:7]
	v_mfma_f32_16x16x32_bf16 v[52:55], v[52:55], v[0:3], v[48:51]
	v_mfma_f32_16x16x32_bf16 v[56:59], v[72:75], v[0:3], v[56:59]
	v_mfma_f32_16x16x32_bf16 v[60:63], v[76:79], v[0:3], v[60:63]
	v_mfma_f32_16x16x32_bf16 v[48:51], v[80:83], v[0:3], v[64:67]
	ds_read_b128 v[76:79], v210
	ds_read_b128 v[84:87], v210 offset:64
	ds_read_b128 v[220:223], v210 offset:128
	ds_read_b128 v[132:135], v210 offset:192
	ds_read_b128 v[124:127], v210 offset:256
	ds_read_b128 v[116:119], v210 offset:320
	ds_read_b128 v[72:75], v210 offset:384
	ds_read_b128 v[64:67], v210 offset:448
	ds_read_b128 v[88:91], v210 offset:8448
	ds_read_b128 v[176:179], v210 offset:8512
	ds_read_b128 v[228:231], v210 offset:8576
	ds_read_b128 v[140:143], v210 offset:8640
	ds_read_b128 v[128:131], v210 offset:8704
	ds_read_b128 v[108:111], v210 offset:8768
	ds_read_b128 v[80:83], v210 offset:8832
	ds_read_b128 v[68:71], v210 offset:8896
	ds_read_b128 v[92:95], v210 offset:16896
	ds_read_b128 v[180:183], v210 offset:16960
	ds_read_b128 v[232:235], v210 offset:17024
	ds_read_b128 v[148:151], v210 offset:17088
	ds_read_b128 v[96:99], v209
	s_waitcnt lgkmcnt(14)
	v_mfma_f32_16x16x32_bf16 v[184:187], v[76:79], v[156:159], 0
	s_waitcnt lgkmcnt(12)
	v_mfma_f32_16x16x32_bf16 v[188:191], v[88:91], v[156:159], 0
	ds_read_b128 v[136:139], v210 offset:17152
	ds_read_b128 v[100:103], v210 offset:17216
	ds_read_b128 v[88:91], v210 offset:17280
	ds_read_b128 v[76:79], v210 offset:17344
	ds_read_b128 v[196:199], v209 offset:64
	ds_read_b128 v[236:239], v209 offset:128
	s_waitcnt lgkmcnt(6)
	v_mfma_f32_16x16x32_bf16 v[240:243], v[96:99], v[156:159], 0
	ds_read_b128 v[152:155], v209 offset:192
	ds_read_b128 v[144:147], v209 offset:256
	ds_read_b128 v[96:99], v209 offset:320
	v_mfma_f32_16x16x32_bf16 v[192:195], v[92:95], v[156:159], 0
	v_mfma_f32_16x16x32_bf16 v[244:247], v[84:87], v[120:123], v[184:187]
	ds_read_b128 v[92:95], v209 offset:384
	ds_read_b128 v[84:87], v209 offset:448
	s_waitcnt vmcnt(7)
	ds_write_b128 v211, v[160:163] offset:36864
	s_waitcnt vmcnt(6)
	ds_write_b128 v212, v[164:167] offset:36864
	s_waitcnt vmcnt(5)
	ds_write_b128 v224, v[168:171] offset:36864
	s_waitcnt vmcnt(4)
	ds_write_b128 v225, v[172:175] offset:36864
	s_waitcnt lgkmcnt(0)
	s_barrier
	v_mfma_f32_16x16x32_bf16 v[172:175], v[196:199], v[120:123], v[240:243]
	ds_read_b128 v[164:167], v210 offset:36864
	s_nop 1
	ds_read_b128 v[240:243], v210 offset:36928
	v_cndmask_b32_e32 v211, v253, v227, vcc
	v_lshlrev_b32_e32 v211, 2, v211
	s_waitcnt lgkmcnt(1)
	v_mfma_f32_16x16x32_bf16 v[248:251], v[164:167], v[156:159], 0
	ds_read_b128 v[164:167], v210 offset:45312
	ds_read_b128 v[184:187], v210 offset:45376
	v_cmp_lt_i32_e32 vcc, v204, v226
	v_mfma_f32_16x16x32_bf16 v[160:163], v[176:179], v[120:123], v[188:191]
	s_nop 0
	v_cndmask_b32_e32 v212, v253, v204, vcc
	v_lshlrev_b32_e32 v212, 2, v212
	v_mfma_f32_16x16x32_bf16 v[168:171], v[180:183], v[120:123], v[192:195]
	s_waitcnt lgkmcnt(1)
	v_mfma_f32_16x16x32_bf16 v[188:191], v[164:167], v[156:159], 0
	ds_read_b128 v[164:167], v210 offset:53760
	ds_read_b128 v[192:195], v210 offset:53824
	s_waitcnt lgkmcnt(1)
	v_mfma_f32_16x16x32_bf16 v[196:199], v[164:167], v[156:159], 0
	ds_read_b128 v[164:167], v209 offset:36864
	ds_read_b128 v[176:179], v209 offset:36928
	s_waitcnt lgkmcnt(1)
	v_mfma_f32_16x16x32_bf16 v[180:183], v[164:167], v[156:159], 0
	v_mfma_f32_16x16x32_bf16 v[164:167], v[220:223], v[112:115], v[244:247]
	v_lshrrev_b32_e32 v220, 1, v200
	v_lshrrev_b32_e32 v221, 3, v200
	v_and_b32_e32 v200, 24, v220
	v_mfma_f32_16x16x32_bf16 v[160:163], v[228:231], v[112:115], v[160:163]
	v_or_b32_e32 v222, 0x70, v214
	v_or_b32_e32 v223, 0xf0, v214
	v_mul_lo_u32 v220, v221, s22
	v_mfma_f32_16x16x32_bf16 v[156:159], v[232:235], v[112:115], v[168:171]
	v_mfma_f32_16x16x32_bf16 v[168:171], v[236:239], v[112:115], v[172:175]
	v_mfma_f32_16x16x32_bf16 v[184:187], v[184:187], v[120:123], v[188:191]
	v_mfma_f32_16x16x32_bf16 v[188:191], v[192:195], v[120:123], v[196:199]
	v_lshrrev_b32_e32 v192, 3, v217
	v_lshrrev_b32_e32 v193, 3, v218
	v_mfma_f32_16x16x32_bf16 v[172:175], v[240:243], v[120:123], v[248:251]
	s_waitcnt lgkmcnt(0)
	v_mfma_f32_16x16x32_bf16 v[120:123], v[176:179], v[120:123], v[180:183]
	v_mul_lo_u32 v178, v193, s22
	v_or_b32_e32 v177, 0xb0, v214
	v_add3_u32 v176, 0, v220, v219
	v_mfma_f32_16x16x32_bf16 v[132:135], v[132:135], v[104:107], v[164:167]
	s_nop 2
	v_mul_lo_u32 v164, v216, s22
	v_mul_lo_u32 v165, v192, s22
	v_mfma_f32_16x16x32_bf16 v[140:143], v[140:143], v[104:107], v[160:163]
	s_nop 2
	v_add3_u32 v160, 0, v164, v219
	v_add3_u32 v161, 0, v165, v219
	v_mfma_f32_16x16x32_bf16 v[164:167], v[148:151], v[104:107], v[156:159]
	v_add3_u32 v148, 0, v178, v219
	v_add_u32_e32 v162, 0, v200
	v_mad_u32_u24 v151, v215, s22, v162
	v_mfma_f32_16x16x32_bf16 v[168:171], v[152:155], v[104:107], v[168:171]
	ds_read_b128 v[152:155], v210 offset:36992
	ds_read_b128 v[178:181], v210 offset:37056
	v_mad_u32_u24 v156, v213, s22, v162
	v_mad_u32_u24 v150, v177, s22, v162
	s_waitcnt lgkmcnt(1)
	v_mfma_f32_16x16x32_bf16 v[172:175], v[152:155], v[112:115], v[172:175]
	ds_read_b128 v[152:155], v210 offset:45440
	ds_read_b128 v[192:195], v210 offset:45504
	v_mad_u32_u24 v149, v223, s22, v162
	v_add_u32_e32 v158, 0x2000, v156
	s_waitcnt lgkmcnt(1)
; #define LAS __attribute__((address_space(3)))
; __device__ __forceinline__ f32x4 mfma16(bf16x8 a, bf16x8 b, f32x4 c) { return __builtin_amdgcn_mfma_f32_16x16x32_bf16(a, b, c, 0, 0, 0); }
; __device__ __forceinline__ void xattn_unit(const Args& a, LAS unsigned char* lds, int b, int h, int qb, int tid, int wave, int lane) {
;     ...
;     for (int j = 0; j < 8; ++j) {
;         if (j < 6) gload(j + 2);
;         const LAS bf16* base = (const LAS bf16*)(lds + (j & 1) * STG);
;         if (j < 4) {
; #pragma unroll
;             for (int rt = 0; rt < 4; ++rt)
; #pragma unroll
;                 for (int kk = 0; kk < 8; ++kk) S[4 * j + rt] = mfma16(*(const LAS bf16x8*)(base + (16 * rt + fr) * KS + 32 * kk + 8 * fq), qf[kk], S[4 * j + rt]);
;             if (j == 3) {
;                 float mx = -3.0e38f;
; #pragma unroll
;                 for (int i = 0; i < 16; ++i) mx = fmaxf(mx, fmaxf(fmaxf(S[i][0], S[i][1]), fmaxf(S[i][2], S[i][3])));
;                 mx = fmaxf(mx, __shfl_xor(mx, 16)); mx = fmaxf(mx, __shfl_xor(mx, 32));
; #pragma unroll
;                 for (int i = 0; i < 16; ++i)
; #pragma unroll
;                     for (int k = 0; k < 4; ++k) { S[i][k] = __builtin_amdgcn_exp2f(S[i][k] - mx); l += S[i][k]; }
	v_mfma_f32_16x16x32_bf16 v[182:185], v[152:155], v[112:115], v[184:187]
	ds_read_b128 v[152:155], v210 offset:53888
	ds_read_b128 v[196:199], v210 offset:53952
	v_add_u32_e32 v159, 0x2800, v156
	v_add_u32_e32 v157, 0x3000, v156
	s_waitcnt lgkmcnt(1)
	v_mfma_f32_16x16x32_bf16 v[186:189], v[152:155], v[112:115], v[188:191]
	ds_read_b128 v[152:155], v209 offset:36992
	ds_read_b128 v[214:217], v209 offset:37056
	v_add_u32_e32 v163, 0x800, v156
	s_waitcnt lgkmcnt(1)
	v_mfma_f32_16x16x32_bf16 v[218:221], v[152:155], v[112:115], v[120:123]
	v_mad_u32_u24 v152, v222, s22, v162
	v_add_u32_e32 v162, 0x1000, v156
	v_add_u32_e32 v154, 0x4800, v156
	v_mfma_f32_16x16x32_bf16 v[228:231], v[124:127], v[28:31], v[132:135]
	v_add_u32_e32 v155, 0x5000, v156
	v_add_u32_e32 v153, 0x5800, v156
	v_mfma_f32_16x16x32_bf16 v[132:135], v[136:139], v[28:31], v[164:167]
	v_add_u32_e32 v139, 0x6800, v156
	v_lshl_add_u64 v[136:137], s[4:5], 0, v[202:203]
	v_add_u32_e32 v138, 0x9000, v156
	v_mfma_f32_16x16x32_bf16 v[112:115], v[144:147], v[28:31], v[168:171]
	v_add_u32_e32 v146, 0x7000, v156
	v_add_u32_e32 v144, 0x7800, v156
	v_add_u32_e32 v145, 0x9800, v156
	v_mfma_f32_16x16x32_bf16 v[140:143], v[128:131], v[28:31], v[140:143]
	v_add_u32_e32 v147, 0xa000, v156
	v_add_u32_e32 v164, 0x9000, v151
	v_add_u32_e32 v165, 0xb000, v156
	v_mfma_f32_16x16x32_bf16 v[120:123], v[178:181], v[104:107], v[172:175]
	v_add_u32_e32 v166, 0xb800, v156
	v_add_u32_e32 v167, 0xc000, v156
	v_add_u32_e32 v168, 0x9000, v152
	v_mfma_f32_16x16x32_bf16 v[100:103], v[100:103], v[8:11], v[132:135]
	v_add_u32_e32 v169, 0xd800, v156
	v_add_u32_e32 v170, 0xe000, v156
	v_add_u32_e32 v171, 0xe800, v156
	v_mfma_f32_16x16x32_bf16 v[96:99], v[96:99], v[8:11], v[112:115]
	s_nop 2
	ds_read_b128 v[112:115], v210 offset:37120
	ds_read_b128 v[132:135], v210 offset:37184
	v_add_u32_e32 v172, 0x9000, v150
	v_add_u32_e32 v173, 0xf800, v156
	v_mfma_f32_16x16x32_bf16 v[124:127], v[192:195], v[104:107], v[182:185]
	v_add_u32_e32 v177, 0x7000, v138
	v_add_u32_e32 v175, 0x7800, v138
	v_add_u32_e32 v174, 0x9000, v149
	v_mfma_f32_16x16x32_bf16 v[108:111], v[108:111], v[8:11], v[140:143]
	v_lshl_add_u64 v[136:137], v[136:137], 0, s[0:1]
	v_lshl_add_u64 v[136:137], v[136:137], 0, v[200:201]
	s_waitcnt lgkmcnt(1)
	v_mfma_f32_16x16x32_bf16 v[112:115], v[112:115], v[28:31], v[120:123]
	s_nop 2
	ds_read_b128 v[120:123], v210 offset:45568
	ds_read_b128 v[140:143], v210 offset:45632
	v_mfma_f32_16x16x32_bf16 v[128:131], v[196:199], v[104:107], v[186:189]
	s_waitcnt lgkmcnt(1)
	v_mfma_f32_16x16x32_bf16 v[120:123], v[120:123], v[28:31], v[124:127]
	s_nop 2
	ds_read_b128 v[124:127], v210 offset:54016
	ds_read_b128 v[178:181], v210 offset:54080
	v_mfma_f32_16x16x32_bf16 v[104:107], v[214:217], v[104:107], v[218:221]
	s_waitcnt lgkmcnt(1)
	v_mfma_f32_16x16x32_bf16 v[124:127], v[124:127], v[28:31], v[128:131]
	s_nop 2
	ds_read_b128 v[128:131], v209 offset:37120
	ds_read_b128 v[182:185], v209 offset:37184
	v_mfma_f32_16x16x32_bf16 v[116:119], v[116:119], v[8:11], v[228:231]
	s_waitcnt lgkmcnt(1)
	v_mfma_f32_16x16x32_bf16 v[28:31], v[128:131], v[28:31], v[104:107]
	s_nop 2
	v_max_f32_e32 v104, v47, v47
	v_max_f32_e32 v105, v46, v46
	v_max_f32_e32 v106, v43, v43
	v_max_f32_e32 v107, v42, v42
	v_mfma_f32_16x16x32_bf16 v[72:75], v[72:75], v[4:7], v[116:119]
	v_max_f32_e32 v104, v105, v104
	s_nop 1
	v_max_f32_e32 v116, v39, v39
	v_max_f32_e32 v117, v38, v38
	v_mfma_f32_16x16x32_bf16 v[80:83], v[80:83], v[4:7], v[108:111]
	s_nop 2
	v_max_f32_e32 v108, v35, v35
	v_max_f32_e32 v109, v34, v34
	v_mfma_f32_16x16x32_bf16 v[88:91], v[88:91], v[4:7], v[100:103]
	s_nop 2
	v_max_f32_e32 v100, v107, v106
	v_max_f32_e32 v101, v117, v116
	v_max_f32_e32 v102, v109, v108
	v_max3_f32 v103, v44, v45, v104
	v_max3_f32 v100, v40, v41, v100
	v_mfma_f32_16x16x32_bf16 v[92:95], v[92:95], v[4:7], v[96:99]
	v_max3_f32 v101, v36, v37, v101
	v_max3_f32 v102, v32, v33, v102
	v_max3_f32 v100, v103, s21, v100
	v_mfma_f32_16x16x32_bf16 v[96:99], v[132:135], v[8:11], v[112:115]
	v_max_f32_e32 v108, v55, v55
	v_max_f32_e32 v109, v54, v54
	v_max_f32_e32 v116, v62, v62
	v_max_f32_e32 v113, v59, v59
	v_max_f32_e32 v114, v58, v58
	v_max3_f32 v112, v100, v101, v102
	v_mfma_f32_16x16x32_bf16 v[100:103], v[140:143], v[8:11], v[120:123]
	v_max_f32_e32 v115, v63, v63
	v_mfma_f32_16x16x32_bf16 v[104:107], v[178:181], v[8:11], v[124:127]
	s_waitcnt lgkmcnt(0)
	v_mfma_f32_16x16x32_bf16 v[8:11], v[182:185], v[8:11], v[28:31]
	s_nop 2
	v_max_f32_e32 v28, v51, v51
	v_max_f32_e32 v29, v50, v50
	v_max_f32_e32 v30, v109, v108
	v_max_f32_e32 v31, v114, v113
	v_mfma_f32_16x16x32_bf16 v[108:111], v[64:67], v[0:3], v[72:75]
	v_max_f32_e32 v64, v116, v115
	v_max_f32_e32 v28, v29, v28
	v_max3_f32 v29, v52, v53, v30
	v_max3_f32 v30, v56, v57, v31
	v_max3_f32 v31, v60, v61, v64
	v_max3_f32 v28, v48, v49, v28
	v_max3_f32 v29, v112, v29, v30
	v_max3_f32 v116, v29, v31, v28
	ds_read_b128 v[28:31], v210 offset:37248
	ds_read_b128 v[72:75], v210 offset:37312
	v_mfma_f32_16x16x32_bf16 v[76:79], v[76:79], v[0:3], v[88:91]
	v_max_f32_e32 v117, v111, v111
	v_max_f32_e32 v118, v110, v110
	v_mfma_f32_16x16x32_bf16 v[84:87], v[84:87], v[0:3], v[92:95]
	s_waitcnt lgkmcnt(1)
	v_mfma_f32_16x16x32_bf16 v[88:91], v[28:31], v[4:7], v[96:99]
	ds_read_b128 v[28:31], v210 offset:45696
	ds_read_b128 v[92:95], v210 offset:45760
	s_waitcnt lgkmcnt(1)
	v_mfma_f32_16x16x32_bf16 v[96:99], v[28:31], v[4:7], v[100:103]
	ds_read_b128 v[28:31], v210 offset:54144
	s_nop 1
	ds_read_b128 v[100:103], v210 offset:54208
	s_waitcnt lgkmcnt(1)
	v_mfma_f32_16x16x32_bf16 v[104:107], v[28:31], v[4:7], v[104:107]
	ds_read_b128 v[28:31], v209 offset:37248
	ds_read_b128 v[112:115], v209 offset:37312
	v_mfma_f32_16x16x32_bf16 v[80:83], v[68:71], v[0:3], v[80:83]
	s_waitcnt lgkmcnt(1)
	v_mfma_f32_16x16x32_bf16 v[4:7], v[28:31], v[4:7], v[8:11]
	global_load_dwordx4 v[68:71], v205, s[6:7] offset:128
	global_load_dwordx4 v[28:31], v206, s[6:7] offset:128
	global_load_dwordx4 v[64:67], v207, s[6:7] offset:128
	v_mfma_f32_16x16x32_bf16 v[8:11], v[72:75], v[0:3], v[88:91]
	global_load_dwordx4 v[72:75], v208, s[6:7] offset:128
	s_waitcnt vmcnt(7)
	ds_write_b128 v176, v[12:15]
	s_waitcnt vmcnt(6)
	ds_write_b128 v160, v[16:19]
	s_waitcnt vmcnt(5)
	ds_write_b128 v161, v[20:23]
	s_waitcnt vmcnt(4)
	ds_write_b128 v148, v[24:27]
	s_waitcnt lgkmcnt(0)
	v_mfma_f32_16x16x32_bf16 v[88:91], v[92:95], v[0:3], v[96:99]
	s_barrier
; #define LAS __attribute__((address_space(3)))
; __device__ __forceinline__ f32x4 mfma16(bf16x8 a, bf16x8 b, f32x4 c) { return __builtin_amdgcn_mfma_f32_16x16x32_bf16(a, b, c, 0, 0, 0); }
; __device__ __forceinline__ bf16x8 pack8(f32x4 a, f32x4 b) { u32x4 w; w.x = pk2(a[0], a[1]); w.y = pk2(a[2], a[3]); w.z = pk2(b[0], b[1]); w.w = pk2(b[2], b[3]); return __builtin_bit_cast(bf16x8, w); }
; __device__ __forceinline__ void xattn_unit(const Args& a, LAS unsigned char* lds, int b, int h, int qb, int tid, int wave, int lane) {
;     ...
;             if (j == 3) {
;                 float mx = -3.0e38f;
; #pragma unroll
;                 for (int i = 0; i < 16; ++i) mx = fmaxf(mx, fmaxf(fmaxf(S[i][0], S[i][1]), fmaxf(S[i][2], S[i][3])));
;                 mx = fmaxf(mx, __shfl_xor(mx, 16)); mx = fmaxf(mx, __shfl_xor(mx, 32));
; #pragma unroll
;                 for (int i = 0; i < 16; ++i)
; #pragma unroll
;                     for (int k = 0; k < 4; ++k) { S[i][k] = __builtin_amdgcn_exp2f(S[i][k] - mx); l += S[i][k]; }
;                 l += __shfl_xor(l, 16); l += __shfl_xor(l, 32);
; #pragma unroll
;                 for (int c2 = 0; c2 < 8; ++c2) pf[c2] = pack8(S[2 * c2], S[2 * c2 + 1]);
;             }
;         } else {
;             const int mt = j - 4;
; #pragma unroll
;             for (int dt = 0; dt < 16; ++dt) {
;                 const LAS bf16* vr = base + (16 * dt + fr) * VS + 4 * fq;
;                 O[dt] = mfma16(cat8(*(const LAS u32x2*)vr, *(const LAS u32x2*)(vr + 16)), pf[2 * mt], O[dt]);
;                 O[dt] = mfma16(cat8(*(const LAS u32x2*)(vr + 32), *(const LAS u32x2*)(vr + 48)), pf[2 * mt + 1], O[dt]);
;             }
	ds_read2_b64 v[12:15], v156 offset1:4
	ds_read2_b64 v[16:19], v163 offset0:32 offset1:36
	v_max_f32_e32 v96, v83, v83
	v_max_f32_e32 v97, v82, v82
	v_max_f32_e32 v98, v79, v79
	v_mfma_f32_16x16x32_bf16 v[92:95], v[100:103], v[0:3], v[104:107]
	v_max_f32_e32 v99, v78, v78
	v_max_f32_e32 v100, v87, v87
	v_max_f32_e32 v101, v86, v86
	v_mfma_f32_16x16x32_bf16 v[0:3], v[112:115], v[0:3], v[4:7]
	ds_read2_b64 v[20:23], v162 offset0:64 offset1:68
	ds_read2_b64 v[24:27], v151 offset1:4
	ds_read2_b64 v[112:115], v156 offset0:8 offset1:12
	v_max_f32_e32 v4, v118, v117
	v_max_f32_e32 v5, v97, v96
	v_max_f32_e32 v6, v99, v98
	v_max_f32_e32 v7, v101, v100
	v_max3_f32 v4, v108, v109, v4
	v_max3_f32 v5, v80, v81, v5
	v_max3_f32 v6, v76, v77, v6
	v_max3_f32 v7, v84, v85, v7
	v_max3_f32 v4, v116, v4, v5
	v_max3_f32 v4, v4, v6, v7
	v_max_f32_e32 v5, v11, v11
	v_max_f32_e32 v6, v10, v10
	v_max_f32_e32 v7, v91, v91
	v_max_f32_e32 v96, v90, v90
	v_max_f32_e32 v97, v95, v95
	v_max_f32_e32 v98, v94, v94
	v_max_f32_e32 v99, v3, v3
	v_max_f32_e32 v100, v2, v2
	v_max_f32_e32 v5, v6, v5
	v_max_f32_e32 v6, v96, v7
	v_max_f32_e32 v7, v98, v97
	v_max_f32_e32 v96, v100, v99
	v_max3_f32 v5, v8, v9, v5
	v_max3_f32 v6, v88, v89, v6
	v_max3_f32 v7, v92, v93, v7
	v_max3_f32 v96, v0, v1, v96
	v_max3_f32 v4, v4, v5, v6
	v_max3_f32 v4, v4, v7, v96
	ds_bpermute_b32 v5, v211, v4
	s_waitcnt lgkmcnt(0)
	v_max_f32_e32 v5, v5, v5
	v_max_f32_e32 v4, v4, v5
	ds_bpermute_b32 v5, v212, v4
	s_waitcnt lgkmcnt(0)
	v_max_f32_e32 v5, v5, v5
	v_max_f32_e32 v4, v4, v5
	v_sub_f32_e32 v5, v44, v4
	v_sub_f32_e32 v6, v45, v4
	v_sub_f32_e32 v7, v46, v4
	v_sub_f32_e32 v44, v47, v4
	v_sub_f32_e32 v40, v40, v4
	v_sub_f32_e32 v41, v41, v4
	v_sub_f32_e32 v42, v42, v4
	v_sub_f32_e32 v43, v43, v4
	v_sub_f32_e32 v36, v36, v4
	v_sub_f32_e32 v37, v37, v4
	v_sub_f32_e32 v38, v38, v4
	v_sub_f32_e32 v39, v39, v4
	v_sub_f32_e32 v32, v32, v4
	v_sub_f32_e32 v33, v33, v4
	v_sub_f32_e32 v34, v34, v4
	v_sub_f32_e32 v35, v35, v4
	v_sub_f32_e32 v45, v52, v4
	v_sub_f32_e32 v46, v53, v4
	v_sub_f32_e32 v47, v54, v4
	v_sub_f32_e32 v52, v55, v4
	v_sub_f32_e32 v53, v56, v4
	v_sub_f32_e32 v54, v57, v4
	v_sub_f32_e32 v55, v58, v4
	v_sub_f32_e32 v56, v59, v4
	v_sub_f32_e32 v57, v60, v4
	v_sub_f32_e32 v58, v61, v4
	v_sub_f32_e32 v59, v62, v4
	v_sub_f32_e32 v60, v63, v4
	v_sub_f32_e32 v48, v48, v4
	v_sub_f32_e32 v49, v49, v4
	v_sub_f32_e32 v50, v50, v4
	v_sub_f32_e32 v51, v51, v4
	v_sub_f32_e32 v61, v108, v4
	v_sub_f32_e32 v62, v109, v4
	v_sub_f32_e32 v63, v110, v4
	v_sub_f32_e32 v96, v111, v4
	v_sub_f32_e32 v80, v80, v4
	v_sub_f32_e32 v81, v81, v4
	v_sub_f32_e32 v82, v82, v4
	v_sub_f32_e32 v83, v83, v4
	v_sub_f32_e32 v76, v76, v4
	v_sub_f32_e32 v77, v77, v4
	v_sub_f32_e32 v78, v78, v4
	v_sub_f32_e32 v79, v79, v4
	v_sub_f32_e32 v84, v84, v4
	v_sub_f32_e32 v85, v85, v4
	v_sub_f32_e32 v86, v86, v4
	v_sub_f32_e32 v87, v87, v4
	v_sub_f32_e32 v8, v8, v4
	v_sub_f32_e32 v9, v9, v4
	v_sub_f32_e32 v10, v10, v4
	v_sub_f32_e32 v11, v11, v4
	v_sub_f32_e32 v88, v88, v4
	v_sub_f32_e32 v89, v89, v4
	v_sub_f32_e32 v90, v90, v4
	v_sub_f32_e32 v91, v91, v4
	v_sub_f32_e32 v92, v92, v4
	v_sub_f32_e32 v93, v93, v4
	v_sub_f32_e32 v94, v94, v4
	v_sub_f32_e32 v95, v95, v4
	v_sub_f32_e32 v0, v0, v4
	v_sub_f32_e32 v1, v1, v4
	v_sub_f32_e32 v2, v2, v4
	v_sub_f32_e32 v3, v3, v4
	v_exp_f32_e32 v4, v5
	v_exp_f32_e32 v97, v6
	v_exp_f32_e32 v98, v7
	v_exp_f32_e32 v99, v44
	v_exp_f32_e32 v100, v40
	v_exp_f32_e32 v189, v52
	v_add_f32_e32 v52, 0, v4
	v_exp_f32_e32 v101, v41
	v_add_f32_e32 v52, v97, v52
	v_exp_f32_e32 v102, v42
	v_add_f32_e32 v52, v98, v52
	v_exp_f32_e32 v103, v43
	v_add_f32_e32 v52, v99, v52
	v_exp_f32_e32 v104, v36
	v_add_f32_e32 v52, v100, v52
	v_exp_f32_e32 v105, v37
	v_add_f32_e32 v52, v101, v52
	v_exp_f32_e32 v106, v38
	v_exp_f32_e32 v120, v39
	v_add_f32_e32 v52, v102, v52
	v_add_f32_e32 v52, v103, v52
	v_add_f32_e32 v52, v104, v52
	v_add_f32_e32 v52, v105, v52
	v_exp_f32_e32 v190, v53
	v_exp_f32_e32 v191, v54
	v_exp_f32_e32 v192, v55
	v_exp_f32_e32 v193, v56
	v_exp_f32_e32 v194, v57
	v_exp_f32_e32 v195, v58
	v_exp_f32_e32 v196, v59
	v_exp_f32_e32 v197, v60
	v_exp_f32_e32 v203, v61
	v_exp_f32_e32 v209, v62
	v_exp_f32_e32 v210, v63
	v_exp_f32_e32 v213, v96
	v_exp_f32_e32 v214, v80
	v_exp_f32_e32 v215, v81
	v_exp_f32_e32 v216, v82
	v_exp_f32_e32 v217, v83
	v_exp_f32_e32 v218, v76
	v_exp_f32_e32 v219, v77
	v_exp_f32_e32 v220, v78
	v_exp_f32_e32 v221, v79
	v_exp_f32_e32 v222, v84
	v_exp_f32_e32 v223, v85
	v_exp_f32_e32 v224, v86
	v_exp_f32_e32 v225, v87
	v_exp_f32_e32 v232, v88
	v_exp_f32_e32 v233, v89
	v_exp_f32_e32 v234, v90
	v_exp_f32_e32 v235, v91
	v_exp_f32_e32 v236, v92
	v_exp_f32_e32 v237, v93
	v_exp_f32_e32 v238, v94
	v_exp_f32_e32 v239, v95
	v_cvt_pk_bf16_f32 v36, v4, v97
	v_cvt_pk_bf16_f32 v37, v98, v99
	v_cvt_pk_bf16_f32 v38, v100, v101
	v_cvt_pk_bf16_f32 v39, v102, v103
	v_cvt_pk_bf16_f32 v40, v104, v105
	v_cvt_pk_bf16_f32 v41, v106, v120
	v_add_f32_e32 v121, v106, v52
	ds_read2_b64 v[52:55], v158 offset0:128 offset1:132
	ds_read2_b64 v[56:59], v159 offset0:160 offset1:164
	ds_read2_b64 v[60:63], v157 offset0:192 offset1:196
	ds_read2_b64 v[76:79], v152 offset1:4
	ds_read2_b64 v[80:83], v154 offset1:4
	ds_read2_b64 v[84:87], v155 offset0:32 offset1:36
	ds_read2_b64 v[88:91], v153 offset0:64 offset1:68
	ds_read2_b64 v[92:95], v150 offset1:4
	ds_read2_b64 v[96:99], v139 offset0:128 offset1:132
	ds_read2_b64 v[100:103], v146 offset0:160 offset1:164
	ds_read2_b64 v[104:107], v144 offset0:192 offset1:196
	ds_read2_b64 v[108:111], v149 offset1:4
	v_exp_f32_e32 v182, v32
	v_exp_f32_e32 v183, v33
	v_exp_f32_e32 v184, v34
	v_exp_f32_e32 v185, v35
	v_mfma_f32_16x16x32_bf16 v[12:15], v[12:15], v[36:39], 0
	v_cvt_pk_bf16_f32 v42, v182, v183
	v_add_f32_e32 v244, v120, v121
	v_cvt_pk_bf16_f32 v43, v184, v185
	v_mfma_f32_16x16x32_bf16 v[16:19], v[16:19], v[36:39], 0
	v_exp_f32_e32 v186, v45
	v_exp_f32_e32 v187, v46
	v_exp_f32_e32 v188, v47
	v_mfma_f32_16x16x32_bf16 v[20:23], v[20:23], v[36:39], 0
	v_cvt_pk_bf16_f32 v46, v190, v191
	v_cvt_pk_bf16_f32 v44, v186, v187
	v_cvt_pk_bf16_f32 v45, v188, v189
	v_mfma_f32_16x16x32_bf16 v[24:27], v[24:27], v[36:39], 0
	v_cvt_pk_bf16_f32 v47, v192, v193
	v_exp_f32_e32 v198, v48
	v_exp_f32_e32 v199, v49
	s_waitcnt lgkmcnt(11)
; #define LAS __attribute__((address_space(3)))
; __device__ __forceinline__ f32x4 mfma16(bf16x8 a, bf16x8 b, f32x4 c) { return __builtin_amdgcn_mfma_f32_16x16x32_bf16(a, b, c, 0, 0, 0); }
; __device__ __forceinline__ void xattn_unit(const Args& a, LAS unsigned char* lds, int b, int h, int qb, int tid, int wave, int lane) {
;     ...
;         } else {
;             const int mt = j - 4;
; #pragma unroll
;             for (int dt = 0; dt < 16; ++dt) {
;                 const LAS bf16* vr = base + (16 * dt + fr) * VS + 4 * fq;
;                 O[dt] = mfma16(cat8(*(const LAS u32x2*)vr, *(const LAS u32x2*)(vr + 16)), pf[2 * mt], O[dt]);
;                 O[dt] = mfma16(cat8(*(const LAS u32x2*)(vr + 32), *(const LAS u32x2*)(vr + 48)), pf[2 * mt + 1], O[dt]);
;             }
;         }
;         if (j < 7) lstore(j + 1);
;         __syncthreads();
	v_mfma_f32_16x16x32_bf16 v[52:55], v[52:55], v[36:39], 0
	v_exp_f32_e32 v200, v50
	v_exp_f32_e32 v202, v51
	v_cvt_pk_bf16_f32 v48, v194, v195
	s_waitcnt lgkmcnt(10)
	v_mfma_f32_16x16x32_bf16 v[56:59], v[56:59], v[36:39], 0
	v_cvt_pk_bf16_f32 v49, v196, v197
	v_cvt_pk_bf16_f32 v50, v198, v199
	v_cvt_pk_bf16_f32 v51, v200, v202
	s_waitcnt lgkmcnt(9)
	v_mfma_f32_16x16x32_bf16 v[60:63], v[60:63], v[36:39], 0
	v_add_f32_e32 v182, v182, v244
	v_exp_f32_e32 v228, v8
	v_exp_f32_e32 v229, v9
	s_waitcnt lgkmcnt(8)
	v_mfma_f32_16x16x32_bf16 v[76:79], v[76:79], v[36:39], 0
	v_exp_f32_e32 v230, v10
	v_exp_f32_e32 v231, v11
	v_exp_f32_e32 v240, v0
	s_waitcnt lgkmcnt(7)
	v_mfma_f32_16x16x32_bf16 v[80:83], v[80:83], v[36:39], 0
	v_exp_f32_e32 v241, v1
	v_exp_f32_e32 v242, v2
	v_exp_f32_e32 v243, v3
	s_waitcnt lgkmcnt(6)
	v_mfma_f32_16x16x32_bf16 v[84:87], v[84:87], v[36:39], 0
	v_cvt_pk_bf16_f32 v32, v203, v209
	v_cvt_pk_bf16_f32 v33, v210, v213
	v_cvt_pk_bf16_f32 v34, v214, v215
	s_waitcnt lgkmcnt(5)
	v_mfma_f32_16x16x32_bf16 v[88:91], v[88:91], v[36:39], 0
	v_cvt_pk_bf16_f32 v35, v216, v217
	v_cvt_pk_bf16_f32 v8, v218, v219
	v_cvt_pk_bf16_f32 v9, v220, v221
	s_waitcnt lgkmcnt(4)
	v_mfma_f32_16x16x32_bf16 v[92:95], v[92:95], v[36:39], 0
	v_cvt_pk_bf16_f32 v10, v222, v223
	v_cvt_pk_bf16_f32 v11, v224, v225
	v_cvt_pk_bf16_f32 v4, v228, v229
	s_waitcnt lgkmcnt(3)
	v_mfma_f32_16x16x32_bf16 v[96:99], v[96:99], v[36:39], 0
	v_cvt_pk_bf16_f32 v5, v230, v231
	v_cvt_pk_bf16_f32 v6, v232, v233
	v_cvt_pk_bf16_f32 v7, v234, v235
	s_waitcnt lgkmcnt(2)
	v_mfma_f32_16x16x32_bf16 v[100:103], v[100:103], v[36:39], 0
	v_cvt_pk_bf16_f32 v0, v236, v237
	v_cvt_pk_bf16_f32 v1, v238, v239
	v_cvt_pk_bf16_f32 v2, v240, v241
	s_waitcnt lgkmcnt(1)
	v_mfma_f32_16x16x32_bf16 v[104:107], v[104:107], v[36:39], 0
	v_cvt_pk_bf16_f32 v3, v242, v243
	s_waitcnt lgkmcnt(0)
	v_mfma_f32_16x16x32_bf16 v[36:39], v[108:111], v[36:39], 0
	ds_read2_b64 v[108:111], v163 offset0:40 offset1:44
	v_mfma_f32_16x16x32_bf16 v[12:15], v[112:115], v[40:43], v[12:15]
	ds_read2_b64 v[112:115], v162 offset0:72 offset1:76
	s_waitcnt lgkmcnt(1)
	v_mfma_f32_16x16x32_bf16 v[16:19], v[108:111], v[40:43], v[16:19]
	ds_read2_b64 v[108:111], v151 offset0:8 offset1:12
	s_waitcnt lgkmcnt(1)
	v_mfma_f32_16x16x32_bf16 v[20:23], v[112:115], v[40:43], v[20:23]
	ds_read2_b64 v[112:115], v158 offset0:136 offset1:140
	s_waitcnt lgkmcnt(1)
	v_mfma_f32_16x16x32_bf16 v[24:27], v[108:111], v[40:43], v[24:27]
	ds_read2_b64 v[108:111], v159 offset0:168 offset1:172
	s_waitcnt lgkmcnt(1)
	v_mfma_f32_16x16x32_bf16 v[52:55], v[112:115], v[40:43], v[52:55]
	ds_read2_b64 v[112:115], v157 offset0:200 offset1:204
	s_waitcnt lgkmcnt(1)
	v_mfma_f32_16x16x32_bf16 v[56:59], v[108:111], v[40:43], v[56:59]
	ds_read2_b64 v[108:111], v152 offset0:8 offset1:12
	s_waitcnt lgkmcnt(1)
	v_mfma_f32_16x16x32_bf16 v[60:63], v[112:115], v[40:43], v[60:63]
	ds_read2_b64 v[112:115], v154 offset0:8 offset1:12
	ds_read2_b64 v[116:119], v155 offset0:40 offset1:44
	ds_read2_b64 v[120:123], v153 offset0:72 offset1:76
	s_waitcnt lgkmcnt(3)
	v_mfma_f32_16x16x32_bf16 v[76:79], v[108:111], v[40:43], v[76:79]
	global_load_dwordx4 v[108:111], v205, s[6:7] offset:256
	s_waitcnt lgkmcnt(2)
	v_mfma_f32_16x16x32_bf16 v[80:83], v[112:115], v[40:43], v[80:83]
	global_load_dwordx4 v[112:115], v206, s[6:7] offset:256
	global_load_dwordx4 v[124:127], v207, s[6:7] offset:256
	ds_read2_b64 v[128:131], v150 offset0:8 offset1:12
	s_waitcnt lgkmcnt(2)
	v_mfma_f32_16x16x32_bf16 v[84:87], v[116:119], v[40:43], v[84:87]
	global_load_dwordx4 v[116:119], v208, s[6:7] offset:256
	ds_read2_b64 v[132:135], v139 offset0:136 offset1:140
	ds_read2_b64 v[140:143], v146 offset0:168 offset1:172
	s_waitcnt lgkmcnt(3)
	v_mfma_f32_16x16x32_bf16 v[88:91], v[120:123], v[40:43], v[88:91]
	ds_read2_b64 v[120:123], v144 offset0:200 offset1:204
	ds_read2_b64 v[178:181], v149 offset0:8 offset1:12
	s_waitcnt vmcnt(7)
	ds_write_b128 v176, v[68:71] offset:36864
	s_waitcnt vmcnt(6)
	ds_write_b128 v160, v[28:31] offset:36864
	s_waitcnt vmcnt(5)
	ds_write_b128 v161, v[64:67] offset:36864
	s_waitcnt vmcnt(4)
	ds_write_b128 v148, v[72:75] offset:36864
	s_waitcnt lgkmcnt(0)
	s_barrier
	ds_read2_b64 v[72:75], v138 offset1:4
	v_mfma_f32_16x16x32_bf16 v[92:95], v[128:131], v[40:43], v[92:95]
	v_add_f32_e32 v128, v183, v182
	v_add_f32_e32 v128, v184, v128
	v_mfma_f32_16x16x32_bf16 v[68:71], v[132:135], v[40:43], v[96:99]
	v_mfma_f32_16x16x32_bf16 v[28:31], v[140:143], v[40:43], v[100:103]
	v_mfma_f32_16x16x32_bf16 v[64:67], v[120:123], v[40:43], v[104:107]
	v_mfma_f32_16x16x32_bf16 v[36:39], v[178:181], v[40:43], v[36:39]
	ds_read2_b64 v[40:43], v145 offset0:32 offset1:36
	v_add_f32_e32 v178, v185, v128
	v_add_f32_e32 v178, v186, v178
	s_waitcnt lgkmcnt(1)
	v_mfma_f32_16x16x32_bf16 v[12:15], v[72:75], v[44:47], v[12:15]
	ds_read2_b64 v[72:75], v147 offset0:64 offset1:68
	v_add_f32_e32 v178, v187, v178
	s_waitcnt lgkmcnt(1)
	v_mfma_f32_16x16x32_bf16 v[16:19], v[40:43], v[44:47], v[16:19]
	ds_read2_b64 v[40:43], v164 offset1:4
	s_waitcnt lgkmcnt(1)
	v_mfma_f32_16x16x32_bf16 v[20:23], v[72:75], v[44:47], v[20:23]
	ds_read2_b64 v[72:75], v165 offset0:128 offset1:132
	s_waitcnt lgkmcnt(1)
	v_mfma_f32_16x16x32_bf16 v[24:27], v[40:43], v[44:47], v[24:27]
	ds_read2_b64 v[40:43], v166 offset0:160 offset1:164
	s_waitcnt lgkmcnt(1)
	v_mfma_f32_16x16x32_bf16 v[52:55], v[72:75], v[44:47], v[52:55]
	ds_read2_b64 v[72:75], v167 offset0:192 offset1:196
	s_waitcnt lgkmcnt(1)
	v_mfma_f32_16x16x32_bf16 v[40:43], v[40:43], v[44:47], v[56:59]
	s_nop 2
	ds_read2_b64 v[56:59], v168 offset1:4
	s_waitcnt lgkmcnt(1)
; #define LAS __attribute__((address_space(3)))
; __device__ __forceinline__ f32x4 mfma16(bf16x8 a, bf16x8 b, f32x4 c) { return __builtin_amdgcn_mfma_f32_16x16x32_bf16(a, b, c, 0, 0, 0); }
; __device__ __forceinline__ bf16x8 pack8(f32x4 a, f32x4 b) { u32x4 w; w.x = pk2(a[0], a[1]); w.y = pk2(a[2], a[3]); w.z = pk2(b[0], b[1]); w.w = pk2(b[2], b[3]); return __builtin_bit_cast(bf16x8, w); }
; __device__ __forceinline__ void xattn_unit(const Args& a, LAS unsigned char* lds, int b, int h, int qb, int tid, int wave, int lane) {
;     ...
;                 l += __shfl_xor(l, 16); l += __shfl_xor(l, 32);
; #pragma unroll
;                 for (int c2 = 0; c2 < 8; ++c2) pf[c2] = pack8(S[2 * c2], S[2 * c2 + 1]);
;             }
;         } else {
;             const int mt = j - 4;
; #pragma unroll
;             for (int dt = 0; dt < 16; ++dt) {
;                 const LAS bf16* vr = base + (16 * dt + fr) * VS + 4 * fq;
;                 O[dt] = mfma16(cat8(*(const LAS u32x2*)vr, *(const LAS u32x2*)(vr + 16)), pf[2 * mt], O[dt]);
;                 O[dt] = mfma16(cat8(*(const LAS u32x2*)(vr + 32), *(const LAS u32x2*)(vr + 48)), pf[2 * mt + 1], O[dt]);
;             }
;         }
;         if (j < 7) lstore(j + 1);
;         __syncthreads();
;     }
;     const float il = 1.f / l;
	v_mfma_f32_16x16x32_bf16 v[60:63], v[72:75], v[44:47], v[60:63]
	ds_read2_b64 v[72:75], v169 offset1:4
	s_waitcnt lgkmcnt(1)
	v_mfma_f32_16x16x32_bf16 v[56:59], v[56:59], v[44:47], v[76:79]
	s_nop 2
	ds_read2_b64 v[76:79], v170 offset0:32 offset1:36
	s_waitcnt lgkmcnt(1)
	v_mfma_f32_16x16x32_bf16 v[72:75], v[72:75], v[44:47], v[80:83]
	s_nop 2
	ds_read2_b64 v[80:83], v171 offset0:64 offset1:68
	s_waitcnt lgkmcnt(1)
	v_mfma_f32_16x16x32_bf16 v[76:79], v[76:79], v[44:47], v[84:87]
	s_nop 2
	ds_read2_b64 v[84:87], v172 offset1:4
	s_waitcnt lgkmcnt(1)
	v_mfma_f32_16x16x32_bf16 v[80:83], v[80:83], v[44:47], v[88:91]
	s_nop 2
	ds_read2_b64 v[88:91], v173 offset0:128 offset1:132
	s_waitcnt lgkmcnt(1)
	v_mfma_f32_16x16x32_bf16 v[84:87], v[84:87], v[44:47], v[92:95]
	s_nop 2
	ds_read2_b64 v[92:95], v177 offset0:160 offset1:164
	s_waitcnt lgkmcnt(1)
	v_mfma_f32_16x16x32_bf16 v[68:71], v[88:91], v[44:47], v[68:71]
	ds_read2_b64 v[88:91], v175 offset0:192 offset1:196
	s_waitcnt lgkmcnt(1)
	v_mfma_f32_16x16x32_bf16 v[28:31], v[92:95], v[44:47], v[28:31]
	ds_read2_b64 v[92:95], v174 offset1:4
	s_waitcnt lgkmcnt(1)
	v_mfma_f32_16x16x32_bf16 v[64:67], v[88:91], v[44:47], v[64:67]
	ds_read2_b64 v[88:91], v138 offset0:8 offset1:12
	s_waitcnt lgkmcnt(1)
	v_mfma_f32_16x16x32_bf16 v[36:39], v[92:95], v[44:47], v[36:39]
	ds_read2_b64 v[44:47], v145 offset0:40 offset1:44
	s_waitcnt lgkmcnt(1)
	v_mfma_f32_16x16x32_bf16 v[12:15], v[88:91], v[48:51], v[12:15]
	ds_read2_b64 v[88:91], v147 offset0:72 offset1:76
	s_waitcnt lgkmcnt(1)
	v_mfma_f32_16x16x32_bf16 v[16:19], v[44:47], v[48:51], v[16:19]
	ds_read2_b64 v[44:47], v164 offset0:8 offset1:12
	s_waitcnt lgkmcnt(1)
	v_mfma_f32_16x16x32_bf16 v[20:23], v[88:91], v[48:51], v[20:23]
	ds_read2_b64 v[88:91], v165 offset0:136 offset1:140
	s_waitcnt lgkmcnt(1)
	v_mfma_f32_16x16x32_bf16 v[24:27], v[44:47], v[48:51], v[24:27]
	ds_read2_b64 v[44:47], v166 offset0:168 offset1:172
	s_waitcnt lgkmcnt(1)
	v_mfma_f32_16x16x32_bf16 v[52:55], v[88:91], v[48:51], v[52:55]
	ds_read2_b64 v[88:91], v167 offset0:200 offset1:204
	ds_read2_b64 v[92:95], v168 offset0:8 offset1:12
	ds_read2_b64 v[96:99], v169 offset0:8 offset1:12
	s_waitcnt lgkmcnt(3)
	v_mfma_f32_16x16x32_bf16 v[40:43], v[44:47], v[48:51], v[40:43]
	global_load_dwordx4 v[44:47], v205, s[6:7] offset:384
	s_waitcnt lgkmcnt(2)
	v_mfma_f32_16x16x32_bf16 v[60:63], v[88:91], v[48:51], v[60:63]
	global_load_dwordx4 v[88:91], v206, s[6:7] offset:384
	global_load_dwordx4 v[100:103], v207, s[6:7] offset:384
	ds_read2_b64 v[104:107], v170 offset0:40 offset1:44
	s_waitcnt lgkmcnt(2)
	v_mfma_f32_16x16x32_bf16 v[56:59], v[92:95], v[48:51], v[56:59]
	global_load_dwordx4 v[92:95], v208, s[6:7] offset:384
	ds_read2_b64 v[120:123], v171 offset0:72 offset1:76
	ds_read2_b64 v[128:131], v172 offset0:8 offset1:12
	s_waitcnt lgkmcnt(1)
	v_mfma_f32_16x16x32_bf16 v[80:83], v[120:123], v[48:51], v[80:83]
	v_add_f32_e32 v120, v188, v178
	v_add_f32_e32 v120, v189, v120
	v_add_f32_e32 v120, v190, v120
	v_mfma_f32_16x16x32_bf16 v[72:75], v[96:99], v[48:51], v[72:75]
	ds_read2_b64 v[96:99], v173 offset0:136 offset1:140
	ds_read2_b64 v[132:135], v177 offset0:168 offset1:172
	ds_read2_b64 v[140:143], v175 offset0:200 offset1:204
	v_add_f32_e32 v120, v191, v120
	v_add_f32_e32 v120, v192, v120
	v_add_f32_e32 v120, v193, v120
	v_mfma_f32_16x16x32_bf16 v[76:79], v[104:107], v[48:51], v[76:79]
	ds_read2_b64 v[104:107], v174 offset0:8 offset1:12
	s_waitcnt vmcnt(7)
	ds_write_b128 v176, v[108:111]
	s_waitcnt vmcnt(6)
	ds_write_b128 v160, v[112:115]
	s_waitcnt vmcnt(5)
	ds_write_b128 v161, v[124:127]
	s_waitcnt vmcnt(4)
	ds_write_b128 v148, v[116:119]
	s_waitcnt lgkmcnt(0)
	v_mfma_f32_16x16x32_bf16 v[68:71], v[96:99], v[48:51], v[68:71]
	v_add_f32_e32 v96, v194, v120
	v_add_f32_e32 v96, v195, v96
	v_add_f32_e32 v96, v196, v96
	v_add_f32_e32 v96, v197, v96
	v_add_f32_e32 v96, v198, v96
	v_add_f32_e32 v96, v199, v96
	v_add_f32_e32 v96, v200, v96
	v_add_f32_e32 v96, v202, v96
	v_add_f32_e32 v96, v203, v96
	v_mfma_f32_16x16x32_bf16 v[84:87], v[128:131], v[48:51], v[84:87]
	s_barrier
	v_mfma_f32_16x16x32_bf16 v[28:31], v[132:135], v[48:51], v[28:31]
	v_mfma_f32_16x16x32_bf16 v[64:67], v[140:143], v[48:51], v[64:67]
	v_mfma_f32_16x16x32_bf16 v[36:39], v[104:107], v[48:51], v[36:39]
	v_add_f32_e32 v48, v209, v96
	v_add_f32_e32 v48, v210, v48
	v_add_f32_e32 v48, v213, v48
	v_add_f32_e32 v48, v214, v48
	v_add_f32_e32 v48, v215, v48
	v_add_f32_e32 v48, v216, v48
	v_add_f32_e32 v48, v217, v48
	v_add_f32_e32 v48, v218, v48
	v_add_f32_e32 v48, v219, v48
	v_add_f32_e32 v48, v220, v48
	v_add_f32_e32 v48, v221, v48
	v_add_f32_e32 v48, v222, v48
	v_add_f32_e32 v48, v223, v48
	v_add_f32_e32 v48, v224, v48
	v_add_f32_e32 v48, v225, v48
	v_add_f32_e32 v48, v228, v48
	v_add_f32_e32 v48, v229, v48
	v_add_f32_e32 v48, v230, v48
	v_add_f32_e32 v48, v231, v48
	v_add_f32_e32 v48, v232, v48
	v_add_f32_e32 v48, v233, v48
	v_add_f32_e32 v48, v234, v48
	v_add_f32_e32 v48, v235, v48
	v_add_f32_e32 v48, v236, v48
	v_add_f32_e32 v48, v237, v48
	v_add_f32_e32 v48, v238, v48
	v_add_f32_e32 v48, v239, v48
	v_add_f32_e32 v48, v240, v48
	v_add_f32_e32 v48, v241, v48
	v_add_f32_e32 v48, v242, v48
	v_add_f32_e32 v48, v243, v48
	ds_bpermute_b32 v49, v211, v48
	s_waitcnt lgkmcnt(0)
	v_add_f32_e32 v48, v48, v49
	ds_bpermute_b32 v49, v212, v48
	s_waitcnt lgkmcnt(0)
	v_add_f32_e32 v48, v48, v49
	v_div_scale_f32 v49, s[6:7], v48, v48, 1.0
	v_rcp_f32_e32 v51, v49
	v_div_scale_f32 v50, vcc, 1.0, v48, 1.0
	v_fma_f32 v96, -v49, v51, 1.0
	v_fmac_f32_e32 v51, v96, v51
	v_mul_f32_e32 v96, v50, v51
	v_fma_f32 v97, -v49, v96, v50
	v_fmac_f32_e32 v96, v97, v51
	v_fma_f32 v49, -v49, v96, v50
	v_div_fmas_f32 v49, v49, v51, v96
	v_div_fixup_f32 v120, v49, v48, 1.0
	ds_read2_b64 v[48:51], v156 offset1:4
	ds_read2_b64 v[96:99], v163 offset0:32 offset1:36
	s_waitcnt lgkmcnt(1)
; #define LAS __attribute__((address_space(3)))
; __device__ __forceinline__ f32x4 mfma16(bf16x8 a, bf16x8 b, f32x4 c) { return __builtin_amdgcn_mfma_f32_16x16x32_bf16(a, b, c, 0, 0, 0); }
; __device__ __forceinline__ void xattn_unit(const Args& a, LAS unsigned char* lds, int b, int h, int qb, int tid, int wave, int lane) {
;     ...
;         } else {
;             const int mt = j - 4;
; #pragma unroll
;             for (int dt = 0; dt < 16; ++dt) {
;                 const LAS bf16* vr = base + (16 * dt + fr) * VS + 4 * fq;
;                 O[dt] = mfma16(cat8(*(const LAS u32x2*)vr, *(const LAS u32x2*)(vr + 16)), pf[2 * mt], O[dt]);
;                 O[dt] = mfma16(cat8(*(const LAS u32x2*)(vr + 32), *(const LAS u32x2*)(vr + 48)), pf[2 * mt + 1], O[dt]);
;             }
;         }
;         if (j < 7) lstore(j + 1);
;         __syncthreads();
	v_mfma_f32_16x16x32_bf16 v[12:15], v[48:51], v[32:35], v[12:15]
	ds_read2_b64 v[48:51], v162 offset0:64 offset1:68
	s_waitcnt lgkmcnt(1)
	v_mfma_f32_16x16x32_bf16 v[16:19], v[96:99], v[32:35], v[16:19]
	ds_read2_b64 v[96:99], v151 offset1:4
	s_waitcnt lgkmcnt(1)
	v_mfma_f32_16x16x32_bf16 v[20:23], v[48:51], v[32:35], v[20:23]
	ds_read2_b64 v[48:51], v158 offset0:128 offset1:132
	s_waitcnt lgkmcnt(1)
	v_mfma_f32_16x16x32_bf16 v[24:27], v[96:99], v[32:35], v[24:27]
	ds_read2_b64 v[96:99], v159 offset0:160 offset1:164
	s_waitcnt lgkmcnt(1)
	v_mfma_f32_16x16x32_bf16 v[48:51], v[48:51], v[32:35], v[52:55]
	s_nop 2
	ds_read2_b64 v[52:55], v157 offset0:192 offset1:196
	s_waitcnt lgkmcnt(1)
	v_mfma_f32_16x16x32_bf16 v[40:43], v[96:99], v[32:35], v[40:43]
	ds_read2_b64 v[96:99], v152 offset1:4
	s_waitcnt lgkmcnt(1)
	v_mfma_f32_16x16x32_bf16 v[52:55], v[52:55], v[32:35], v[60:63]
	s_nop 2
	ds_read2_b64 v[60:63], v154 offset1:4
	s_waitcnt lgkmcnt(1)
	v_mfma_f32_16x16x32_bf16 v[56:59], v[96:99], v[32:35], v[56:59]
	ds_read2_b64 v[96:99], v155 offset0:32 offset1:36
	s_waitcnt lgkmcnt(1)
	v_mfma_f32_16x16x32_bf16 v[60:63], v[60:63], v[32:35], v[72:75]
	s_nop 2
	ds_read2_b64 v[72:75], v153 offset0:64 offset1:68
	s_waitcnt lgkmcnt(1)
	v_mfma_f32_16x16x32_bf16 v[76:79], v[96:99], v[32:35], v[76:79]
	ds_read2_b64 v[96:99], v150 offset1:4
	s_waitcnt lgkmcnt(1)
	v_mfma_f32_16x16x32_bf16 v[72:75], v[72:75], v[32:35], v[80:83]
	s_nop 2
	ds_read2_b64 v[80:83], v139 offset0:128 offset1:132
	s_waitcnt lgkmcnt(1)
	v_mfma_f32_16x16x32_bf16 v[84:87], v[96:99], v[32:35], v[84:87]
	ds_read2_b64 v[96:99], v146 offset0:160 offset1:164
	s_waitcnt lgkmcnt(1)
	v_mfma_f32_16x16x32_bf16 v[68:71], v[80:83], v[32:35], v[68:71]
	ds_read2_b64 v[80:83], v144 offset0:192 offset1:196
	s_waitcnt lgkmcnt(1)
	v_mfma_f32_16x16x32_bf16 v[28:31], v[96:99], v[32:35], v[28:31]
	ds_read2_b64 v[96:99], v149 offset1:4
	s_waitcnt lgkmcnt(1)
	v_mfma_f32_16x16x32_bf16 v[64:67], v[80:83], v[32:35], v[64:67]
	ds_read2_b64 v[80:83], v156 offset0:8 offset1:12
	s_waitcnt lgkmcnt(1)
	v_mfma_f32_16x16x32_bf16 v[32:35], v[96:99], v[32:35], v[36:39]
	s_nop 2
	ds_read2_b64 v[36:39], v163 offset0:40 offset1:44
	s_waitcnt lgkmcnt(1)
	v_mfma_f32_16x16x32_bf16 v[12:15], v[80:83], v[8:11], v[12:15]
	ds_read2_b64 v[80:83], v162 offset0:72 offset1:76
	s_waitcnt lgkmcnt(1)
	v_mfma_f32_16x16x32_bf16 v[16:19], v[36:39], v[8:11], v[16:19]
	ds_read2_b64 v[36:39], v151 offset0:8 offset1:12
	s_waitcnt lgkmcnt(1)
	v_mfma_f32_16x16x32_bf16 v[20:23], v[80:83], v[8:11], v[20:23]
	ds_read2_b64 v[80:83], v158 offset0:136 offset1:140
	s_waitcnt lgkmcnt(1)
	v_mfma_f32_16x16x32_bf16 v[24:27], v[36:39], v[8:11], v[24:27]
	ds_read2_b64 v[36:39], v159 offset0:168 offset1:172
	s_waitcnt lgkmcnt(1)
	v_mfma_f32_16x16x32_bf16 v[48:51], v[80:83], v[8:11], v[48:51]
	ds_read2_b64 v[80:83], v157 offset0:200 offset1:204
	s_waitcnt lgkmcnt(1)
	v_mfma_f32_16x16x32_bf16 v[36:39], v[36:39], v[8:11], v[40:43]
	s_nop 2
	ds_read2_b64 v[40:43], v152 offset0:8 offset1:12
	s_waitcnt lgkmcnt(1)
	v_mfma_f32_16x16x32_bf16 v[52:55], v[80:83], v[8:11], v[52:55]
	ds_read2_b64 v[80:83], v154 offset0:8 offset1:12
	s_waitcnt lgkmcnt(1)
	v_mfma_f32_16x16x32_bf16 v[40:43], v[40:43], v[8:11], v[56:59]
	s_nop 2
	ds_read2_b64 v[56:59], v155 offset0:40 offset1:44
	s_waitcnt lgkmcnt(1)
	v_mfma_f32_16x16x32_bf16 v[60:63], v[80:83], v[8:11], v[60:63]
	ds_read2_b64 v[80:83], v153 offset0:72 offset1:76
	s_waitcnt lgkmcnt(1)
	v_mfma_f32_16x16x32_bf16 v[56:59], v[56:59], v[8:11], v[76:79]
	s_nop 2
	ds_read2_b64 v[76:79], v150 offset0:8 offset1:12
	s_waitcnt lgkmcnt(1)
	v_mfma_f32_16x16x32_bf16 v[72:75], v[80:83], v[8:11], v[72:75]
	ds_read2_b64 v[80:83], v139 offset0:136 offset1:140
	ds_read2_b64 v[96:99], v146 offset0:168 offset1:172
	s_waitcnt lgkmcnt(2)
	v_mfma_f32_16x16x32_bf16 v[76:79], v[76:79], v[8:11], v[84:87]
	s_nop 2
	ds_read2_b64 v[84:87], v144 offset0:200 offset1:204
	ds_read2_b64 v[104:107], v149 offset0:8 offset1:12
	s_waitcnt vmcnt(3)
	ds_write_b128 v176, v[44:47] offset:36864
	s_waitcnt vmcnt(2)
	ds_write_b128 v160, v[88:91] offset:36864
	s_waitcnt vmcnt(1)
	ds_write_b128 v161, v[100:103] offset:36864
	s_waitcnt vmcnt(0)
	ds_write_b128 v148, v[92:95] offset:36864
	s_waitcnt lgkmcnt(7)
	v_mfma_f32_16x16x32_bf16 v[44:47], v[80:83], v[8:11], v[68:71]
	s_waitcnt lgkmcnt(0)
	s_barrier
; #define LAS __attribute__((address_space(3)))
; __device__ __forceinline__ unsigned pk2(float lo, float hi) { f32x2_t v = {lo, hi}; bf16x2_t b = __builtin_convertvector(v, bf16x2_t); return __builtin_bit_cast(unsigned, b); }
; __device__ __forceinline__ f32x4 mfma16(bf16x8 a, bf16x8 b, f32x4 c) { return __builtin_amdgcn_mfma_f32_16x16x32_bf16(a, b, c, 0, 0, 0); }
; __device__ __forceinline__ void xattn_unit(const Args& a, LAS unsigned char* lds, int b, int h, int qb, int tid, int wave, int lane) {
;     ...
; #pragma unroll
;             for (int dt = 0; dt < 16; ++dt) {
;                 const LAS bf16* vr = base + (16 * dt + fr) * VS + 4 * fq;
;                 O[dt] = mfma16(cat8(*(const LAS u32x2*)vr, *(const LAS u32x2*)(vr + 16)), pf[2 * mt], O[dt]);
;                 O[dt] = mfma16(cat8(*(const LAS u32x2*)(vr + 32), *(const LAS u32x2*)(vr + 48)), pf[2 * mt + 1], O[dt]);
;             }
;         }
;         if (j < 7) lstore(j + 1);
;         __syncthreads();
;     }
;     const float il = 1.f / l;
; #pragma unroll
;     for (int dt = 0; dt < 16; ++dt) { u32x2 w; w.x = pk2(O[dt][0] * il, O[dt][1] * il); w.y = pk2(O[dt][2] * il, O[dt][3] * il);
	v_mfma_f32_16x16x32_bf16 v[28:31], v[96:99], v[8:11], v[28:31]
	ds_read2_b64 v[68:71], v138 offset1:4
	v_mfma_f32_16x16x32_bf16 v[64:67], v[84:87], v[8:11], v[64:67]
	v_mfma_f32_16x16x32_bf16 v[8:11], v[104:107], v[8:11], v[32:35]
	s_nop 2
	ds_read2_b64 v[32:35], v145 offset0:32 offset1:36
	s_waitcnt lgkmcnt(1)
	v_mfma_f32_16x16x32_bf16 v[12:15], v[68:71], v[4:7], v[12:15]
	ds_read2_b64 v[68:71], v147 offset0:64 offset1:68
	s_waitcnt lgkmcnt(1)
	v_mfma_f32_16x16x32_bf16 v[16:19], v[32:35], v[4:7], v[16:19]
	ds_read2_b64 v[32:35], v164 offset1:4
	s_waitcnt lgkmcnt(1)
	v_mfma_f32_16x16x32_bf16 v[20:23], v[68:71], v[4:7], v[20:23]
	ds_read2_b64 v[68:71], v165 offset0:128 offset1:132
	s_waitcnt lgkmcnt(1)
	v_mfma_f32_16x16x32_bf16 v[24:27], v[32:35], v[4:7], v[24:27]
	ds_read2_b64 v[32:35], v166 offset0:160 offset1:164
	s_waitcnt lgkmcnt(1)
	v_mfma_f32_16x16x32_bf16 v[48:51], v[68:71], v[4:7], v[48:51]
	ds_read2_b64 v[68:71], v167 offset0:192 offset1:196
	s_waitcnt lgkmcnt(1)
	v_mfma_f32_16x16x32_bf16 v[32:35], v[32:35], v[4:7], v[36:39]
	s_nop 2
	ds_read2_b64 v[36:39], v168 offset1:4
	s_waitcnt lgkmcnt(1)
	v_mfma_f32_16x16x32_bf16 v[52:55], v[68:71], v[4:7], v[52:55]
	ds_read2_b64 v[68:71], v169 offset1:4
	s_waitcnt lgkmcnt(1)
	v_mfma_f32_16x16x32_bf16 v[36:39], v[36:39], v[4:7], v[40:43]
	s_nop 2
	ds_read2_b64 v[40:43], v170 offset0:32 offset1:36
	s_waitcnt lgkmcnt(1)
	v_mfma_f32_16x16x32_bf16 v[60:63], v[68:71], v[4:7], v[60:63]
	ds_read2_b64 v[68:71], v171 offset0:64 offset1:68
	s_waitcnt lgkmcnt(1)
	v_mfma_f32_16x16x32_bf16 v[40:43], v[40:43], v[4:7], v[56:59]
	s_nop 2
	ds_read2_b64 v[56:59], v172 offset1:4
	s_waitcnt lgkmcnt(1)
	v_mfma_f32_16x16x32_bf16 v[68:71], v[68:71], v[4:7], v[72:75]
	s_nop 2
	ds_read2_b64 v[72:75], v173 offset0:128 offset1:132
	s_waitcnt lgkmcnt(1)
	v_mfma_f32_16x16x32_bf16 v[56:59], v[56:59], v[4:7], v[76:79]
	s_nop 2
	ds_read2_b64 v[76:79], v177 offset0:160 offset1:164
	s_waitcnt lgkmcnt(1)
	v_mfma_f32_16x16x32_bf16 v[44:47], v[72:75], v[4:7], v[44:47]
	ds_read2_b64 v[72:75], v175 offset0:192 offset1:196
	s_waitcnt lgkmcnt(1)
	v_mfma_f32_16x16x32_bf16 v[28:31], v[76:79], v[4:7], v[28:31]
	ds_read2_b64 v[76:79], v174 offset1:4
	s_waitcnt lgkmcnt(1)
	v_mfma_f32_16x16x32_bf16 v[64:67], v[72:75], v[4:7], v[64:67]
	ds_read2_b64 v[72:75], v138 offset0:8 offset1:12
	s_waitcnt lgkmcnt(1)
	v_mfma_f32_16x16x32_bf16 v[4:7], v[76:79], v[4:7], v[8:11]
	s_nop 2
	ds_read2_b64 v[8:11], v145 offset0:40 offset1:44
	s_waitcnt lgkmcnt(1)
	v_mfma_f32_16x16x32_bf16 v[12:15], v[72:75], v[0:3], v[12:15]
	ds_read2_b64 v[72:75], v147 offset0:72 offset1:76
	s_waitcnt lgkmcnt(1)
	v_mfma_f32_16x16x32_bf16 v[8:11], v[8:11], v[0:3], v[16:19]
	s_nop 2
	ds_read2_b64 v[16:19], v164 offset0:8 offset1:12
	s_waitcnt lgkmcnt(1)
	v_mfma_f32_16x16x32_bf16 v[20:23], v[72:75], v[0:3], v[20:23]
	ds_read2_b64 v[72:75], v165 offset0:136 offset1:140
	s_nop 0
	v_pk_mul_f32 v[8:9], v[120:121], v[8:9] op_sel_hi:[0,1]
	v_pk_mul_f32 v[10:11], v[120:121], v[10:11] op_sel_hi:[0,1]
	s_waitcnt lgkmcnt(1)
	v_mfma_f32_16x16x32_bf16 v[16:19], v[16:19], v[0:3], v[24:27]
	s_nop 2
	ds_read2_b64 v[24:27], v166 offset0:168 offset1:172
	s_waitcnt lgkmcnt(1)
	v_mfma_f32_16x16x32_bf16 v[48:51], v[72:75], v[0:3], v[48:51]
	ds_read2_b64 v[72:75], v167 offset0:200 offset1:204
	s_nop 0
	v_pk_mul_f32 v[16:17], v[120:121], v[16:17] op_sel_hi:[0,1]
	v_pk_mul_f32 v[18:19], v[120:121], v[18:19] op_sel_hi:[0,1]
	s_waitcnt lgkmcnt(1)
	v_mfma_f32_16x16x32_bf16 v[24:27], v[24:27], v[0:3], v[32:35]
	s_nop 2
	ds_read2_b64 v[32:35], v168 offset0:8 offset1:12
	s_waitcnt lgkmcnt(1)
	v_mfma_f32_16x16x32_bf16 v[52:55], v[72:75], v[0:3], v[52:55]
	ds_read2_b64 v[72:75], v169 offset0:8 offset1:12
	s_nop 0
	v_pk_mul_f32 v[24:25], v[120:121], v[24:25] op_sel_hi:[0,1]
	v_pk_mul_f32 v[26:27], v[120:121], v[26:27] op_sel_hi:[0,1]
	s_waitcnt lgkmcnt(1)
	v_mfma_f32_16x16x32_bf16 v[32:35], v[32:35], v[0:3], v[36:39]
	s_nop 2
	ds_read2_b64 v[36:39], v170 offset0:40 offset1:44
	s_waitcnt lgkmcnt(1)
	v_mfma_f32_16x16x32_bf16 v[60:63], v[72:75], v[0:3], v[60:63]
	ds_read2_b64 v[72:75], v171 offset0:72 offset1:76
	s_nop 0
	v_pk_mul_f32 v[32:33], v[120:121], v[32:33] op_sel_hi:[0,1]
	v_pk_mul_f32 v[34:35], v[120:121], v[34:35] op_sel_hi:[0,1]
	s_waitcnt lgkmcnt(1)
	v_mfma_f32_16x16x32_bf16 v[36:39], v[36:39], v[0:3], v[40:43]
	s_nop 2
	ds_read2_b64 v[40:43], v172 offset0:8 offset1:12
	s_waitcnt lgkmcnt(1)
	v_mfma_f32_16x16x32_bf16 v[68:71], v[72:75], v[0:3], v[68:71]
	ds_read2_b64 v[72:75], v173 offset0:136 offset1:140
	s_nop 0
	v_pk_mul_f32 v[36:37], v[120:121], v[36:37] op_sel_hi:[0,1]
	v_pk_mul_f32 v[38:39], v[120:121], v[38:39] op_sel_hi:[0,1]
	s_waitcnt lgkmcnt(1)
	v_mfma_f32_16x16x32_bf16 v[40:43], v[40:43], v[0:3], v[56:59]
	s_nop 2
	ds_read2_b64 v[56:59], v177 offset0:168 offset1:172
	s_waitcnt lgkmcnt(1)
	v_mfma_f32_16x16x32_bf16 v[44:47], v[72:75], v[0:3], v[44:47]
	ds_read2_b64 v[72:75], v175 offset0:200 offset1:204
	s_nop 0
	v_pk_mul_f32 v[40:41], v[120:121], v[40:41] op_sel_hi:[0,1]
	v_pk_mul_f32 v[42:43], v[120:121], v[42:43] op_sel_hi:[0,1]
	s_waitcnt lgkmcnt(1)
	v_mfma_f32_16x16x32_bf16 v[28:31], v[56:59], v[0:3], v[28:31]
	ds_read2_b64 v[56:59], v174 offset0:8 offset1:12
	s_nop 0
	v_pk_mul_f32 v[44:45], v[120:121], v[44:45] op_sel_hi:[0,1]
	v_pk_mul_f32 v[46:47], v[120:121], v[46:47] op_sel_hi:[0,1]
	s_waitcnt lgkmcnt(1)
	v_mfma_f32_16x16x32_bf16 v[64:67], v[72:75], v[0:3], v[64:67]
	s_nop 1
	v_mul_f32_e64 v28, v120, v28
	v_mul_f32_e64 v29, v120, v29
	v_pk_mul_f32 v[30:31], v[120:121], v[30:31] op_sel_hi:[0,1]
	s_waitcnt lgkmcnt(0)
	v_mfma_f32_16x16x32_bf16 v[0:3], v[56:59], v[0:3], v[4:7]
	v_mul_f32_e64 v56, v120, v68
	v_mul_f32_e64 v57, v120, v69
	s_nop 0
	v_pk_mul_f32 v[4:5], v[120:121], v[12:13] op_sel_hi:[0,1]
	v_pk_mul_f32 v[6:7], v[120:121], v[14:15] op_sel_hi:[0,1]
	v_pk_mul_f32 v[12:13], v[120:121], v[20:21] op_sel_hi:[0,1]
	v_pk_mul_f32 v[14:15], v[120:121], v[22:23] op_sel_hi:[0,1]
	v_pk_mul_f32 v[20:21], v[120:121], v[48:49] op_sel_hi:[0,1]
	v_pk_mul_f32 v[22:23], v[120:121], v[50:51] op_sel_hi:[0,1]
	v_pk_mul_f32 v[48:49], v[120:121], v[52:53] op_sel_hi:[0,1]
	v_pk_mul_f32 v[50:51], v[120:121], v[54:55] op_sel_hi:[0,1]
	v_pk_mul_f32 v[52:53], v[120:121], v[60:61] op_sel_hi:[0,1]
	v_pk_mul_f32 v[54:55], v[120:121], v[62:63] op_sel_hi:[0,1]
	v_pk_mul_f32 v[58:59], v[120:121], v[70:71] op_sel_hi:[0,1]
	v_pk_mul_f32 v[60:61], v[120:121], v[64:65] op_sel_hi:[0,1]
	v_pk_mul_f32 v[62:63], v[120:121], v[66:67] op_sel_hi:[0,1]
	v_pk_mul_f32 v[0:1], v[120:121], v[0:1] op_sel_hi:[0,1]
	v_pk_mul_f32 v[2:3], v[120:121], v[2:3] op_sel_hi:[0,1]
	v_cvt_pk_bf16_f32 v4, v4, v5
	v_cvt_pk_bf16_f32 v5, v6, v7
	s_barrier
; #define GAS __attribute__((address_space(1)))
; __device__ __forceinline__ unsigned pk2(float lo, float hi) { f32x2_t v = {lo, hi}; bf16x2_t b = __builtin_convertvector(v, bf16x2_t); return __builtin_bit_cast(unsigned, b); }
; __device__ __forceinline__ void xattn_unit(const Args& a, LAS unsigned char* lds, int b, int h, int qb, int tid, int wave, int lane) {
;     ...
;     const float il = 1.f / l;
; #pragma unroll
;     for (int dt = 0; dt < 16; ++dt) { u32x2 w; w.x = pk2(O[dt][0] * il, O[dt][1] * il); w.y = pk2(O[dt][2] * il, O[dt][3] * il);
;         *(GAS u32x2*)(XO + qrow * DM + h * 256 + 16 * dt + 4 * fq) = w; }
	v_cvt_pk_bf16_f32 v6, v8, v9
	v_cvt_pk_bf16_f32 v7, v10, v11
	v_cvt_pk_bf16_f32 v8, v12, v13
	v_cvt_pk_bf16_f32 v9, v14, v15
	v_cvt_pk_bf16_f32 v10, v16, v17
	v_cvt_pk_bf16_f32 v11, v18, v19
	v_cvt_pk_bf16_f32 v12, v20, v21
	v_cvt_pk_bf16_f32 v13, v22, v23
	v_cvt_pk_bf16_f32 v14, v24, v25
	v_cvt_pk_bf16_f32 v15, v26, v27
	v_cvt_pk_bf16_f32 v16, v48, v49
	v_cvt_pk_bf16_f32 v17, v50, v51
	v_cvt_pk_bf16_f32 v18, v32, v33
	v_cvt_pk_bf16_f32 v19, v34, v35
	v_cvt_pk_bf16_f32 v20, v52, v53
	v_cvt_pk_bf16_f32 v21, v54, v55
	v_cvt_pk_bf16_f32 v22, v36, v37
	v_cvt_pk_bf16_f32 v23, v38, v39
	v_cvt_pk_bf16_f32 v24, v56, v57
	v_cvt_pk_bf16_f32 v25, v58, v59
	v_cvt_pk_bf16_f32 v26, v40, v41
	v_cvt_pk_bf16_f32 v27, v42, v43
	v_cvt_pk_bf16_f32 v36, v44, v45
	v_cvt_pk_bf16_f32 v37, v46, v47
	v_cvt_pk_bf16_f32 v38, v28, v29
	v_cvt_pk_bf16_f32 v39, v30, v31
	v_cvt_pk_bf16_f32 v40, v60, v61
	v_cvt_pk_bf16_f32 v41, v62, v63
	v_cvt_pk_bf16_f32 v42, v0, v1
	v_cvt_pk_bf16_f32 v43, v2, v3
	v_bfe_u32 v44, v252, 4, 1
	v_mul_u32_u24_e32 v44, 24, v44
	v_mov_b32_e32 v45, 0
	v_lshl_add_u64 v[44:45], v[136:137], 0, v[44:45]
	v_permlane16_swap_b32_e32 v4, v6
	v_permlane16_swap_b32_e32 v5, v7
	v_permlane16_swap_b32_e32 v8, v10
	v_permlane16_swap_b32_e32 v9, v11
	v_permlane16_swap_b32_e32 v12, v14
	v_permlane16_swap_b32_e32 v13, v15
	v_permlane16_swap_b32_e32 v16, v18
	v_permlane16_swap_b32_e32 v17, v19
	v_permlane16_swap_b32_e32 v20, v22
	v_permlane16_swap_b32_e32 v21, v23
	v_permlane16_swap_b32_e32 v24, v26
	v_permlane16_swap_b32_e32 v25, v27
	v_permlane16_swap_b32_e32 v36, v38
	v_permlane16_swap_b32_e32 v37, v39
	v_permlane16_swap_b32_e32 v40, v42
	v_permlane16_swap_b32_e32 v41, v43
	global_store_dwordx4 v[44:45], v[4:7], off
	global_store_dwordx4 v[44:45], v[8:11], off offset:64
	global_store_dwordx4 v[44:45], v[12:15], off offset:128
	global_store_dwordx4 v[44:45], v[16:19], off offset:192
	global_store_dwordx4 v[44:45], v[20:23], off offset:256
	global_store_dwordx4 v[44:45], v[24:27], off offset:320
	global_store_dwordx4 v[44:45], v[36:39], off offset:384
	global_store_dwordx4 v[44:45], v[40:43], off offset:448
	s_cbranch_scc0 .LBB0_1518

; #define PG8_GAS __attribute__((address_space(1)))
; __device__ __forceinline__ float row_rstd(const float* parts, int r, int fq) {
;     const f32x4 p = *(const PG8_GAS f32x4*)(parts + (size_t)r * 16 + 4 * fq);
;     float s = (p[0] + p[1]) + (p[2] + p[3]);
;     s += __shfl_xor(s, 16); s += __shfl_xor(s, 32);
;     return rsqrtf(s * (1.0f / 1024.0f) + RMS_EPS);
; }
;     __device__ __forceinline__ void operator()(const f32x4 (&acc)[2][2][4][2], const Unit& u, int wr, int wc, int fr, int fq) const {
;         const int row0 = u.pm * BM + wr * 64 + fr, col0 = u.pn * 128 + wc * 32 + 8 * fq;
;         float rs8[2][4];
; #pragma unroll
;         for (int ai = 0; ai < 2; ++ai)
; #pragma unroll
;             for (int m = 0; m < 4; ++m) rs8[ai][m] = row_rstd(parts, row0 + ai * HALF + m * 16, fq);
.LBB0_1661:
	s_lshl_b32 s8, s8, 8
	v_mov_b32_e32 v132, v252
	s_add_i32 s8, s8, s56
	v_cmp_lt_i32_e32 vcc, v227, v226
	v_bfe_u32 v200, v132, 4, 2
	v_and_or_b32 v160, v132, 15, s8
	v_lshlrev_b32_e32 v132, 4, v200
	v_ashrrev_i32_e32 v161, 31, v160
	v_or_b32_e32 v156, 16, v160
	v_lshl_add_u64 v[188:189], s[16:17], 0, v[132:133]
	v_lshlrev_b64 v[140:141], 6, v[160:161]
	v_ashrrev_i32_e32 v157, 31, v156
	v_lshl_add_u64 v[140:141], v[188:189], 0, v[140:141]
	v_lshlrev_b64 v[142:143], 6, v[156:157]
	v_or_b32_e32 v152, 32, v160
	v_lshl_add_u64 v[142:143], v[188:189], 0, v[142:143]
	global_load_dwordx4 v[164:167], v[140:141], off
	global_load_dwordx4 v[168:171], v[142:143], off
	v_ashrrev_i32_e32 v153, 31, v152
	v_lshlrev_b64 v[140:141], 6, v[152:153]
	v_or_b32_e32 v150, 48, v160
	v_lshl_add_u64 v[140:141], v[188:189], 0, v[140:141]
	v_ashrrev_i32_e32 v151, 31, v150
	global_load_dwordx4 v[172:175], v[140:141], off
	v_lshlrev_b64 v[140:141], 6, v[150:151]
	v_lshl_add_u64 v[140:141], v[188:189], 0, v[140:141]
	global_load_dwordx4 v[176:179], v[140:141], off
	v_add_u32_e32 v146, 0x80, v160
	v_ashrrev_i32_e32 v147, 31, v146
	v_lshlrev_b64 v[140:141], 6, v[146:147]
	v_add_u32_e32 v144, 0x90, v160
	v_lshl_add_u64 v[140:141], v[188:189], 0, v[140:141]
	v_ashrrev_i32_e32 v145, 31, v144
	global_load_dwordx4 v[180:183], v[140:141], off
	v_lshlrev_b64 v[140:141], 6, v[144:145]
	v_lshl_add_u64 v[140:141], v[188:189], 0, v[140:141]
	global_load_dwordx4 v[184:187], v[140:141], off
	v_add_u32_e32 v142, 0xa0, v160
	v_add_u32_e32 v140, 0xb0, v160
	v_ashrrev_i32_e32 v143, 31, v142
	v_ashrrev_i32_e32 v141, 31, v140
	v_lshlrev_b64 v[190:191], 6, v[142:143]
	v_lshlrev_b64 v[192:193], 6, v[140:141]
	v_lshl_add_u64 v[190:191], v[188:189], 0, v[190:191]
	v_lshl_add_u64 v[192:193], v[188:189], 0, v[192:193]
	global_load_dwordx4 v[188:191], v[190:191], off
	s_nop 0
	global_load_dwordx4 v[192:195], v[192:193], off
	v_cndmask_b32_e32 v132, v253, v227, vcc
	v_lshlrev_b32_e32 v132, 2, v132
	v_xor_b32_e32 v145, 32, v253
	v_cmp_lt_i32_e32 vcc, v145, v226
	v_mov_b64_e32 v[196:197], s[30:31]
	s_waitcnt vmcnt(0)
	v_mov_b32_e32 v198, v165
	v_mov_b32_e32 v199, v166
	v_mov_b32_e32 v165, v167
	v_mov_b32_e32 v166, v169
	v_mov_b32_e32 v167, v170
	v_mov_b32_e32 v169, v171
	v_pk_add_f32 v[164:165], v[198:199], v[164:165]
	v_pk_add_f32 v[166:167], v[166:167], v[168:169]
	v_mov_b32_e32 v169, v164
	v_mov_b32_e32 v168, v166
	v_mov_b32_e32 v164, v167
	v_pk_add_f32 v[164:165], v[168:169], v[164:165]
	v_mov_b32_e32 v169, v165
	s_nop 1
	v_permlane16_swap_b32_e32 v165, v169
	v_mov_b32_e32 v168, v164
	s_nop 1
	v_permlane16_swap_b32_e32 v164, v168
	v_mov_b32_e32 v170, v173
	v_mov_b32_e32 v171, v174
	v_mov_b32_e32 v173, v175
	v_mov_b32_e32 v174, v177
	v_mov_b32_e32 v175, v178
	v_mov_b32_e32 v177, v179
	v_pk_add_f32 v[170:171], v[170:171], v[172:173]
	v_pk_add_f32 v[172:173], v[174:175], v[176:177]
	v_mov_b32_e32 v167, v170
	v_mov_b32_e32 v166, v172
	v_mov_b32_e32 v170, v173
	v_pk_add_f32 v[166:167], v[166:167], v[170:171]
	v_cndmask_b32_e32 v141, v253, v145, vcc
	v_mov_b32_e32 v171, v167
	s_nop 1
	v_permlane16_swap_b32_e32 v167, v171
	v_mov_b32_e32 v170, v166
	s_nop 1
	v_permlane16_swap_b32_e32 v166, v170
	v_lshlrev_b32_e32 v141, 2, v141
	s_waitcnt lgkmcnt(2)
	v_pk_add_f32 v[164:165], v[164:165], v[168:169]
	v_mov_b32_e32 v169, v165
	s_nop 1
	v_permlane32_swap_b32_e32 v165, v169
	v_mov_b32_e32 v168, v164
	s_nop 1
	v_permlane32_swap_b32_e32 v164, v168
	s_waitcnt lgkmcnt(2)
	v_pk_add_f32 v[166:167], v[166:167], v[170:171]
	v_mov_b32_e32 v171, v167
	s_nop 1
	v_permlane32_swap_b32_e32 v167, v171
	v_mov_b32_e32 v170, v166
	s_nop 1
	v_permlane32_swap_b32_e32 v166, v170
	v_mov_b32_e32 v172, v181
	s_waitcnt lgkmcnt(2)
	v_pk_add_f32 v[164:165], v[164:165], v[168:169]
	v_mov_b32_e32 v173, v182
	v_pk_fma_f32 v[164:165], v[164:165], s[28:29], v[196:197] op_sel_hi:[1,0,0]
	v_mov_b32_e32 v181, v183
	v_mul_f32_e32 v143, 0x4b800000, v165
	v_mul_f32_e32 v145, 0x4b800000, v164
	v_cmp_gt_f32_e32 vcc, s61, v165
	v_cmp_gt_f32_e64 s[8:9], s61, v164
	v_pk_add_f32 v[172:173], v[172:173], v[180:181]
	v_cndmask_b32_e32 v143, v165, v143, vcc
	v_cndmask_b32_e64 v145, v164, v145, s[8:9]
	v_mov_b32_e32 v164, v185
	v_mov_b32_e32 v165, v186
	v_mov_b32_e32 v185, v187
	v_pk_add_f32 v[164:165], v[164:165], v[184:185]
	s_waitcnt lgkmcnt(0)
	v_pk_add_f32 v[166:167], v[166:167], v[170:171]
	v_mov_b32_e32 v170, v164
	v_mov_b32_e32 v171, v172
	v_mov_b32_e32 v172, v165
	v_rsq_f32_e32 v143, v143
	v_pk_add_f32 v[164:165], v[170:171], v[172:173]
	v_mov_b32_e32 v171, v165
	s_nop 1
	v_permlane16_swap_b32_e32 v165, v171
	v_mov_b32_e32 v170, v164
	s_nop 1
	v_permlane16_swap_b32_e32 v164, v170
	v_pk_fma_f32 v[166:167], v[166:167], s[28:29], v[196:197] op_sel_hi:[1,0,0]
	v_mul_f32_e32 v148, 0x45800000, v143
	v_mul_f32_e32 v147, 0x4b800000, v167
	v_cmp_gt_f32_e64 s[10:11], s61, v167
	v_cndmask_b32_e32 v168, v143, v148, vcc
	v_mul_f32_e32 v143, 0x4b800000, v166
	v_cmp_gt_f32_e32 vcc, s61, v166
	v_cndmask_b32_e64 v147, v167, v147, s[10:11]
	v_mov_b32_e32 v174, v193
	v_cndmask_b32_e32 v143, v166, v143, vcc
	s_waitcnt lgkmcnt(0)
	v_pk_add_f32 v[166:167], v[164:165], v[170:171]
	v_mov_b32_e32 v171, v167
	s_nop 1
	v_permlane32_swap_b32_e32 v167, v171
	v_mov_b32_e32 v170, v166
	s_nop 1
	v_permlane32_swap_b32_e32 v166, v170
	v_mov_b32_e32 v175, v194
	v_mov_b32_e32 v193, v195
	v_pk_add_f32 v[174:175], v[174:175], v[192:193]
	v_rsq_f32_e32 v145, v145
	s_waitcnt lgkmcnt(0)
; #define PG8_GAS __attribute__((address_space(1)))
; __device__ __forceinline__ unsigned pk2_(float lo, float hi) { f32x2c_t v = {lo, hi}; bf16x2c_t b = __builtin_convertvector(v, bf16x2c_t); return __builtin_bit_cast(unsigned, b); }
; __device__ __forceinline__ float silu_f(float x) { return x * __builtin_amdgcn_rcpf(1.0f + __builtin_amdgcn_exp2f(-1.4426950408889634f * x)); }
; __device__ __forceinline__ float row_rstd(const float* parts, int r, int fq) {
;     const f32x4 p = *(const PG8_GAS f32x4*)(parts + (size_t)r * 16 + 4 * fq);
;     float s = (p[0] + p[1]) + (p[2] + p[3]);
;     s += __shfl_xor(s, 16); s += __shfl_xor(s, 32);
;     return rsqrtf(s * (1.0f / 1024.0f) + RMS_EPS);
; }
;     __device__ __forceinline__ void operator()(const f32x4 (&acc)[2][2][4][2], const Unit& u, int wr, int wc, int fr, int fq) const {
;     ...
; #pragma unroll
;         for (int ai = 0; ai < 2; ++ai)
; #pragma unroll
;             for (int m = 0; m < 4; ++m) {
;                 const int r = row0 + ai * HALF + m * 16; const float s = rs8[ai][m];
;                 float o[8];
; #pragma unroll
;                 for (int n = 0; n < 2; ++n)
; #pragma unroll
;                     for (int i = 0; i < 4; ++i) o[4 * n + i] = silu_f(acc[ai][0][m][n][i] * s) * (acc[ai][1][m][n][i] * s);
;                 u32x4 w; w.x = pk2_(o[0], o[1]); w.y = pk2_(o[2], o[3]); w.z = pk2_(o[4], o[5]); w.w = pk2_(o[6], o[7]);
;                 *(PG8_GAS u32x4*)(O + (size_t)r * 2816 + col0) = w;
	v_pk_add_f32 v[166:167], v[166:167], v[170:171]
	v_mov_b32_e32 v170, v189
	v_mov_b32_e32 v171, v190
	v_mov_b32_e32 v189, v191
	v_pk_add_f32 v[170:171], v[170:171], v[188:189]
	v_mov_b32_e32 v176, v174
	v_mov_b32_e32 v177, v170
	v_mov_b32_e32 v170, v175
	v_rsq_f32_e32 v147, v147
	v_pk_add_f32 v[170:171], v[176:177], v[170:171]
	v_mov_b32_e32 v175, v171
	s_nop 1
	v_permlane16_swap_b32_e32 v171, v175
	v_mov_b32_e32 v174, v170
	s_nop 1
	v_permlane16_swap_b32_e32 v170, v174
	v_mul_f32_e32 v151, 0x45800000, v145
	v_cndmask_b32_e64 v172, v145, v151, s[8:9]
	v_mul_f32_e32 v145, 0x45800000, v147
	v_pk_fma_f32 v[166:167], v[166:167], s[28:29], v[196:197] op_sel_hi:[1,0,0]
	v_cndmask_b32_e64 v164, v147, v145, s[10:11]
	v_mul_f32_e32 v147, 0x4b800000, v167
	v_cmp_gt_f32_e64 s[8:9], s61, v167
	v_mul_f32_e32 v132, 0x4b800000, v166
	v_cmp_gt_f32_e64 s[10:11], s61, v166
	v_cndmask_b32_e64 v147, v167, v147, s[8:9]
	v_rsq_f32_e32 v143, v143
	v_cndmask_b32_e64 v132, v166, v132, s[10:11]
	s_waitcnt lgkmcnt(0)
	v_pk_add_f32 v[166:167], v[170:171], v[174:175]
	v_mov_b32_e32 v171, v167
	s_nop 1
	v_permlane32_swap_b32_e32 v167, v171
	v_mov_b32_e32 v170, v166
	s_nop 1
	v_permlane32_swap_b32_e32 v166, v170
	v_rsq_f32_e32 v147, v147
	v_mul_f32_e32 v145, 0x45800000, v143
	v_cndmask_b32_e32 v162, v143, v145, vcc
	v_rsq_f32_e32 v132, v132
	s_waitcnt lgkmcnt(0)
	v_pk_add_f32 v[166:167], v[166:167], v[170:171]
	v_mul_f32_e32 v141, 0x45800000, v147
	v_pk_fma_f32 v[166:167], v[166:167], s[28:29], v[196:197] op_sel_hi:[1,0,0]
	v_cndmask_b32_e64 v158, v147, v141, s[8:9]
	v_mul_f32_e32 v143, 0x4b800000, v167
	v_cmp_gt_f32_e32 vcc, s61, v167
	v_mul_f32_e32 v145, 0x4b800000, v166
	v_cmp_gt_f32_e64 s[8:9], s61, v166
	v_cndmask_b32_e32 v143, v167, v143, vcc
	v_rsq_f32_e32 v143, v143
	v_cndmask_b32_e64 v145, v166, v145, s[8:9]
	v_rsq_f32_e32 v145, v145
	v_mul_f32_e32 v141, 0x45800000, v132
	v_cndmask_b32_e64 v154, v132, v141, s[10:11]
	v_mul_f32_e32 v132, 0x45800000, v143
	v_cndmask_b32_e32 v148, v143, v132, vcc
	v_mul_f32_e32 v132, 0x45800000, v145
	v_cndmask_b32_e64 v132, v145, v132, s[8:9]
	s_lshl_b32 s8, s63, 7
	v_lshl_or_b32 v141, v200, 3, s8
	v_pk_mul_f32 v[124:125], v[124:125], v[168:169] op_sel_hi:[1,0]
	v_or_b32_e32 v166, s57, v141
	v_mul_f32_e32 v141, 0xbfb8aa3b, v124
	v_exp_f32_e32 v141, v141
	v_mul_f32_e32 v143, 0xbfb8aa3b, v125
	v_exp_f32_e32 v143, v143
	v_pk_mul_f32 v[126:127], v[126:127], v[168:169] op_sel_hi:[1,0]
	v_add_f32_e32 v141, 1.0, v141
	v_rcp_f32_e32 v170, v141
	v_add_f32_e32 v141, 1.0, v143
	v_mul_f32_e32 v143, 0xbfb8aa3b, v126
	v_exp_f32_e32 v143, v143
	v_mul_f32_e32 v145, 0xbfb8aa3b, v127
	v_exp_f32_e32 v145, v145
	v_rcp_f32_e32 v171, v141
	v_add_f32_e32 v141, 1.0, v143
	v_rcp_f32_e32 v174, v141
	v_add_f32_e32 v141, 1.0, v145
	v_rcp_f32_e32 v175, v141
	v_pk_mul_f32 v[124:125], v[124:125], v[170:171]
	v_pk_mul_f32 v[116:117], v[116:117], v[168:169] op_sel_hi:[1,0]
	v_pk_mul_f32 v[120:121], v[120:121], v[168:169] op_sel_hi:[1,0]
	v_pk_mul_f32 v[116:117], v[116:117], v[124:125]
	v_pk_mul_f32 v[124:125], v[126:127], v[174:175]
	v_mul_f32_e32 v126, 0xbfb8aa3b, v120
	v_mul_f32_e32 v127, 0xbfb8aa3b, v121
	v_exp_f32_e32 v126, v126
	v_exp_f32_e32 v127, v127
	v_pk_mul_f32 v[118:119], v[118:119], v[168:169] op_sel_hi:[1,0]
	v_pk_mul_f32 v[122:123], v[122:123], v[168:169] op_sel_hi:[1,0]
	v_pk_mul_f32 v[118:119], v[118:119], v[124:125]
	v_add_f32_e32 v124, 1.0, v126
	v_add_f32_e32 v125, 1.0, v127
	v_mul_f32_e32 v126, 0xbfb8aa3b, v122
	v_mul_f32_e32 v127, 0xbfb8aa3b, v123
	v_exp_f32_e32 v126, v126
	v_exp_f32_e32 v127, v127
	v_rcp_f32_e32 v124, v124
	v_rcp_f32_e32 v125, v125
	v_add_f32_e32 v126, 1.0, v126
	v_add_f32_e32 v127, 1.0, v127
	v_rcp_f32_e32 v126, v126
	v_rcp_f32_e32 v127, v127
	v_pk_mul_f32 v[120:121], v[120:121], v[124:125]
	v_pk_mul_f32 v[112:113], v[112:113], v[168:169] op_sel_hi:[1,0]
	v_pk_mul_f32 v[114:115], v[114:115], v[168:169] op_sel_hi:[1,0]
	v_pk_mul_f32 v[112:113], v[112:113], v[120:121]
	v_pk_mul_f32 v[120:121], v[122:123], v[126:127]
	v_ashrrev_i32_e32 v167, 31, v166
	v_pk_mul_f32 v[114:115], v[114:115], v[120:121]
	v_cvt_pk_bf16_f32 v116, v116, v117
	v_cvt_pk_bf16_f32 v117, v118, v119
	v_cvt_pk_bf16_f32 v118, v112, v113
	v_mov_b64_e32 v[112:113], s[14:15]
	v_cvt_pk_bf16_f32 v119, v114, v115
	v_mad_i64_i32 v[120:121], s[8:9], v160, s62, v[112:113]
	v_lshlrev_b64 v[114:115], 1, v[166:167]
	v_pk_mul_f32 v[108:109], v[108:109], v[172:173] op_sel_hi:[1,0]
	v_lshl_add_u64 v[120:121], v[120:121], 0, v[114:115]
	v_mul_f32_e32 v122, 0xbfb8aa3b, v108
	v_mul_f32_e32 v123, 0xbfb8aa3b, v109
	v_pk_mul_f32 v[110:111], v[110:111], v[172:173] op_sel_hi:[1,0]
	v_exp_f32_e32 v122, v122
	v_exp_f32_e32 v123, v123
	global_store_dwordx4 v[120:121], v[116:119], off
	v_pk_mul_f32 v[100:101], v[100:101], v[172:173] op_sel_hi:[1,0]
	v_pk_mul_f32 v[104:105], v[104:105], v[172:173] op_sel_hi:[1,0]
	v_mul_f32_e32 v118, 0xbfb8aa3b, v110
	v_mul_f32_e32 v119, 0xbfb8aa3b, v111
	v_exp_f32_e32 v118, v118
	v_exp_f32_e32 v119, v119
	v_add_f32_e32 v116, 1.0, v122
	v_add_f32_e32 v117, 1.0, v123
	v_rcp_f32_e32 v116, v116
	v_rcp_f32_e32 v117, v117
	v_add_f32_e32 v118, 1.0, v118
	v_add_f32_e32 v119, 1.0, v119
	v_rcp_f32_e32 v118, v118
	v_rcp_f32_e32 v119, v119
	v_pk_mul_f32 v[108:109], v[108:109], v[116:117]
	v_pk_mul_f32 v[102:103], v[102:103], v[172:173] op_sel_hi:[1,0]
	v_pk_mul_f32 v[100:101], v[100:101], v[108:109]
	v_pk_mul_f32 v[108:109], v[110:111], v[118:119]
	v_mul_f32_e32 v110, 0xbfb8aa3b, v104
	v_mul_f32_e32 v111, 0xbfb8aa3b, v105
	v_exp_f32_e32 v110, v110
	v_exp_f32_e32 v111, v111
	v_pk_mul_f32 v[106:107], v[106:107], v[172:173] op_sel_hi:[1,0]
; #define PG8_GAS __attribute__((address_space(1)))
; __device__ __forceinline__ unsigned pk2_(float lo, float hi) { f32x2c_t v = {lo, hi}; bf16x2c_t b = __builtin_convertvector(v, bf16x2c_t); return __builtin_bit_cast(unsigned, b); }
; __device__ __forceinline__ float silu_f(float x) { return x * __builtin_amdgcn_rcpf(1.0f + __builtin_amdgcn_exp2f(-1.4426950408889634f * x)); }
;     __device__ __forceinline__ void operator()(const f32x4 (&acc)[2][2][4][2], const Unit& u, int wr, int wc, int fr, int fq) const {
;     ...
;             for (int m = 0; m < 4; ++m) {
;                 const int r = row0 + ai * HALF + m * 16; const float s = rs8[ai][m];
;                 float o[8];
; #pragma unroll
;                 for (int n = 0; n < 2; ++n)
; #pragma unroll
;                     for (int i = 0; i < 4; ++i) o[4 * n + i] = silu_f(acc[ai][0][m][n][i] * s) * (acc[ai][1][m][n][i] * s);
;                 u32x4 w; w.x = pk2_(o[0], o[1]); w.y = pk2_(o[2], o[3]); w.z = pk2_(o[4], o[5]); w.w = pk2_(o[6], o[7]);
;                 *(PG8_GAS u32x4*)(O + (size_t)r * 2816 + col0) = w;
	v_pk_mul_f32 v[102:103], v[102:103], v[108:109]
	v_add_f32_e32 v108, 1.0, v110
	v_add_f32_e32 v109, 1.0, v111
	v_mul_f32_e32 v110, 0xbfb8aa3b, v106
	v_mul_f32_e32 v111, 0xbfb8aa3b, v107
	v_exp_f32_e32 v110, v110
	v_exp_f32_e32 v111, v111
	v_rcp_f32_e32 v108, v108
	v_rcp_f32_e32 v109, v109
	v_add_f32_e32 v110, 1.0, v110
	v_add_f32_e32 v111, 1.0, v111
	v_rcp_f32_e32 v110, v110
	v_rcp_f32_e32 v111, v111
	v_pk_mul_f32 v[104:105], v[104:105], v[108:109]
	v_pk_mul_f32 v[96:97], v[96:97], v[172:173] op_sel_hi:[1,0]
	v_pk_mul_f32 v[98:99], v[98:99], v[172:173] op_sel_hi:[1,0]
	v_pk_mul_f32 v[104:105], v[96:97], v[104:105]
	v_pk_mul_f32 v[96:97], v[106:107], v[110:111]
	v_pk_mul_f32 v[92:93], v[92:93], v[164:165] op_sel_hi:[1,0]
	v_pk_mul_f32 v[106:107], v[98:99], v[96:97]
	v_cvt_pk_bf16_f32 v96, v100, v101
	v_mad_i64_i32 v[100:101], s[8:9], v156, s62, v[112:113]
	v_cvt_pk_bf16_f32 v97, v102, v103
	v_cvt_pk_bf16_f32 v98, v104, v105
	v_cvt_pk_bf16_f32 v99, v106, v107
	v_lshl_add_u64 v[100:101], v[100:101], 0, v[114:115]
	v_mul_f32_e32 v102, 0xbfb8aa3b, v92
	v_mul_f32_e32 v103, 0xbfb8aa3b, v93
	v_pk_mul_f32 v[94:95], v[94:95], v[164:165] op_sel_hi:[1,0]
	v_exp_f32_e32 v102, v102
	v_exp_f32_e32 v103, v103
	global_store_dwordx4 v[100:101], v[96:99], off
	v_pk_mul_f32 v[84:85], v[84:85], v[164:165] op_sel_hi:[1,0]
	v_pk_mul_f32 v[88:89], v[88:89], v[164:165] op_sel_hi:[1,0]
	v_mul_f32_e32 v98, 0xbfb8aa3b, v94
	v_mul_f32_e32 v99, 0xbfb8aa3b, v95
	v_exp_f32_e32 v98, v98
	v_exp_f32_e32 v99, v99
	v_add_f32_e32 v96, 1.0, v102
	v_add_f32_e32 v97, 1.0, v103
	v_rcp_f32_e32 v96, v96
	v_rcp_f32_e32 v97, v97
	v_add_f32_e32 v98, 1.0, v98
	v_add_f32_e32 v99, 1.0, v99
	v_rcp_f32_e32 v98, v98
	v_rcp_f32_e32 v99, v99
	v_pk_mul_f32 v[92:93], v[92:93], v[96:97]
	v_pk_mul_f32 v[86:87], v[86:87], v[164:165] op_sel_hi:[1,0]
	v_pk_mul_f32 v[84:85], v[84:85], v[92:93]
	v_pk_mul_f32 v[92:93], v[94:95], v[98:99]
	v_mul_f32_e32 v94, 0xbfb8aa3b, v88
	v_mul_f32_e32 v95, 0xbfb8aa3b, v89
	v_exp_f32_e32 v94, v94
	v_exp_f32_e32 v95, v95
	v_pk_mul_f32 v[90:91], v[90:91], v[164:165] op_sel_hi:[1,0]
	v_pk_mul_f32 v[86:87], v[86:87], v[92:93]
	v_add_f32_e32 v92, 1.0, v94
	v_add_f32_e32 v93, 1.0, v95
	v_mul_f32_e32 v94, 0xbfb8aa3b, v90
	v_mul_f32_e32 v95, 0xbfb8aa3b, v91
	v_exp_f32_e32 v94, v94
	v_exp_f32_e32 v95, v95
	v_rcp_f32_e32 v92, v92
	v_rcp_f32_e32 v93, v93
	v_add_f32_e32 v94, 1.0, v94
	v_add_f32_e32 v95, 1.0, v95
	v_rcp_f32_e32 v94, v94
	v_rcp_f32_e32 v95, v95
	v_pk_mul_f32 v[88:89], v[88:89], v[92:93]
	v_pk_mul_f32 v[80:81], v[80:81], v[164:165] op_sel_hi:[1,0]
	v_pk_mul_f32 v[82:83], v[82:83], v[164:165] op_sel_hi:[1,0]
	v_pk_mul_f32 v[88:89], v[80:81], v[88:89]
	v_pk_mul_f32 v[80:81], v[90:91], v[94:95]
	v_pk_mul_f32 v[76:77], v[76:77], v[162:163] op_sel_hi:[1,0]
	v_pk_mul_f32 v[90:91], v[82:83], v[80:81]
	v_cvt_pk_bf16_f32 v80, v84, v85
	v_mad_i64_i32 v[84:85], s[8:9], v152, s62, v[112:113]
	v_cvt_pk_bf16_f32 v81, v86, v87
	v_cvt_pk_bf16_f32 v82, v88, v89
	v_cvt_pk_bf16_f32 v83, v90, v91
	v_lshl_add_u64 v[84:85], v[84:85], 0, v[114:115]
	v_mul_f32_e32 v86, 0xbfb8aa3b, v76
	v_mul_f32_e32 v87, 0xbfb8aa3b, v77
	v_pk_mul_f32 v[78:79], v[78:79], v[162:163] op_sel_hi:[1,0]
	v_exp_f32_e32 v86, v86
	v_exp_f32_e32 v87, v87
	global_store_dwordx4 v[84:85], v[80:83], off
	v_pk_mul_f32 v[68:69], v[68:69], v[162:163] op_sel_hi:[1,0]
	v_pk_mul_f32 v[72:73], v[72:73], v[162:163] op_sel_hi:[1,0]
	v_mul_f32_e32 v82, 0xbfb8aa3b, v78
	v_mul_f32_e32 v83, 0xbfb8aa3b, v79
	v_exp_f32_e32 v82, v82
	v_exp_f32_e32 v83, v83
	v_add_f32_e32 v80, 1.0, v86
	v_add_f32_e32 v81, 1.0, v87
	v_rcp_f32_e32 v80, v80
	v_rcp_f32_e32 v81, v81
	v_add_f32_e32 v82, 1.0, v82
	v_add_f32_e32 v83, 1.0, v83
	v_rcp_f32_e32 v82, v82
	v_rcp_f32_e32 v83, v83
	v_pk_mul_f32 v[76:77], v[76:77], v[80:81]
	v_pk_mul_f32 v[70:71], v[70:71], v[162:163] op_sel_hi:[1,0]
	v_pk_mul_f32 v[68:69], v[68:69], v[76:77]
	v_pk_mul_f32 v[76:77], v[78:79], v[82:83]
	v_mul_f32_e32 v78, 0xbfb8aa3b, v72
	v_mul_f32_e32 v79, 0xbfb8aa3b, v73
	v_exp_f32_e32 v78, v78
	v_exp_f32_e32 v79, v79
	v_pk_mul_f32 v[74:75], v[74:75], v[162:163] op_sel_hi:[1,0]
	v_pk_mul_f32 v[70:71], v[70:71], v[76:77]
	v_add_f32_e32 v76, 1.0, v78
	v_add_f32_e32 v77, 1.0, v79
	v_mul_f32_e32 v78, 0xbfb8aa3b, v74
	v_mul_f32_e32 v79, 0xbfb8aa3b, v75
	v_exp_f32_e32 v78, v78
	v_exp_f32_e32 v79, v79
	v_rcp_f32_e32 v76, v76
	v_rcp_f32_e32 v77, v77
	v_add_f32_e32 v78, 1.0, v78
	v_add_f32_e32 v79, 1.0, v79
	v_rcp_f32_e32 v78, v78
	v_rcp_f32_e32 v79, v79
	v_pk_mul_f32 v[72:73], v[72:73], v[76:77]
	v_pk_mul_f32 v[64:65], v[64:65], v[162:163] op_sel_hi:[1,0]
	v_pk_mul_f32 v[66:67], v[66:67], v[162:163] op_sel_hi:[1,0]
	v_pk_mul_f32 v[72:73], v[64:65], v[72:73]
	v_pk_mul_f32 v[64:65], v[74:75], v[78:79]
	v_pk_mul_f32 v[60:61], v[60:61], v[158:159] op_sel_hi:[1,0]
	v_pk_mul_f32 v[74:75], v[66:67], v[64:65]
	v_cvt_pk_bf16_f32 v64, v68, v69
	v_mad_i64_i32 v[68:69], s[8:9], v150, s62, v[112:113]
	v_cvt_pk_bf16_f32 v65, v70, v71
	v_cvt_pk_bf16_f32 v66, v72, v73
	v_cvt_pk_bf16_f32 v67, v74, v75
	v_lshl_add_u64 v[68:69], v[68:69], 0, v[114:115]
	v_mul_f32_e32 v70, 0xbfb8aa3b, v60
	v_mul_f32_e32 v71, 0xbfb8aa3b, v61
	v_pk_mul_f32 v[62:63], v[62:63], v[158:159] op_sel_hi:[1,0]
	v_exp_f32_e32 v70, v70
	v_exp_f32_e32 v71, v71
	global_store_dwordx4 v[68:69], v[64:67], off
	v_pk_mul_f32 v[52:53], v[52:53], v[158:159] op_sel_hi:[1,0]
	v_pk_mul_f32 v[56:57], v[56:57], v[158:159] op_sel_hi:[1,0]
	v_mul_f32_e32 v66, 0xbfb8aa3b, v62
	v_mul_f32_e32 v67, 0xbfb8aa3b, v63
	v_exp_f32_e32 v66, v66
	v_exp_f32_e32 v67, v67
	v_add_f32_e32 v64, 1.0, v70
	v_add_f32_e32 v65, 1.0, v71
	v_rcp_f32_e32 v64, v64
	v_rcp_f32_e32 v65, v65
; #define PG8_GAS __attribute__((address_space(1)))
; __device__ __forceinline__ unsigned pk2_(float lo, float hi) { f32x2c_t v = {lo, hi}; bf16x2c_t b = __builtin_convertvector(v, bf16x2c_t); return __builtin_bit_cast(unsigned, b); }
; __device__ __forceinline__ float silu_f(float x) { return x * __builtin_amdgcn_rcpf(1.0f + __builtin_amdgcn_exp2f(-1.4426950408889634f * x)); }
;     __device__ __forceinline__ void operator()(const f32x4 (&acc)[2][2][4][2], const Unit& u, int wr, int wc, int fr, int fq) const {
;     ...
;             for (int m = 0; m < 4; ++m) {
;                 const int r = row0 + ai * HALF + m * 16; const float s = rs8[ai][m];
;                 float o[8];
; #pragma unroll
;                 for (int n = 0; n < 2; ++n)
; #pragma unroll
;                     for (int i = 0; i < 4; ++i) o[4 * n + i] = silu_f(acc[ai][0][m][n][i] * s) * (acc[ai][1][m][n][i] * s);
;                 u32x4 w; w.x = pk2_(o[0], o[1]); w.y = pk2_(o[2], o[3]); w.z = pk2_(o[4], o[5]); w.w = pk2_(o[6], o[7]);
;                 *(PG8_GAS u32x4*)(O + (size_t)r * 2816 + col0) = w;
	v_add_f32_e32 v66, 1.0, v66
	v_add_f32_e32 v67, 1.0, v67
	v_rcp_f32_e32 v66, v66
	v_rcp_f32_e32 v67, v67
	v_pk_mul_f32 v[60:61], v[60:61], v[64:65]
	v_pk_mul_f32 v[54:55], v[54:55], v[158:159] op_sel_hi:[1,0]
	v_pk_mul_f32 v[52:53], v[52:53], v[60:61]
	v_pk_mul_f32 v[60:61], v[62:63], v[66:67]
	v_mul_f32_e32 v62, 0xbfb8aa3b, v56
	v_mul_f32_e32 v63, 0xbfb8aa3b, v57
	v_exp_f32_e32 v62, v62
	v_exp_f32_e32 v63, v63
	v_pk_mul_f32 v[58:59], v[58:59], v[158:159] op_sel_hi:[1,0]
	v_pk_mul_f32 v[54:55], v[54:55], v[60:61]
	v_add_f32_e32 v60, 1.0, v62
	v_add_f32_e32 v61, 1.0, v63
	v_mul_f32_e32 v62, 0xbfb8aa3b, v58
	v_mul_f32_e32 v63, 0xbfb8aa3b, v59
	v_exp_f32_e32 v62, v62
	v_exp_f32_e32 v63, v63
	v_rcp_f32_e32 v60, v60
	v_rcp_f32_e32 v61, v61
	v_add_f32_e32 v62, 1.0, v62
	v_add_f32_e32 v63, 1.0, v63
	v_rcp_f32_e32 v62, v62
	v_rcp_f32_e32 v63, v63
	v_pk_mul_f32 v[56:57], v[56:57], v[60:61]
	v_pk_mul_f32 v[48:49], v[48:49], v[158:159] op_sel_hi:[1,0]
	v_pk_mul_f32 v[50:51], v[50:51], v[158:159] op_sel_hi:[1,0]
	v_pk_mul_f32 v[56:57], v[48:49], v[56:57]
	v_pk_mul_f32 v[48:49], v[58:59], v[62:63]
	v_pk_mul_f32 v[44:45], v[44:45], v[154:155] op_sel_hi:[1,0]
	v_pk_mul_f32 v[58:59], v[50:51], v[48:49]
	v_cvt_pk_bf16_f32 v48, v52, v53
	v_mad_i64_i32 v[52:53], s[8:9], v146, s62, v[112:113]
	v_cvt_pk_bf16_f32 v49, v54, v55
	v_cvt_pk_bf16_f32 v50, v56, v57
	v_cvt_pk_bf16_f32 v51, v58, v59
	v_lshl_add_u64 v[52:53], v[52:53], 0, v[114:115]
	v_mul_f32_e32 v54, 0xbfb8aa3b, v44
	v_mul_f32_e32 v55, 0xbfb8aa3b, v45
	v_pk_mul_f32 v[46:47], v[46:47], v[154:155] op_sel_hi:[1,0]
	v_exp_f32_e32 v54, v54
	v_exp_f32_e32 v55, v55
	global_store_dwordx4 v[52:53], v[48:51], off
	v_pk_mul_f32 v[36:37], v[36:37], v[154:155] op_sel_hi:[1,0]
	v_pk_mul_f32 v[40:41], v[40:41], v[154:155] op_sel_hi:[1,0]
	v_mul_f32_e32 v50, 0xbfb8aa3b, v46
	v_mul_f32_e32 v51, 0xbfb8aa3b, v47
	v_exp_f32_e32 v50, v50
	v_exp_f32_e32 v51, v51
	v_add_f32_e32 v48, 1.0, v54
	v_add_f32_e32 v49, 1.0, v55
	v_rcp_f32_e32 v48, v48
	v_rcp_f32_e32 v49, v49
	v_add_f32_e32 v50, 1.0, v50
	v_add_f32_e32 v51, 1.0, v51
	v_rcp_f32_e32 v50, v50
	v_rcp_f32_e32 v51, v51
	v_pk_mul_f32 v[44:45], v[44:45], v[48:49]
	v_pk_mul_f32 v[38:39], v[38:39], v[154:155] op_sel_hi:[1,0]
	v_pk_mul_f32 v[36:37], v[36:37], v[44:45]
	v_pk_mul_f32 v[44:45], v[46:47], v[50:51]
	v_mul_f32_e32 v46, 0xbfb8aa3b, v40
	v_mul_f32_e32 v47, 0xbfb8aa3b, v41
	v_exp_f32_e32 v46, v46
	v_exp_f32_e32 v47, v47
	v_pk_mul_f32 v[42:43], v[42:43], v[154:155] op_sel_hi:[1,0]
	v_pk_mul_f32 v[38:39], v[38:39], v[44:45]
	v_add_f32_e32 v44, 1.0, v46
	v_add_f32_e32 v45, 1.0, v47
	v_mul_f32_e32 v46, 0xbfb8aa3b, v42
	v_mul_f32_e32 v47, 0xbfb8aa3b, v43
	v_exp_f32_e32 v46, v46
	v_exp_f32_e32 v47, v47
	v_rcp_f32_e32 v44, v44
	v_rcp_f32_e32 v45, v45
	v_add_f32_e32 v46, 1.0, v46
	v_add_f32_e32 v47, 1.0, v47
	v_rcp_f32_e32 v46, v46
	v_rcp_f32_e32 v47, v47
	v_pk_mul_f32 v[40:41], v[40:41], v[44:45]
	v_pk_mul_f32 v[32:33], v[32:33], v[154:155] op_sel_hi:[1,0]
	v_pk_mul_f32 v[34:35], v[34:35], v[154:155] op_sel_hi:[1,0]
	v_pk_mul_f32 v[40:41], v[32:33], v[40:41]
	v_pk_mul_f32 v[32:33], v[42:43], v[46:47]
	v_pk_mul_f32 v[28:29], v[28:29], v[148:149] op_sel_hi:[1,0]
	v_pk_mul_f32 v[42:43], v[34:35], v[32:33]
	v_cvt_pk_bf16_f32 v32, v36, v37
	v_mad_i64_i32 v[36:37], s[8:9], v144, s62, v[112:113]
	v_cvt_pk_bf16_f32 v33, v38, v39
	v_cvt_pk_bf16_f32 v34, v40, v41
	v_cvt_pk_bf16_f32 v35, v42, v43
	v_lshl_add_u64 v[36:37], v[36:37], 0, v[114:115]
	v_mul_f32_e32 v38, 0xbfb8aa3b, v28
	v_mul_f32_e32 v39, 0xbfb8aa3b, v29
	v_pk_mul_f32 v[30:31], v[30:31], v[148:149] op_sel_hi:[1,0]
	v_exp_f32_e32 v38, v38
	v_exp_f32_e32 v39, v39
	global_store_dwordx4 v[36:37], v[32:35], off
	v_pk_mul_f32 v[20:21], v[20:21], v[148:149] op_sel_hi:[1,0]
	v_pk_mul_f32 v[24:25], v[24:25], v[148:149] op_sel_hi:[1,0]
; #define PG8_GAS __attribute__((address_space(1)))
; __device__ __forceinline__ unsigned pk2_(float lo, float hi) { f32x2c_t v = {lo, hi}; bf16x2c_t b = __builtin_convertvector(v, bf16x2c_t); return __builtin_bit_cast(unsigned, b); }
; __device__ __forceinline__ float silu_f(float x) { return x * __builtin_amdgcn_rcpf(1.0f + __builtin_amdgcn_exp2f(-1.4426950408889634f * x)); }
;     __device__ __forceinline__ void operator()(const f32x4 (&acc)[2][2][4][2], const Unit& u, int wr, int wc, int fr, int fq) const {
;     ...
;             for (int m = 0; m < 4; ++m) {
;                 const int r = row0 + ai * HALF + m * 16; const float s = rs8[ai][m];
;                 float o[8];
; #pragma unroll
;                 for (int n = 0; n < 2; ++n)
; #pragma unroll
;                     for (int i = 0; i < 4; ++i) o[4 * n + i] = silu_f(acc[ai][0][m][n][i] * s) * (acc[ai][1][m][n][i] * s);
;                 u32x4 w; w.x = pk2_(o[0], o[1]); w.y = pk2_(o[2], o[3]); w.z = pk2_(o[4], o[5]); w.w = pk2_(o[6], o[7]);
;                 *(PG8_GAS u32x4*)(O + (size_t)r * 2816 + col0) = w;
	v_mul_f32_e32 v34, 0xbfb8aa3b, v30
	v_mul_f32_e32 v35, 0xbfb8aa3b, v31
	v_exp_f32_e32 v34, v34
	v_exp_f32_e32 v35, v35
	v_add_f32_e32 v32, 1.0, v38
	v_add_f32_e32 v33, 1.0, v39
	v_rcp_f32_e32 v32, v32
	v_rcp_f32_e32 v33, v33
	v_add_f32_e32 v34, 1.0, v34
	v_add_f32_e32 v35, 1.0, v35
	v_rcp_f32_e32 v34, v34
	v_rcp_f32_e32 v35, v35
	v_pk_mul_f32 v[28:29], v[28:29], v[32:33]
	v_pk_mul_f32 v[22:23], v[22:23], v[148:149] op_sel_hi:[1,0]
	v_pk_mul_f32 v[20:21], v[20:21], v[28:29]
	v_pk_mul_f32 v[28:29], v[30:31], v[34:35]
	v_mul_f32_e32 v30, 0xbfb8aa3b, v24
	v_mul_f32_e32 v31, 0xbfb8aa3b, v25
	v_exp_f32_e32 v30, v30
	v_exp_f32_e32 v31, v31
	v_pk_mul_f32 v[26:27], v[26:27], v[148:149] op_sel_hi:[1,0]
	v_pk_mul_f32 v[22:23], v[22:23], v[28:29]
	v_add_f32_e32 v28, 1.0, v30
	v_add_f32_e32 v29, 1.0, v31
	v_mul_f32_e32 v30, 0xbfb8aa3b, v26
	v_mul_f32_e32 v31, 0xbfb8aa3b, v27
	v_exp_f32_e32 v30, v30
	v_exp_f32_e32 v31, v31
	v_rcp_f32_e32 v28, v28
	v_rcp_f32_e32 v29, v29
	v_add_f32_e32 v30, 1.0, v30
	v_add_f32_e32 v31, 1.0, v31
	v_rcp_f32_e32 v30, v30
	v_rcp_f32_e32 v31, v31
	v_pk_mul_f32 v[24:25], v[24:25], v[28:29]
	v_pk_mul_f32 v[16:17], v[16:17], v[148:149] op_sel_hi:[1,0]
	v_pk_mul_f32 v[18:19], v[18:19], v[148:149] op_sel_hi:[1,0]
	v_pk_mul_f32 v[24:25], v[16:17], v[24:25]
	v_pk_mul_f32 v[16:17], v[26:27], v[30:31]
	v_pk_mul_f32 v[12:13], v[12:13], v[132:133] op_sel_hi:[1,0]
	v_pk_mul_f32 v[26:27], v[18:19], v[16:17]
	v_cvt_pk_bf16_f32 v16, v20, v21
	v_mad_i64_i32 v[20:21], s[8:9], v142, s62, v[112:113]
	v_cvt_pk_bf16_f32 v17, v22, v23
	v_cvt_pk_bf16_f32 v18, v24, v25
	v_cvt_pk_bf16_f32 v19, v26, v27
	v_lshl_add_u64 v[20:21], v[20:21], 0, v[114:115]
	v_mul_f32_e32 v22, 0xbfb8aa3b, v12
	v_mul_f32_e32 v23, 0xbfb8aa3b, v13
	v_pk_mul_f32 v[14:15], v[14:15], v[132:133] op_sel_hi:[1,0]
	v_exp_f32_e32 v22, v22
	v_exp_f32_e32 v23, v23
	global_store_dwordx4 v[20:21], v[16:19], off
	v_pk_mul_f32 v[4:5], v[4:5], v[132:133] op_sel_hi:[1,0]
	v_pk_mul_f32 v[8:9], v[8:9], v[132:133] op_sel_hi:[1,0]
	v_mul_f32_e32 v18, 0xbfb8aa3b, v14
	v_mul_f32_e32 v19, 0xbfb8aa3b, v15
	v_exp_f32_e32 v18, v18
	v_exp_f32_e32 v19, v19
	v_add_f32_e32 v16, 1.0, v22
	v_add_f32_e32 v17, 1.0, v23
	v_rcp_f32_e32 v16, v16
	v_rcp_f32_e32 v17, v17
	v_add_f32_e32 v18, 1.0, v18
	v_add_f32_e32 v19, 1.0, v19
	v_rcp_f32_e32 v18, v18
	v_rcp_f32_e32 v19, v19
	v_pk_mul_f32 v[12:13], v[12:13], v[16:17]
	v_pk_mul_f32 v[6:7], v[6:7], v[132:133] op_sel_hi:[1,0]
	v_pk_mul_f32 v[4:5], v[4:5], v[12:13]
	v_pk_mul_f32 v[12:13], v[14:15], v[18:19]
	v_mul_f32_e32 v14, 0xbfb8aa3b, v8
	v_mul_f32_e32 v15, 0xbfb8aa3b, v9
	v_exp_f32_e32 v14, v14
	v_exp_f32_e32 v15, v15
	v_pk_mul_f32 v[10:11], v[10:11], v[132:133] op_sel_hi:[1,0]
	v_pk_mul_f32 v[6:7], v[6:7], v[12:13]
	v_add_f32_e32 v12, 1.0, v14
	v_add_f32_e32 v13, 1.0, v15
	v_mul_f32_e32 v14, 0xbfb8aa3b, v10
	v_mul_f32_e32 v15, 0xbfb8aa3b, v11
	v_exp_f32_e32 v14, v14
	v_exp_f32_e32 v15, v15
	v_rcp_f32_e32 v12, v12
	v_rcp_f32_e32 v13, v13
	v_add_f32_e32 v14, 1.0, v14
	v_add_f32_e32 v15, 1.0, v15
	v_rcp_f32_e32 v14, v14
	v_rcp_f32_e32 v15, v15
	v_pk_mul_f32 v[8:9], v[8:9], v[12:13]
	v_pk_mul_f32 v[0:1], v[0:1], v[132:133] op_sel_hi:[1,0]
	v_pk_mul_f32 v[2:3], v[2:3], v[132:133] op_sel_hi:[1,0]
	v_pk_mul_f32 v[8:9], v[0:1], v[8:9]
	v_pk_mul_f32 v[0:1], v[10:11], v[14:15]
	s_andn2_b64 vcc, exec, s[6:7]
	v_pk_mul_f32 v[10:11], v[2:3], v[0:1]
	v_cvt_pk_bf16_f32 v0, v4, v5
	v_mad_i64_i32 v[4:5], s[8:9], v140, s62, v[112:113]
	v_cvt_pk_bf16_f32 v1, v6, v7
	v_cvt_pk_bf16_f32 v2, v8, v9
	v_cvt_pk_bf16_f32 v3, v10, v11
	v_lshl_add_u64 v[4:5], v[4:5], 0, v[114:115]
	s_mov_b64 s[6:7], -1
	global_store_dwordx4 v[4:5], v[0:3], off
	s_cbranch_vccnz .LBB0_1654
	s_andn2_b64 vcc, exec, s[12:13]
	s_cbranch_vccnz .LBB0_1653
	s_barrier
	s_branch .LBB0_1653
